# v19_9 + first K-loop trip peeled with SrcC=0 on each accumulator's first MFMA; 128 accumulator zero-init v_movs per tile removed (7 loops)
# speedup vs baseline: 1.0035x; 1.0035x over previous
;     __device__ __forceinline__ bool next(int i, Unit& u) const { if (i >= 2) return false; const int xcd = c & 7, off = c >> 3; u.pm = 16 * i + 4 * (xcd >> 1) + (off & 3); u.pn = 8 * (xcd & 1) + (off >> 2); return true; }
; #define PG8_STAGE(bufoff, gbase, voff) do { _Pragma("unroll") for (int _i = 0; _i < 2; ++_i) \
;         __builtin_amdgcn_global_load_lds((const unsigned*)((const char*)(gbase) + (voff)[_i]), (PG8_LAS unsigned*)(lds + (bufoff) + ldsw + _i * 8192), 16, 0, 0); } while (0)
; #define PG8_BAR __builtin_amdgcn_s_barrier()
; template <class Epi, class Sched, bool ALIGN_EPI = false, bool SP2 = false>
; __device__ __forceinline__ void gemm_phase(PG8_LAS unsigned char* lds, const Gemm g, const Sched& S, const Epi& E) {
;     ...
;     f32x4 acc[2][2][4][2];
; #pragma unroll
;     for (int a = 0; a < 2; ++a)
; #pragma unroll
;         for (int b = 0; b < 2; ++b)
; #pragma unroll
;             for (int m = 0; m < 4; ++m)
; #pragma unroll
;                 for (int n = 0; n < 2; ++n) acc[a][b][m][n] = (f32x4){0.f, 0.f, 0.f, 0.f};
;     ...
;         const bool has_next = S.next(ui + 1, nxt);
;         const char* nA = has_next ? (const char*)g.A + (size_t)nxt.pm * tstep : cA; const char* nB = has_next ? (const char*)g.Bt + (size_t)nxt.pn * tstep : cB;
;         constexpr int NSEG = Epi::HAS_MID ? 2 : 1; int t = 0;
; #pragma unroll
;         for (int seg = 0; seg < NSEG; ++seg) { const int tend = (seg + 1 < NSEG) ? (nt >> 1) : nt;
;         for (; t < tend; t += 2) {
;             const bool last = (t == nt - 2);
;             const char* a1 = cA + (size_t)(t + 1) * kstep;
;             const char* a2 = last ? nA : cA + (size_t)(t + 2) * kstep; const char* b2 = last ? nB : cB + (size_t)(t + 2) * kstep;
;             const char* a3 = a2 + kstep; const char* b3 = b2 + kstep;
;             if (last && has_next) S.a_ready(nxt);
;             if constexpr (SP2) {
;             PG8_LDB(B0, 0, 0); PG8_LDB(B1, 0, 1); PG8_SCHED; PG8_LDA(At, 0, 0); PG8_STAGE(PG8_SA(1, 1), a1 + hstep, voffA);
;             PG8_WAIT_V(8); PG8_WAIT_L(0); PG8_BAR; PG8_MMA(0, 0, At, B0); PG8_MMA(0, 1, At, B1); PG8_BAR; PG8_SCHED;
;             PG8_LDA(At, 0, 1); PG8_STAGE(PG8_SB(0, 0), b2, voffB); PG8_STAGE(PG8_SB(0, 1), b2 + hstep, voffB); PG8_STAGE(PG8_SA(0, 0), a2, voffA);
;             PG8_WAIT_V(8); PG8_WAIT_L(0); PG8_BAR; PG8_MMA(1, 0, At, B0); PG8_MMA(1, 1, At, B1); PG8_BAR; PG8_SCHED;
.LBB0_114:
	s_ashr_i32 s25, s24, 31
	s_lshl_b64 s[42:43], s[24:25], 21
	s_add_u32 s42, s66, s42
	s_addc_u32 s43, s67, s43
	s_and_b64 s[44:45], s[0:1], exec
	s_cselect_b32 s25, s43, s49
	s_cselect_b32 s64, s42, s48
	s_ashr_i32 s19, s18, 31
	s_lshl_b64 s[44:45], s[18:19], 21
	s_add_u32 s44, s4, s44
	s_addc_u32 s45, s5, s45
	s_and_b64 s[68:69], s[0:1], exec
	s_cselect_b32 s19, s45, s51
	s_cselect_b32 s65, s44, s50
	s_add_u32 s48, s48, 0xc000
	s_addc_u32 s49, s49, 0
	s_add_u32 s68, s50, 0x10000
	s_addc_u32 s69, s51, 0
	s_mov_b32 s76, -2
	s_nop 3
	ds_read_b128 v[154:157], v150
	ds_read_b128 v[158:161], v150 offset:1024
	ds_read_b128 v[162:165], v150 offset:2048
	ds_read_b128 v[166:169], v150 offset:3072
	ds_read_b128 v[170:173], v151
	ds_read_b128 v[174:177], v151 offset:1024
	ds_read_b128 v[180:183], v151 offset:2048
	ds_read_b128 v[184:187], v151 offset:3072
	s_add_u32 s50, s48, 0x4000
	s_addc_u32 s51, s49, 0
	s_cmp_eq_u32 s76, 60
	s_cselect_b32 s74, s64, s50
	s_cselect_b32 s75, s25, s51
	s_cselect_b32 s72, s65, s68
	s_cselect_b32 s73, s19, s69
	s_add_u32 s50, s74, 0x8000
	s_addc_u32 s51, s75, 0
	s_sub_u32 s50, s48, 0x4000
	s_subb_u32 s51, s49, 0
	s_mov_b32 m0, s58
	s_nop 0
	global_load_lds_dwordx4 v130, s[50:51]
	s_mov_b32 m0, s59
	s_nop 0
	global_load_lds_dwordx4 v134, s[50:51]
	s_add_i32 m0, s28, 0xc000
	ds_read_b128 v[188:191], v152
	ds_read_b128 v[196:199], v152 offset:1024
	ds_read_b128 v[200:203], v152 offset:2048
	ds_read_b128 v[204:207], v152 offset:3072
	ds_read_b128 v[208:211], v152 offset:4096
	ds_read_b128 v[212:215], v152 offset:5120
	ds_read_b128 v[216:219], v152 offset:6144
	ds_read_b128 v[220:223], v152 offset:7168
	global_load_lds_dwordx4 v140, s[48:49]
	s_add_i32 m0, s28, 0xe000
	s_nop 0
	global_load_lds_dwordx4 v142, s[48:49]
	s_waitcnt vmcnt(8)
	s_waitcnt lgkmcnt(0)
	s_barrier
	s_waitcnt lgkmcnt(0)
	v_mfma_f32_16x16x32_bf16 v[126:129], v[154:157], v[188:191], 0
	v_mfma_f32_16x16x32_bf16 v[126:129], v[158:161], v[196:199], v[126:129]
	v_mfma_f32_16x16x32_bf16 v[110:113], v[158:161], v[204:207], 0
	v_mfma_f32_16x16x32_bf16 v[110:113], v[154:157], v[200:203], v[110:113]
	v_mfma_f32_16x16x32_bf16 v[94:97], v[154:157], v[208:211], 0
	v_mfma_f32_16x16x32_bf16 v[94:97], v[158:161], v[212:215], v[94:97]
	v_mfma_f32_16x16x32_bf16 v[78:81], v[158:161], v[220:223], 0
	v_mfma_f32_16x16x32_bf16 v[78:81], v[154:157], v[216:219], v[78:81]
	v_mfma_f32_16x16x32_bf16 v[70:73], v[162:165], v[216:219], 0
	v_mfma_f32_16x16x32_bf16 v[70:73], v[166:169], v[220:223], v[70:73]
	v_mfma_f32_16x16x32_bf16 v[86:89], v[166:169], v[212:215], 0
	v_mfma_f32_16x16x32_bf16 v[86:89], v[162:165], v[208:211], v[86:89]
	v_mfma_f32_16x16x32_bf16 v[102:105], v[162:165], v[200:203], 0
	v_mfma_f32_16x16x32_bf16 v[102:105], v[166:169], v[204:207], v[102:105]
	v_mfma_f32_16x16x32_bf16 v[118:121], v[166:169], v[196:199], 0
	v_mfma_f32_16x16x32_bf16 v[118:121], v[162:165], v[188:191], v[118:121]
	v_mfma_f32_16x16x32_bf16 v[122:125], v[170:173], v[188:191], 0
	v_mfma_f32_16x16x32_bf16 v[122:125], v[174:177], v[196:199], v[122:125]
	v_mfma_f32_16x16x32_bf16 v[106:109], v[174:177], v[204:207], 0
	v_mfma_f32_16x16x32_bf16 v[106:109], v[170:173], v[200:203], v[106:109]
	v_mfma_f32_16x16x32_bf16 v[90:93], v[170:173], v[208:211], 0
	v_mfma_f32_16x16x32_bf16 v[90:93], v[174:177], v[212:215], v[90:93]
	v_mfma_f32_16x16x32_bf16 v[74:77], v[174:177], v[220:223], 0
	v_mfma_f32_16x16x32_bf16 v[74:77], v[170:173], v[216:219], v[74:77]
	v_mfma_f32_16x16x32_bf16 v[66:69], v[180:183], v[216:219], 0
	v_mfma_f32_16x16x32_bf16 v[66:69], v[184:187], v[220:223], v[66:69]
	v_mfma_f32_16x16x32_bf16 v[82:85], v[184:187], v[212:215], 0
	v_mfma_f32_16x16x32_bf16 v[82:85], v[180:183], v[208:211], v[82:85]
	v_mfma_f32_16x16x32_bf16 v[98:101], v[180:183], v[200:203], 0
	v_mfma_f32_16x16x32_bf16 v[98:101], v[184:187], v[204:207], v[98:101]
	v_mfma_f32_16x16x32_bf16 v[114:117], v[184:187], v[196:199], 0
	v_mfma_f32_16x16x32_bf16 v[114:117], v[180:183], v[188:191], v[114:117]
	s_barrier
	s_add_i32 s77, s61, s3
	s_mov_b32 m0, s77
	ds_read_b128 v[188:191], v152 offset:16384
	ds_read_b128 v[196:199], v152 offset:17408
	ds_read_b128 v[200:203], v152 offset:18432
	ds_read_b128 v[204:207], v152 offset:19456
	ds_read_b128 v[208:211], v152 offset:20480
	ds_read_b128 v[212:215], v152 offset:21504
	ds_read_b128 v[216:219], v152 offset:22528
	ds_read_b128 v[220:223], v152 offset:23552
	global_load_lds_dwordx4 v132, s[72:73]
	s_add_i32 m0, s77, 0x2000
	s_add_u32 s78, s72, 0x4000
	s_addc_u32 s79, s73, 0
	s_add_i32 s77, s62, s3
	global_load_lds_dwordx4 v136, s[72:73]
	s_mov_b32 m0, s77
	s_nop 0
	global_load_lds_dwordx4 v132, s[78:79]
	s_add_i32 m0, s77, 0x2000
	s_nop 0
	global_load_lds_dwordx4 v136, s[78:79]
	s_waitcnt vmcnt(6)
	s_waitcnt lgkmcnt(0)
	s_barrier
; #define PG8_STAGE(bufoff, gbase, voff) do { _Pragma("unroll") for (int _i = 0; _i < 2; ++_i) \
;         __builtin_amdgcn_global_load_lds((const unsigned*)((const char*)(gbase) + (voff)[_i]), (PG8_LAS unsigned*)(lds + (bufoff) + ldsw + _i * 8192), 16, 0, 0); } while (0)
; #define PG8_LDA(dst, b, h) do { _Pragma("unroll") for (int m = 0; m < 4; ++m) _Pragma("unroll") for (int k = 0; k < 2; ++k) dst[m][k] = *(const PG8_LAS bf16x8*)(lds + PG8_SA(b, h) + aoff + m * 2048 + k * 1024); } while (0)
; #define PG8_LDB(dst, b, h) do { _Pragma("unroll") for (int n = 0; n < 2; ++n) _Pragma("unroll") for (int k = 0; k < 2; ++k) dst[n][k] = *(const PG8_LAS bf16x8*)(lds + PG8_SB(b, h) + boff + n * 2048 + k * 1024); } while (0)
; #define PG8_MMA(ai, bj, At, Bt) do { __builtin_amdgcn_s_setprio(1); _Pragma("unroll") for (int m = 0; m < 4; ++m) _Pragma("unroll") for (int n = 0; n < 2; ++n) _Pragma("unroll") for (int k = 0; k < 2; ++k) \
;         acc[ai][bj][m][n] = __builtin_amdgcn_mfma_f32_16x16x32_bf16(Bt[n][k], At[m][k], acc[ai][bj][m][n], 0, 0, 0); __builtin_amdgcn_s_setprio(0); } while (0)
; #define PG8_WAIT_V(n) asm volatile("s_waitcnt vmcnt(" #n ")" ::: "memory")
; #define PG8_WAIT_L(n) asm volatile("s_waitcnt lgkmcnt(" #n ")" ::: "memory")
; #define PG8_BAR __builtin_amdgcn_s_barrier()
; #define PG8_SCHED __builtin_amdgcn_sched_barrier(0)
; template <class Epi, class Sched, bool ALIGN_EPI = false, bool SP2 = false>
; __device__ __forceinline__ void gemm_phase(PG8_LAS unsigned char* lds, const Gemm g, const Sched& S, const Epi& E) {
;     ...
;             PG8_WAIT_V(8); PG8_WAIT_L(0); PG8_BAR; PG8_MMA(1, 0, At, B0); PG8_MMA(1, 1, At, B1); PG8_BAR; PG8_SCHED;
;             PG8_LDB(B0, 1, 0); PG8_LDB(B1, 1, 1); PG8_SCHED; PG8_LDA(At, 1, 0); PG8_STAGE(PG8_SA(0, 1), a2 + hstep, voffA);
;             PG8_WAIT_V(8); PG8_WAIT_L(0); PG8_BAR; PG8_MMA(0, 0, At, B0); PG8_MMA(0, 1, At, B1); PG8_BAR; PG8_SCHED;
;             PG8_LDA(At, 1, 1); PG8_STAGE(PG8_SB(1, 0), b3, voffB); PG8_STAGE(PG8_SB(1, 1), b3 + hstep, voffB); PG8_STAGE(PG8_SA(1, 0), a3, voffA);
	s_waitcnt lgkmcnt(0)
	v_mfma_f32_16x16x32_bf16 v[62:65], v[154:157], v[188:191], 0
	v_mfma_f32_16x16x32_bf16 v[62:65], v[158:161], v[196:199], v[62:65]
	v_mfma_f32_16x16x32_bf16 v[46:49], v[158:161], v[204:207], 0
	v_mfma_f32_16x16x32_bf16 v[46:49], v[154:157], v[200:203], v[46:49]
	v_mfma_f32_16x16x32_bf16 v[30:33], v[154:157], v[208:211], 0
	v_mfma_f32_16x16x32_bf16 v[30:33], v[158:161], v[212:215], v[30:33]
	v_mfma_f32_16x16x32_bf16 v[14:17], v[158:161], v[220:223], 0
	v_mfma_f32_16x16x32_bf16 v[14:17], v[154:157], v[216:219], v[14:17]
	v_mfma_f32_16x16x32_bf16 v[6:9], v[162:165], v[216:219], 0
	v_mfma_f32_16x16x32_bf16 v[6:9], v[166:169], v[220:223], v[6:9]
	v_mfma_f32_16x16x32_bf16 v[22:25], v[166:169], v[212:215], 0
	v_mfma_f32_16x16x32_bf16 v[22:25], v[162:165], v[208:211], v[22:25]
	v_mfma_f32_16x16x32_bf16 v[38:41], v[162:165], v[200:203], 0
	v_mfma_f32_16x16x32_bf16 v[38:41], v[166:169], v[204:207], v[38:41]
	v_mfma_f32_16x16x32_bf16 v[54:57], v[166:169], v[196:199], 0
	v_mfma_f32_16x16x32_bf16 v[54:57], v[162:165], v[188:191], v[54:57]
	v_mfma_f32_16x16x32_bf16 v[58:61], v[170:173], v[188:191], 0
	v_mfma_f32_16x16x32_bf16 v[58:61], v[174:177], v[196:199], v[58:61]
	v_mfma_f32_16x16x32_bf16 v[42:45], v[174:177], v[204:207], 0
	v_mfma_f32_16x16x32_bf16 v[42:45], v[170:173], v[200:203], v[42:45]
	v_mfma_f32_16x16x32_bf16 v[26:29], v[170:173], v[208:211], 0
	v_mfma_f32_16x16x32_bf16 v[26:29], v[174:177], v[212:215], v[26:29]
	v_mfma_f32_16x16x32_bf16 v[10:13], v[174:177], v[220:223], 0
	v_mfma_f32_16x16x32_bf16 v[10:13], v[170:173], v[216:219], v[10:13]
	v_mfma_f32_16x16x32_bf16 v[2:5], v[180:183], v[216:219], 0
	v_mfma_f32_16x16x32_bf16 v[2:5], v[184:187], v[220:223], v[2:5]
	v_mfma_f32_16x16x32_bf16 v[18:21], v[184:187], v[212:215], 0
	v_mfma_f32_16x16x32_bf16 v[18:21], v[180:183], v[208:211], v[18:21]
	v_mfma_f32_16x16x32_bf16 v[34:37], v[180:183], v[200:203], 0
	v_mfma_f32_16x16x32_bf16 v[34:37], v[184:187], v[204:207], v[34:37]
	v_mfma_f32_16x16x32_bf16 v[50:53], v[184:187], v[196:199], 0
	v_mfma_f32_16x16x32_bf16 v[50:53], v[180:183], v[188:191], v[50:53]
	s_barrier
	s_add_i32 s77, 0, 0x18000
	v_add_u32_e32 v138, s77, v148
	s_add_i32 s78, 0, 0x1c000
	ds_read_b128 v[154:157], v138
	ds_read_b128 v[158:161], v138 offset:1024
	ds_read_b128 v[162:165], v138 offset:2048
	ds_read_b128 v[166:169], v138 offset:3072
	v_add_u32_e32 v138, s78, v148
	ds_read_b128 v[170:173], v138
	ds_read_b128 v[174:177], v138 offset:1024
	ds_read_b128 v[180:183], v138 offset:2048
	ds_read_b128 v[184:187], v138 offset:3072
	s_mov_b32 m0, s28
	s_nop 0
	global_load_lds_dwordx4 v130, s[74:75]
	s_mov_b32 m0, s29
	s_nop 0
	global_load_lds_dwordx4 v134, s[74:75]
	s_add_u32 s74, s74, 0x4000
	s_addc_u32 s75, s75, 0
	s_mov_b32 m0, s30
	ds_read_b128 v[188:191], v152 offset:32768
	ds_read_b128 v[196:199], v152 offset:33792
	ds_read_b128 v[200:203], v152 offset:34816
	ds_read_b128 v[204:207], v152 offset:35840
	ds_read_b128 v[208:211], v152 offset:36864
	ds_read_b128 v[212:215], v152 offset:37888
	ds_read_b128 v[216:219], v152 offset:38912
	ds_read_b128 v[220:223], v152 offset:39936
	global_load_lds_dwordx4 v130, s[74:75]
	s_mov_b32 m0, s31
	s_nop 0
	global_load_lds_dwordx4 v134, s[74:75]
	s_waitcnt vmcnt(8)
	s_waitcnt lgkmcnt(0)
	s_barrier
; #define PG8_STAGE(bufoff, gbase, voff) do { _Pragma("unroll") for (int _i = 0; _i < 2; ++_i) \
;         __builtin_amdgcn_global_load_lds((const unsigned*)((const char*)(gbase) + (voff)[_i]), (PG8_LAS unsigned*)(lds + (bufoff) + ldsw + _i * 8192), 16, 0, 0); } while (0)
; #define PG8_LDA(dst, b, h) do { _Pragma("unroll") for (int m = 0; m < 4; ++m) _Pragma("unroll") for (int k = 0; k < 2; ++k) dst[m][k] = *(const PG8_LAS bf16x8*)(lds + PG8_SA(b, h) + aoff + m * 2048 + k * 1024); } while (0)
; #define PG8_MMA(ai, bj, At, Bt) do { __builtin_amdgcn_s_setprio(1); _Pragma("unroll") for (int m = 0; m < 4; ++m) _Pragma("unroll") for (int n = 0; n < 2; ++n) _Pragma("unroll") for (int k = 0; k < 2; ++k) \
;         acc[ai][bj][m][n] = __builtin_amdgcn_mfma_f32_16x16x32_bf16(Bt[n][k], At[m][k], acc[ai][bj][m][n], 0, 0, 0); __builtin_amdgcn_s_setprio(0); } while (0)
; #define PG8_WAIT_V(n) asm volatile("s_waitcnt vmcnt(" #n ")" ::: "memory")
; #define PG8_WAIT_L(n) asm volatile("s_waitcnt lgkmcnt(" #n ")" ::: "memory")
; #define PG8_BAR __builtin_amdgcn_s_barrier()
; #define PG8_SCHED __builtin_amdgcn_sched_barrier(0)
; template <class Epi, class Sched, bool ALIGN_EPI = false, bool SP2 = false>
; __device__ __forceinline__ void gemm_phase(PG8_LAS unsigned char* lds, const Gemm g, const Sched& S, const Epi& E) {
;     ...
;             PG8_WAIT_V(8); PG8_WAIT_L(0); PG8_BAR; PG8_MMA(0, 0, At, B0); PG8_MMA(0, 1, At, B1); PG8_BAR; PG8_SCHED;
;             PG8_LDA(At, 1, 1); PG8_STAGE(PG8_SB(1, 0), b3, voffB); PG8_STAGE(PG8_SB(1, 1), b3 + hstep, voffB); PG8_STAGE(PG8_SA(1, 0), a3, voffA);
;             PG8_WAIT_V(8); PG8_WAIT_L(0); PG8_BAR; PG8_MMA(1, 0, At, B0); PG8_MMA(1, 1, At, B1); PG8_BAR; PG8_SCHED;
	s_waitcnt lgkmcnt(0)
	v_mfma_f32_16x16x32_bf16 v[126:129], v[154:157], v[188:191], v[126:129]
	v_mfma_f32_16x16x32_bf16 v[126:129], v[158:161], v[196:199], v[126:129]
	v_mfma_f32_16x16x32_bf16 v[110:113], v[158:161], v[204:207], v[110:113]
	v_mfma_f32_16x16x32_bf16 v[110:113], v[154:157], v[200:203], v[110:113]
	v_mfma_f32_16x16x32_bf16 v[94:97], v[154:157], v[208:211], v[94:97]
	v_mfma_f32_16x16x32_bf16 v[94:97], v[158:161], v[212:215], v[94:97]
	v_mfma_f32_16x16x32_bf16 v[78:81], v[158:161], v[220:223], v[78:81]
	v_mfma_f32_16x16x32_bf16 v[78:81], v[154:157], v[216:219], v[78:81]
	v_mfma_f32_16x16x32_bf16 v[70:73], v[162:165], v[216:219], v[70:73]
	v_mfma_f32_16x16x32_bf16 v[70:73], v[166:169], v[220:223], v[70:73]
	v_mfma_f32_16x16x32_bf16 v[86:89], v[166:169], v[212:215], v[86:89]
	v_mfma_f32_16x16x32_bf16 v[86:89], v[162:165], v[208:211], v[86:89]
	v_mfma_f32_16x16x32_bf16 v[102:105], v[162:165], v[200:203], v[102:105]
	v_mfma_f32_16x16x32_bf16 v[102:105], v[166:169], v[204:207], v[102:105]
	v_mfma_f32_16x16x32_bf16 v[118:121], v[166:169], v[196:199], v[118:121]
	v_mfma_f32_16x16x32_bf16 v[118:121], v[162:165], v[188:191], v[118:121]
	v_mfma_f32_16x16x32_bf16 v[122:125], v[170:173], v[188:191], v[122:125]
	v_mfma_f32_16x16x32_bf16 v[122:125], v[174:177], v[196:199], v[122:125]
	v_mfma_f32_16x16x32_bf16 v[106:109], v[174:177], v[204:207], v[106:109]
	v_mfma_f32_16x16x32_bf16 v[106:109], v[170:173], v[200:203], v[106:109]
	v_mfma_f32_16x16x32_bf16 v[90:93], v[170:173], v[208:211], v[90:93]
	v_mfma_f32_16x16x32_bf16 v[90:93], v[174:177], v[212:215], v[90:93]
	v_mfma_f32_16x16x32_bf16 v[74:77], v[174:177], v[220:223], v[74:77]
	v_mfma_f32_16x16x32_bf16 v[74:77], v[170:173], v[216:219], v[74:77]
	v_mfma_f32_16x16x32_bf16 v[66:69], v[180:183], v[216:219], v[66:69]
	v_mfma_f32_16x16x32_bf16 v[66:69], v[184:187], v[220:223], v[66:69]
	v_mfma_f32_16x16x32_bf16 v[82:85], v[184:187], v[212:215], v[82:85]
	v_mfma_f32_16x16x32_bf16 v[82:85], v[180:183], v[208:211], v[82:85]
	v_mfma_f32_16x16x32_bf16 v[98:101], v[180:183], v[200:203], v[98:101]
	v_mfma_f32_16x16x32_bf16 v[98:101], v[184:187], v[204:207], v[98:101]
	v_mfma_f32_16x16x32_bf16 v[114:117], v[184:187], v[196:199], v[114:117]
	v_mfma_f32_16x16x32_bf16 v[114:117], v[180:183], v[188:191], v[114:117]
	s_barrier
	s_add_u32 s74, s72, 0x8000
	s_addc_u32 s75, s73, 0
	s_add_i32 s77, s77, s3
	s_mov_b32 m0, s77
	ds_read_b128 v[188:191], v152 offset:49152
	ds_read_b128 v[196:199], v152 offset:50176
	ds_read_b128 v[200:203], v152 offset:51200
	ds_read_b128 v[204:207], v152 offset:52224
	ds_read_b128 v[208:211], v152 offset:53248
	ds_read_b128 v[212:215], v152 offset:54272
	ds_read_b128 v[216:219], v152 offset:55296
	ds_read_b128 v[220:223], v152 offset:56320
	global_load_lds_dwordx4 v132, s[74:75]
	s_add_i32 m0, s77, 0x2000
	s_add_u32 s72, s72, 0xc000
	v_lshl_add_u64 v[224:225], s[74:75], 0, v[136:137]
	s_addc_u32 s73, s73, 0
	s_add_i32 s74, s78, s3
	global_load_lds_dwordx4 v[224:225], off
	s_mov_b32 m0, s74
	s_nop 0
	global_load_lds_dwordx4 v132, s[72:73]
	s_add_i32 m0, s74, 0x2000
	s_nop 0
	global_load_lds_dwordx4 v136, s[72:73]
	s_waitcnt vmcnt(6)
	s_waitcnt lgkmcnt(0)
	s_barrier
	s_waitcnt lgkmcnt(0)
	v_mfma_f32_16x16x32_bf16 v[62:65], v[154:157], v[188:191], v[62:65]
	v_mfma_f32_16x16x32_bf16 v[62:65], v[158:161], v[196:199], v[62:65]
	v_mfma_f32_16x16x32_bf16 v[46:49], v[158:161], v[204:207], v[46:49]
	v_mfma_f32_16x16x32_bf16 v[46:49], v[154:157], v[200:203], v[46:49]
	v_mfma_f32_16x16x32_bf16 v[30:33], v[154:157], v[208:211], v[30:33]
	v_mfma_f32_16x16x32_bf16 v[30:33], v[158:161], v[212:215], v[30:33]
	v_mfma_f32_16x16x32_bf16 v[14:17], v[158:161], v[220:223], v[14:17]
	v_mfma_f32_16x16x32_bf16 v[14:17], v[154:157], v[216:219], v[14:17]
	v_mfma_f32_16x16x32_bf16 v[6:9], v[162:165], v[216:219], v[6:9]
	v_mfma_f32_16x16x32_bf16 v[6:9], v[166:169], v[220:223], v[6:9]
	v_mfma_f32_16x16x32_bf16 v[22:25], v[166:169], v[212:215], v[22:25]
	v_mfma_f32_16x16x32_bf16 v[22:25], v[162:165], v[208:211], v[22:25]
	v_mfma_f32_16x16x32_bf16 v[38:41], v[162:165], v[200:203], v[38:41]
	v_mfma_f32_16x16x32_bf16 v[38:41], v[166:169], v[204:207], v[38:41]
	v_mfma_f32_16x16x32_bf16 v[54:57], v[166:169], v[196:199], v[54:57]
	v_mfma_f32_16x16x32_bf16 v[54:57], v[162:165], v[188:191], v[54:57]
	v_mfma_f32_16x16x32_bf16 v[58:61], v[170:173], v[188:191], v[58:61]
	v_mfma_f32_16x16x32_bf16 v[58:61], v[174:177], v[196:199], v[58:61]
	v_mfma_f32_16x16x32_bf16 v[42:45], v[174:177], v[204:207], v[42:45]
	v_mfma_f32_16x16x32_bf16 v[42:45], v[170:173], v[200:203], v[42:45]
	v_mfma_f32_16x16x32_bf16 v[26:29], v[170:173], v[208:211], v[26:29]
	v_mfma_f32_16x16x32_bf16 v[26:29], v[174:177], v[212:215], v[26:29]
	v_mfma_f32_16x16x32_bf16 v[10:13], v[174:177], v[220:223], v[10:13]
	v_mfma_f32_16x16x32_bf16 v[10:13], v[170:173], v[216:219], v[10:13]
	v_mfma_f32_16x16x32_bf16 v[2:5], v[180:183], v[216:219], v[2:5]
	v_mfma_f32_16x16x32_bf16 v[2:5], v[184:187], v[220:223], v[2:5]
	v_mfma_f32_16x16x32_bf16 v[18:21], v[184:187], v[212:215], v[18:21]
	v_mfma_f32_16x16x32_bf16 v[18:21], v[180:183], v[208:211], v[18:21]
	v_mfma_f32_16x16x32_bf16 v[34:37], v[180:183], v[200:203], v[34:37]
	v_mfma_f32_16x16x32_bf16 v[34:37], v[184:187], v[204:207], v[34:37]
	v_mfma_f32_16x16x32_bf16 v[50:53], v[184:187], v[196:199], v[50:53]
	v_mfma_f32_16x16x32_bf16 v[50:53], v[180:183], v[188:191], v[50:53]
	s_barrier
	s_add_i32 s76, s76, 2
	s_add_u32 s48, s48, 0x10000
	s_addc_u32 s49, s49, 0
	s_add_u32 s68, s68, 0x10000
	s_addc_u32 s69, s69, 0
	s_cmp_gt_u32 s76, 61

; #define PG8_STAGE(bufoff, gbase, voff) do { _Pragma("unroll") for (int _i = 0; _i < 2; ++_i) \
;         __builtin_amdgcn_global_load_lds((const unsigned*)((const char*)(gbase) + (voff)[_i]), (PG8_LAS unsigned*)(lds + (bufoff) + ldsw + _i * 8192), 16, 0, 0); } while (0)
; #define PG8_LDA(dst, b, h) do { _Pragma("unroll") for (int m = 0; m < 4; ++m) _Pragma("unroll") for (int k = 0; k < 2; ++k) dst[m][k] = *(const PG8_LAS bf16x8*)(lds + PG8_SA(b, h) + aoff + m * 2048 + k * 1024); } while (0)
; #define PG8_LDB(dst, b, h) do { _Pragma("unroll") for (int n = 0; n < 2; ++n) _Pragma("unroll") for (int k = 0; k < 2; ++k) dst[n][k] = *(const PG8_LAS bf16x8*)(lds + PG8_SB(b, h) + boff + n * 2048 + k * 1024); } while (0)
; #define PG8_MMA(ai, bj, At, Bt) do { __builtin_amdgcn_s_setprio(1); _Pragma("unroll") for (int m = 0; m < 4; ++m) _Pragma("unroll") for (int n = 0; n < 2; ++n) _Pragma("unroll") for (int k = 0; k < 2; ++k) \
;         acc[ai][bj][m][n] = __builtin_amdgcn_mfma_f32_16x16x32_bf16(Bt[n][k], At[m][k], acc[ai][bj][m][n], 0, 0, 0); __builtin_amdgcn_s_setprio(0); } while (0)
; #define PG8_WAIT_V(n) asm volatile("s_waitcnt vmcnt(" #n ")" ::: "memory")
; #define PG8_WAIT_L(n) asm volatile("s_waitcnt lgkmcnt(" #n ")" ::: "memory")
; template <class Epi, class Sched, bool ALIGN_EPI = false, bool SP2 = false>
; __device__ __forceinline__ void gemm_phase(PG8_LAS unsigned char* lds, const Gemm g, const Sched& S, const Epi& E) {
;     ...
;         for (; t < tend; t += 2) {
;             const bool last = (t == nt - 2);
;             const char* a1 = cA + (size_t)(t + 1) * kstep;
;             const char* a2 = last ? nA : cA + (size_t)(t + 2) * kstep; const char* b2 = last ? nB : cB + (size_t)(t + 2) * kstep;
;             const char* a3 = a2 + kstep; const char* b3 = b2 + kstep;
;             if (last && has_next) S.a_ready(nxt);
;             if constexpr (SP2) {
;             PG8_LDB(B0, 0, 0); PG8_LDB(B1, 0, 1); PG8_SCHED; PG8_LDA(At, 0, 0); PG8_STAGE(PG8_SA(1, 1), a1 + hstep, voffA);
;             PG8_WAIT_V(8); PG8_WAIT_L(0); PG8_BAR; PG8_MMA(0, 0, At, B0); PG8_MMA(0, 1, At, B1); PG8_BAR; PG8_SCHED;
;             PG8_LDA(At, 0, 1); PG8_STAGE(PG8_SB(0, 0), b2, voffB); PG8_STAGE(PG8_SB(0, 1), b2 + hstep, voffB); PG8_STAGE(PG8_SA(0, 0), a2, voffA);
;             PG8_WAIT_V(8); PG8_WAIT_L(0); PG8_BAR; PG8_MMA(1, 0, At, B0); PG8_MMA(1, 1, At, B1); PG8_BAR; PG8_SCHED;
.LBB0_199:
	s_add_u32 s44, s44, 0xc000
	s_addc_u32 s45, s45, 0
	s_add_u32 s74, s46, 0x10000
	s_addc_u32 s75, s47, 0
	s_mov_b32 s76, -2
	s_waitcnt lgkmcnt(0)
	s_nop 3
	ds_read_b128 v[148:151], v154
	ds_read_b128 v[158:161], v154 offset:1024
	ds_read_b128 v[162:165], v154 offset:2048
	ds_read_b128 v[166:169], v154 offset:3072
	ds_read_b128 v[170:173], v155
	ds_read_b128 v[174:177], v155 offset:1024
	ds_read_b128 v[180:183], v155 offset:2048
	ds_read_b128 v[184:187], v155 offset:3072
	s_add_u32 s46, s44, 0x4000
	s_addc_u32 s47, s45, 0
	s_cmpk_eq_i32 s76, 0xa8
	s_cselect_b32 s50, s6, s46
	s_cselect_b32 s51, s7, s47
	s_cselect_b32 s48, s24, s74
	s_cselect_b32 s49, s25, s75
	s_add_u32 s46, s50, 0x8000
	s_addc_u32 s47, s51, 0
	s_sub_u32 s46, s44, 0x4000
	s_subb_u32 s47, s45, 0
	s_mov_b32 m0, s57
	s_nop 0
	global_load_lds_dwordx4 v130, s[46:47]
	s_mov_b32 m0, s58
	s_nop 0
	global_load_lds_dwordx4 v134, s[46:47]
	s_add_i32 m0, s26, 0xc000
	ds_read_b128 v[188:191], v156
	ds_read_b128 v[196:199], v156 offset:1024
	ds_read_b128 v[200:203], v156 offset:2048
	ds_read_b128 v[204:207], v156 offset:3072
	ds_read_b128 v[208:211], v156 offset:4096
	ds_read_b128 v[212:215], v156 offset:5120
	ds_read_b128 v[216:219], v156 offset:6144
	ds_read_b128 v[220:223], v156 offset:7168
	global_load_lds_dwordx4 v140, s[44:45]
	s_add_i32 m0, s26, 0xe000
	s_nop 0
	global_load_lds_dwordx4 v142, s[44:45]
	s_waitcnt vmcnt(8)
	s_waitcnt lgkmcnt(0)
	s_barrier
	s_waitcnt lgkmcnt(0)
	v_mfma_f32_16x16x32_bf16 v[126:129], v[148:151], v[188:191], 0
	v_mfma_f32_16x16x32_bf16 v[126:129], v[158:161], v[196:199], v[126:129]
	v_mfma_f32_16x16x32_bf16 v[110:113], v[158:161], v[204:207], 0
	v_mfma_f32_16x16x32_bf16 v[110:113], v[148:151], v[200:203], v[110:113]
	v_mfma_f32_16x16x32_bf16 v[94:97], v[148:151], v[208:211], 0
	v_mfma_f32_16x16x32_bf16 v[94:97], v[158:161], v[212:215], v[94:97]
	v_mfma_f32_16x16x32_bf16 v[78:81], v[158:161], v[220:223], 0
	v_mfma_f32_16x16x32_bf16 v[78:81], v[148:151], v[216:219], v[78:81]
	v_mfma_f32_16x16x32_bf16 v[74:77], v[162:165], v[216:219], 0
	v_mfma_f32_16x16x32_bf16 v[74:77], v[166:169], v[220:223], v[74:77]
	v_mfma_f32_16x16x32_bf16 v[90:93], v[166:169], v[212:215], 0
	v_mfma_f32_16x16x32_bf16 v[90:93], v[162:165], v[208:211], v[90:93]
	v_mfma_f32_16x16x32_bf16 v[106:109], v[162:165], v[200:203], 0
	v_mfma_f32_16x16x32_bf16 v[106:109], v[166:169], v[204:207], v[106:109]
	v_mfma_f32_16x16x32_bf16 v[122:125], v[166:169], v[196:199], 0
	v_mfma_f32_16x16x32_bf16 v[122:125], v[162:165], v[188:191], v[122:125]
	v_mfma_f32_16x16x32_bf16 v[118:121], v[170:173], v[188:191], 0
	v_mfma_f32_16x16x32_bf16 v[118:121], v[174:177], v[196:199], v[118:121]
	v_mfma_f32_16x16x32_bf16 v[102:105], v[174:177], v[204:207], 0
	v_mfma_f32_16x16x32_bf16 v[102:105], v[170:173], v[200:203], v[102:105]
	v_mfma_f32_16x16x32_bf16 v[86:89], v[170:173], v[208:211], 0
	v_mfma_f32_16x16x32_bf16 v[86:89], v[174:177], v[212:215], v[86:89]
	v_mfma_f32_16x16x32_bf16 v[70:73], v[174:177], v[220:223], 0
	v_mfma_f32_16x16x32_bf16 v[70:73], v[170:173], v[216:219], v[70:73]
	v_mfma_f32_16x16x32_bf16 v[66:69], v[180:183], v[216:219], 0
	v_mfma_f32_16x16x32_bf16 v[66:69], v[184:187], v[220:223], v[66:69]
	v_mfma_f32_16x16x32_bf16 v[82:85], v[184:187], v[212:215], 0
	v_mfma_f32_16x16x32_bf16 v[82:85], v[180:183], v[208:211], v[82:85]
	v_mfma_f32_16x16x32_bf16 v[98:101], v[180:183], v[200:203], 0
	v_mfma_f32_16x16x32_bf16 v[98:101], v[184:187], v[204:207], v[98:101]
	v_mfma_f32_16x16x32_bf16 v[114:117], v[184:187], v[196:199], 0
	v_mfma_f32_16x16x32_bf16 v[114:117], v[180:183], v[188:191], v[114:117]
	s_barrier
	s_add_i32 s77, s59, s3
	s_mov_b32 m0, s77
	ds_read_b128 v[188:191], v156 offset:16384
	ds_read_b128 v[196:199], v156 offset:17408
	ds_read_b128 v[200:203], v156 offset:18432
	ds_read_b128 v[204:207], v156 offset:19456
	ds_read_b128 v[208:211], v156 offset:20480
	ds_read_b128 v[212:215], v156 offset:21504
	ds_read_b128 v[216:219], v156 offset:22528
	ds_read_b128 v[220:223], v156 offset:23552
	global_load_lds_dwordx4 v132, s[48:49]
	s_add_i32 m0, s77, 0x2000
	s_add_u32 s78, s48, 0x4000
	s_addc_u32 s79, s49, 0
	s_add_i32 s77, s61, s3
	global_load_lds_dwordx4 v136, s[48:49]
	s_mov_b32 m0, s77
	s_nop 0
	global_load_lds_dwordx4 v132, s[78:79]
	s_add_i32 m0, s77, 0x2000
	s_nop 0
	global_load_lds_dwordx4 v136, s[78:79]
	s_waitcnt vmcnt(6)
	s_waitcnt lgkmcnt(0)
	s_barrier
	s_waitcnt lgkmcnt(0)
	v_mfma_f32_16x16x32_bf16 v[62:65], v[148:151], v[188:191], 0
	v_mfma_f32_16x16x32_bf16 v[62:65], v[158:161], v[196:199], v[62:65]
	v_mfma_f32_16x16x32_bf16 v[46:49], v[158:161], v[204:207], 0
	v_mfma_f32_16x16x32_bf16 v[46:49], v[148:151], v[200:203], v[46:49]
	v_mfma_f32_16x16x32_bf16 v[30:33], v[148:151], v[208:211], 0
	v_mfma_f32_16x16x32_bf16 v[30:33], v[158:161], v[212:215], v[30:33]
	v_mfma_f32_16x16x32_bf16 v[14:17], v[158:161], v[220:223], 0
	v_mfma_f32_16x16x32_bf16 v[14:17], v[148:151], v[216:219], v[14:17]
	v_mfma_f32_16x16x32_bf16 v[10:13], v[162:165], v[216:219], 0
	v_mfma_f32_16x16x32_bf16 v[10:13], v[166:169], v[220:223], v[10:13]
	v_mfma_f32_16x16x32_bf16 v[26:29], v[166:169], v[212:215], 0
	v_mfma_f32_16x16x32_bf16 v[26:29], v[162:165], v[208:211], v[26:29]
	v_mfma_f32_16x16x32_bf16 v[42:45], v[162:165], v[200:203], 0
	v_mfma_f32_16x16x32_bf16 v[42:45], v[166:169], v[204:207], v[42:45]
	v_mfma_f32_16x16x32_bf16 v[58:61], v[166:169], v[196:199], 0
	v_mfma_f32_16x16x32_bf16 v[58:61], v[162:165], v[188:191], v[58:61]
	v_mfma_f32_16x16x32_bf16 v[54:57], v[170:173], v[188:191], 0
	v_mfma_f32_16x16x32_bf16 v[54:57], v[174:177], v[196:199], v[54:57]
	v_mfma_f32_16x16x32_bf16 v[38:41], v[174:177], v[204:207], 0
	v_mfma_f32_16x16x32_bf16 v[38:41], v[170:173], v[200:203], v[38:41]
	v_mfma_f32_16x16x32_bf16 v[22:25], v[170:173], v[208:211], 0
	v_mfma_f32_16x16x32_bf16 v[22:25], v[174:177], v[212:215], v[22:25]
	v_mfma_f32_16x16x32_bf16 v[6:9], v[174:177], v[220:223], 0
	v_mfma_f32_16x16x32_bf16 v[6:9], v[170:173], v[216:219], v[6:9]
	v_mfma_f32_16x16x32_bf16 v[2:5], v[180:183], v[216:219], 0
	v_mfma_f32_16x16x32_bf16 v[2:5], v[184:187], v[220:223], v[2:5]
	v_mfma_f32_16x16x32_bf16 v[18:21], v[184:187], v[212:215], 0
	v_mfma_f32_16x16x32_bf16 v[18:21], v[180:183], v[208:211], v[18:21]
	v_mfma_f32_16x16x32_bf16 v[34:37], v[180:183], v[200:203], 0
	v_mfma_f32_16x16x32_bf16 v[34:37], v[184:187], v[204:207], v[34:37]
	v_mfma_f32_16x16x32_bf16 v[50:53], v[184:187], v[196:199], 0
	v_mfma_f32_16x16x32_bf16 v[50:53], v[180:183], v[188:191], v[50:53]
	s_barrier
; #define PG8_STAGE(bufoff, gbase, voff) do { _Pragma("unroll") for (int _i = 0; _i < 2; ++_i) \
;         __builtin_amdgcn_global_load_lds((const unsigned*)((const char*)(gbase) + (voff)[_i]), (PG8_LAS unsigned*)(lds + (bufoff) + ldsw + _i * 8192), 16, 0, 0); } while (0)
; #define PG8_LDA(dst, b, h) do { _Pragma("unroll") for (int m = 0; m < 4; ++m) _Pragma("unroll") for (int k = 0; k < 2; ++k) dst[m][k] = *(const PG8_LAS bf16x8*)(lds + PG8_SA(b, h) + aoff + m * 2048 + k * 1024); } while (0)
; #define PG8_LDB(dst, b, h) do { _Pragma("unroll") for (int n = 0; n < 2; ++n) _Pragma("unroll") for (int k = 0; k < 2; ++k) dst[n][k] = *(const PG8_LAS bf16x8*)(lds + PG8_SB(b, h) + boff + n * 2048 + k * 1024); } while (0)
; #define PG8_MMA(ai, bj, At, Bt) do { __builtin_amdgcn_s_setprio(1); _Pragma("unroll") for (int m = 0; m < 4; ++m) _Pragma("unroll") for (int n = 0; n < 2; ++n) _Pragma("unroll") for (int k = 0; k < 2; ++k) \
;         acc[ai][bj][m][n] = __builtin_amdgcn_mfma_f32_16x16x32_bf16(Bt[n][k], At[m][k], acc[ai][bj][m][n], 0, 0, 0); __builtin_amdgcn_s_setprio(0); } while (0)
; #define PG8_WAIT_V(n) asm volatile("s_waitcnt vmcnt(" #n ")" ::: "memory")
; #define PG8_WAIT_L(n) asm volatile("s_waitcnt lgkmcnt(" #n ")" ::: "memory")
; #define PG8_BAR __builtin_amdgcn_s_barrier()
; #define PG8_SCHED __builtin_amdgcn_sched_barrier(0)
; template <class Epi, class Sched, bool ALIGN_EPI = false, bool SP2 = false>
; __device__ __forceinline__ void gemm_phase(PG8_LAS unsigned char* lds, const Gemm g, const Sched& S, const Epi& E) {
;     ...
;             PG8_LDB(B0, 1, 0); PG8_LDB(B1, 1, 1); PG8_SCHED; PG8_LDA(At, 1, 0); PG8_STAGE(PG8_SA(0, 1), a2 + hstep, voffA);
;             PG8_WAIT_V(8); PG8_WAIT_L(0); PG8_BAR; PG8_MMA(0, 0, At, B0); PG8_MMA(0, 1, At, B1); PG8_BAR; PG8_SCHED;
;             PG8_LDA(At, 1, 1); PG8_STAGE(PG8_SB(1, 0), b3, voffB); PG8_STAGE(PG8_SB(1, 1), b3 + hstep, voffB); PG8_STAGE(PG8_SA(1, 0), a3, voffA);
;             PG8_WAIT_V(8); PG8_WAIT_L(0); PG8_BAR; PG8_MMA(1, 0, At, B0); PG8_MMA(1, 1, At, B1); PG8_BAR; PG8_SCHED;
	s_add_i32 s77, 0, 0x18000
	v_add_u32_e32 v138, s77, v153
	s_add_i32 s78, 0, 0x1c000
	ds_read_b128 v[148:151], v138
	ds_read_b128 v[158:161], v138 offset:1024
	ds_read_b128 v[162:165], v138 offset:2048
	ds_read_b128 v[166:169], v138 offset:3072
	v_add_u32_e32 v138, s78, v153
	ds_read_b128 v[170:173], v138
	ds_read_b128 v[174:177], v138 offset:1024
	ds_read_b128 v[180:183], v138 offset:2048
	ds_read_b128 v[184:187], v138 offset:3072
	s_mov_b32 m0, s26
	s_nop 0
	global_load_lds_dwordx4 v130, s[50:51]
	s_mov_b32 m0, s27
	s_nop 0
	global_load_lds_dwordx4 v134, s[50:51]
	s_add_u32 s50, s50, 0x4000
	s_addc_u32 s51, s51, 0
	s_mov_b32 m0, s28
	ds_read_b128 v[188:191], v156 offset:32768
	ds_read_b128 v[196:199], v156 offset:33792
	ds_read_b128 v[200:203], v156 offset:34816
	ds_read_b128 v[204:207], v156 offset:35840
	ds_read_b128 v[208:211], v156 offset:36864
	ds_read_b128 v[212:215], v156 offset:37888
	ds_read_b128 v[216:219], v156 offset:38912
	ds_read_b128 v[220:223], v156 offset:39936
	global_load_lds_dwordx4 v130, s[50:51]
	s_mov_b32 m0, s29
	s_nop 0
	global_load_lds_dwordx4 v134, s[50:51]
	s_waitcnt vmcnt(8)
	s_waitcnt lgkmcnt(0)
	s_barrier
	s_waitcnt lgkmcnt(0)
	v_mfma_f32_16x16x32_bf16 v[126:129], v[148:151], v[188:191], v[126:129]
	v_mfma_f32_16x16x32_bf16 v[126:129], v[158:161], v[196:199], v[126:129]
	v_mfma_f32_16x16x32_bf16 v[110:113], v[158:161], v[204:207], v[110:113]
	v_mfma_f32_16x16x32_bf16 v[110:113], v[148:151], v[200:203], v[110:113]
	v_mfma_f32_16x16x32_bf16 v[94:97], v[148:151], v[208:211], v[94:97]
	v_mfma_f32_16x16x32_bf16 v[94:97], v[158:161], v[212:215], v[94:97]
	v_mfma_f32_16x16x32_bf16 v[78:81], v[158:161], v[220:223], v[78:81]
	v_mfma_f32_16x16x32_bf16 v[78:81], v[148:151], v[216:219], v[78:81]
	v_mfma_f32_16x16x32_bf16 v[74:77], v[162:165], v[216:219], v[74:77]
	v_mfma_f32_16x16x32_bf16 v[74:77], v[166:169], v[220:223], v[74:77]
	v_mfma_f32_16x16x32_bf16 v[90:93], v[166:169], v[212:215], v[90:93]
	v_mfma_f32_16x16x32_bf16 v[90:93], v[162:165], v[208:211], v[90:93]
	v_mfma_f32_16x16x32_bf16 v[106:109], v[162:165], v[200:203], v[106:109]
	v_mfma_f32_16x16x32_bf16 v[106:109], v[166:169], v[204:207], v[106:109]
	v_mfma_f32_16x16x32_bf16 v[122:125], v[166:169], v[196:199], v[122:125]
	v_mfma_f32_16x16x32_bf16 v[122:125], v[162:165], v[188:191], v[122:125]
	v_mfma_f32_16x16x32_bf16 v[118:121], v[170:173], v[188:191], v[118:121]
	v_mfma_f32_16x16x32_bf16 v[118:121], v[174:177], v[196:199], v[118:121]
	v_mfma_f32_16x16x32_bf16 v[102:105], v[174:177], v[204:207], v[102:105]
	v_mfma_f32_16x16x32_bf16 v[102:105], v[170:173], v[200:203], v[102:105]
	v_mfma_f32_16x16x32_bf16 v[86:89], v[170:173], v[208:211], v[86:89]
	v_mfma_f32_16x16x32_bf16 v[86:89], v[174:177], v[212:215], v[86:89]
	v_mfma_f32_16x16x32_bf16 v[70:73], v[174:177], v[220:223], v[70:73]
	v_mfma_f32_16x16x32_bf16 v[70:73], v[170:173], v[216:219], v[70:73]
	v_mfma_f32_16x16x32_bf16 v[66:69], v[180:183], v[216:219], v[66:69]
	v_mfma_f32_16x16x32_bf16 v[66:69], v[184:187], v[220:223], v[66:69]
	v_mfma_f32_16x16x32_bf16 v[82:85], v[184:187], v[212:215], v[82:85]
	v_mfma_f32_16x16x32_bf16 v[82:85], v[180:183], v[208:211], v[82:85]
	v_mfma_f32_16x16x32_bf16 v[98:101], v[180:183], v[200:203], v[98:101]
	v_mfma_f32_16x16x32_bf16 v[98:101], v[184:187], v[204:207], v[98:101]
	v_mfma_f32_16x16x32_bf16 v[114:117], v[184:187], v[196:199], v[114:117]
	v_mfma_f32_16x16x32_bf16 v[114:117], v[180:183], v[188:191], v[114:117]
	s_barrier
	s_add_u32 s50, s48, 0x8000
	s_addc_u32 s51, s49, 0
	s_add_i32 s77, s77, s3
	s_mov_b32 m0, s77
	ds_read_b128 v[188:191], v156 offset:49152
	ds_read_b128 v[196:199], v156 offset:50176
	ds_read_b128 v[200:203], v156 offset:51200
	ds_read_b128 v[204:207], v156 offset:52224
	ds_read_b128 v[208:211], v156 offset:53248
	ds_read_b128 v[212:215], v156 offset:54272
	ds_read_b128 v[216:219], v156 offset:55296
	ds_read_b128 v[220:223], v156 offset:56320
	global_load_lds_dwordx4 v132, s[50:51]
	s_add_i32 m0, s77, 0x2000
	s_add_u32 s48, s48, 0xc000
	v_lshl_add_u64 v[224:225], s[50:51], 0, v[136:137]
	s_addc_u32 s49, s49, 0
	s_add_i32 s50, s78, s3
	global_load_lds_dwordx4 v[224:225], off
	s_mov_b32 m0, s50
	s_nop 0
	global_load_lds_dwordx4 v132, s[48:49]
	s_add_i32 m0, s50, 0x2000
	s_nop 0
	global_load_lds_dwordx4 v136, s[48:49]
	s_waitcnt vmcnt(6)
	s_waitcnt lgkmcnt(0)
	s_barrier
	s_waitcnt lgkmcnt(0)
	v_mfma_f32_16x16x32_bf16 v[62:65], v[148:151], v[188:191], v[62:65]
	v_mfma_f32_16x16x32_bf16 v[62:65], v[158:161], v[196:199], v[62:65]
	v_mfma_f32_16x16x32_bf16 v[46:49], v[158:161], v[204:207], v[46:49]
	v_mfma_f32_16x16x32_bf16 v[46:49], v[148:151], v[200:203], v[46:49]
	v_mfma_f32_16x16x32_bf16 v[30:33], v[148:151], v[208:211], v[30:33]
	v_mfma_f32_16x16x32_bf16 v[30:33], v[158:161], v[212:215], v[30:33]
	v_mfma_f32_16x16x32_bf16 v[14:17], v[158:161], v[220:223], v[14:17]
	v_mfma_f32_16x16x32_bf16 v[14:17], v[148:151], v[216:219], v[14:17]
	v_mfma_f32_16x16x32_bf16 v[10:13], v[162:165], v[216:219], v[10:13]
	v_mfma_f32_16x16x32_bf16 v[10:13], v[166:169], v[220:223], v[10:13]
	v_mfma_f32_16x16x32_bf16 v[26:29], v[166:169], v[212:215], v[26:29]
	v_mfma_f32_16x16x32_bf16 v[26:29], v[162:165], v[208:211], v[26:29]
	v_mfma_f32_16x16x32_bf16 v[42:45], v[162:165], v[200:203], v[42:45]
	v_mfma_f32_16x16x32_bf16 v[42:45], v[166:169], v[204:207], v[42:45]
	v_mfma_f32_16x16x32_bf16 v[58:61], v[166:169], v[196:199], v[58:61]
	v_mfma_f32_16x16x32_bf16 v[58:61], v[162:165], v[188:191], v[58:61]
	v_mfma_f32_16x16x32_bf16 v[54:57], v[170:173], v[188:191], v[54:57]
	v_mfma_f32_16x16x32_bf16 v[54:57], v[174:177], v[196:199], v[54:57]
	v_mfma_f32_16x16x32_bf16 v[38:41], v[174:177], v[204:207], v[38:41]
	v_mfma_f32_16x16x32_bf16 v[38:41], v[170:173], v[200:203], v[38:41]
	v_mfma_f32_16x16x32_bf16 v[22:25], v[170:173], v[208:211], v[22:25]
	v_mfma_f32_16x16x32_bf16 v[22:25], v[174:177], v[212:215], v[22:25]
	v_mfma_f32_16x16x32_bf16 v[6:9], v[174:177], v[220:223], v[6:9]
	v_mfma_f32_16x16x32_bf16 v[6:9], v[170:173], v[216:219], v[6:9]
	v_mfma_f32_16x16x32_bf16 v[2:5], v[180:183], v[216:219], v[2:5]
	v_mfma_f32_16x16x32_bf16 v[2:5], v[184:187], v[220:223], v[2:5]
	v_mfma_f32_16x16x32_bf16 v[18:21], v[184:187], v[212:215], v[18:21]
	v_mfma_f32_16x16x32_bf16 v[18:21], v[180:183], v[208:211], v[18:21]
	v_mfma_f32_16x16x32_bf16 v[34:37], v[180:183], v[200:203], v[34:37]
	v_mfma_f32_16x16x32_bf16 v[34:37], v[184:187], v[204:207], v[34:37]
	v_mfma_f32_16x16x32_bf16 v[50:53], v[184:187], v[196:199], v[50:53]
	v_mfma_f32_16x16x32_bf16 v[50:53], v[180:183], v[188:191], v[50:53]
	s_barrier
	s_add_i32 s76, s76, 2
	s_add_u32 s44, s44, 0x10000
	s_addc_u32 s45, s45, 0
	s_add_u32 s74, s74, 0x10000
	s_addc_u32 s75, s75, 0
	s_cmpk_gt_u32 s76, 0xa9

;     __device__ __forceinline__ bool next(int i, Unit& u) const { if (i >= 2) return false; const int xcd = c & 7, off = c >> 3; u.pm = 16 * i + 4 * (xcd >> 1) + (off & 3); u.pn = 8 * (xcd & 1) + (off >> 2); return true; }
; #define PG8_STAGE(bufoff, gbase, voff) do { _Pragma("unroll") for (int _i = 0; _i < 2; ++_i) \
;         __builtin_amdgcn_global_load_lds((const unsigned*)((const char*)(gbase) + (voff)[_i]), (PG8_LAS unsigned*)(lds + (bufoff) + ldsw + _i * 8192), 16, 0, 0); } while (0)
; #define PG8_LDA(dst, b, h) do { _Pragma("unroll") for (int m = 0; m < 4; ++m) _Pragma("unroll") for (int k = 0; k < 2; ++k) dst[m][k] = *(const PG8_LAS bf16x8*)(lds + PG8_SA(b, h) + aoff + m * 2048 + k * 1024); } while (0)
; #define PG8_WAIT_V(n) asm volatile("s_waitcnt vmcnt(" #n ")" ::: "memory")
; #define PG8_BAR __builtin_amdgcn_s_barrier()
; template <class Epi, class Sched, bool ALIGN_EPI = false, bool SP2 = false>
; __device__ __forceinline__ void gemm_phase(PG8_LAS unsigned char* lds, const Gemm g, const Sched& S, const Epi& E) {
;     ...
;         const bool has_next = S.next(ui + 1, nxt);
;         const char* nA = has_next ? (const char*)g.A + (size_t)nxt.pm * tstep : cA; const char* nB = has_next ? (const char*)g.Bt + (size_t)nxt.pn * tstep : cB;
;         constexpr int NSEG = Epi::HAS_MID ? 2 : 1; int t = 0;
; #pragma unroll
;         for (int seg = 0; seg < NSEG; ++seg) { const int tend = (seg + 1 < NSEG) ? (nt >> 1) : nt;
;         for (; t < tend; t += 2) {
;             const bool last = (t == nt - 2);
;             const char* a1 = cA + (size_t)(t + 1) * kstep;
;             const char* a2 = last ? nA : cA + (size_t)(t + 2) * kstep; const char* b2 = last ? nB : cB + (size_t)(t + 2) * kstep;
;             const char* a3 = a2 + kstep; const char* b3 = b2 + kstep;
;             if (last && has_next) S.a_ready(nxt);
;             if constexpr (SP2) {
;             PG8_LDB(B0, 0, 0); PG8_LDB(B1, 0, 1); PG8_SCHED; PG8_LDA(At, 0, 0); PG8_STAGE(PG8_SA(1, 1), a1 + hstep, voffA);
;             PG8_WAIT_V(8); PG8_WAIT_L(0); PG8_BAR; PG8_MMA(0, 0, At, B0); PG8_MMA(0, 1, At, B1); PG8_BAR; PG8_SCHED;
;             PG8_LDA(At, 0, 1); PG8_STAGE(PG8_SB(0, 0), b2, voffB); PG8_STAGE(PG8_SB(0, 1), b2 + hstep, voffB); PG8_STAGE(PG8_SA(0, 0), a2, voffA);
;             PG8_WAIT_V(8); PG8_WAIT_L(0); PG8_BAR; PG8_MMA(1, 0, At, B0); PG8_MMA(1, 1, At, B1); PG8_BAR; PG8_SCHED;
.LBB0_289:
	s_ashr_i32 s19, s18, 31
	s_lshl_b64 s[46:47], s[18:19], 21
	s_add_u32 s46, s42, s46
	s_addc_u32 s47, s43, s47
	s_and_b64 s[48:49], s[0:1], exec
	s_cselect_b32 s5, s47, s73
	s_cselect_b32 s19, s46, s72
	s_ashr_i32 s17, s16, 31
	s_lshl_b64 s[48:49], s[16:17], 21
	s_add_u32 s48, s70, s48
	s_addc_u32 s49, s71, s49
	s_and_b64 s[58:59], s[0:1], exec
	s_cselect_b32 s17, s49, s75
	s_cselect_b32 s26, s48, s74
	s_add_u32 s72, s72, 0xc000
	s_addc_u32 s73, s73, 0
	s_add_u32 s33, s74, 0x10000
	s_addc_u32 s56, s75, 0
	s_mov_b32 s58, -2
	s_nop 3
	ds_read_b128 v[146:149], v162
	ds_read_b128 v[150:153], v162 offset:1024
	ds_read_b128 v[154:157], v162 offset:2048
	ds_read_b128 v[168:171], v162 offset:3072
	ds_read_b128 v[172:175], v163
	ds_read_b128 v[180:183], v163 offset:1024
	ds_read_b128 v[184:187], v163 offset:2048
	ds_read_b128 v[188:191], v163 offset:3072
	s_add_u32 s59, s72, 0x4000
	s_addc_u32 s62, s73, 0
	s_cmp_eq_u32 s58, 60
	s_cselect_b32 s78, s19, s59
	s_cselect_b32 s79, s5, s62
	s_cselect_b32 s76, s26, s33
	s_cselect_b32 s77, s17, s56
	s_add_u32 s74, s78, 0x8000
	s_addc_u32 s75, s79, 0
	s_sub_u32 s74, s72, 0x4000
	s_subb_u32 s75, s73, 0
	s_mov_b32 m0, s51
	s_nop 0
	global_load_lds_dwordx4 v130, s[74:75]
	s_mov_b32 m0, s57
	s_nop 0
	global_load_lds_dwordx4 v134, s[74:75]
	s_add_i32 m0, s15, 0xc000
	ds_read_b128 v[198:201], v164
	ds_read_b128 v[202:205], v164 offset:1024
	ds_read_b128 v[206:209], v164 offset:2048
	ds_read_b128 v[210:213], v164 offset:3072
	ds_read_b128 v[214:217], v164 offset:4096
	ds_read_b128 v[218:221], v164 offset:5120
	ds_read_b128 v[222:225], v164 offset:6144
	ds_read_b128 v[226:229], v164 offset:7168
	global_load_lds_dwordx4 v138, s[72:73]
	s_add_i32 m0, s15, 0xe000
	s_nop 0
	global_load_lds_dwordx4 v140, s[72:73]
	s_waitcnt vmcnt(8)
	s_waitcnt lgkmcnt(0)
	s_barrier
	s_waitcnt lgkmcnt(0)
	v_mfma_f32_16x16x32_bf16 v[126:129], v[146:149], v[198:201], 0
	v_mfma_f32_16x16x32_bf16 v[126:129], v[150:153], v[202:205], v[126:129]
	v_mfma_f32_16x16x32_bf16 v[110:113], v[150:153], v[210:213], 0
	v_mfma_f32_16x16x32_bf16 v[110:113], v[146:149], v[206:209], v[110:113]
	v_mfma_f32_16x16x32_bf16 v[94:97], v[146:149], v[214:217], 0
	v_mfma_f32_16x16x32_bf16 v[94:97], v[150:153], v[218:221], v[94:97]
	v_mfma_f32_16x16x32_bf16 v[78:81], v[150:153], v[226:229], 0
	v_mfma_f32_16x16x32_bf16 v[78:81], v[146:149], v[222:225], v[78:81]
	v_mfma_f32_16x16x32_bf16 v[74:77], v[154:157], v[222:225], 0
	v_mfma_f32_16x16x32_bf16 v[74:77], v[168:171], v[226:229], v[74:77]
	v_mfma_f32_16x16x32_bf16 v[90:93], v[168:171], v[218:221], 0
	v_mfma_f32_16x16x32_bf16 v[90:93], v[154:157], v[214:217], v[90:93]
	v_mfma_f32_16x16x32_bf16 v[106:109], v[154:157], v[206:209], 0
	v_mfma_f32_16x16x32_bf16 v[106:109], v[168:171], v[210:213], v[106:109]
	v_mfma_f32_16x16x32_bf16 v[122:125], v[168:171], v[202:205], 0
	v_mfma_f32_16x16x32_bf16 v[122:125], v[154:157], v[198:201], v[122:125]
	v_mfma_f32_16x16x32_bf16 v[118:121], v[172:175], v[198:201], 0
	v_mfma_f32_16x16x32_bf16 v[118:121], v[180:183], v[202:205], v[118:121]
	v_mfma_f32_16x16x32_bf16 v[102:105], v[180:183], v[210:213], 0
	v_mfma_f32_16x16x32_bf16 v[102:105], v[172:175], v[206:209], v[102:105]
	v_mfma_f32_16x16x32_bf16 v[86:89], v[172:175], v[214:217], 0
	v_mfma_f32_16x16x32_bf16 v[86:89], v[180:183], v[218:221], v[86:89]
	v_mfma_f32_16x16x32_bf16 v[70:73], v[180:183], v[226:229], 0
	v_mfma_f32_16x16x32_bf16 v[70:73], v[172:175], v[222:225], v[70:73]
	v_mfma_f32_16x16x32_bf16 v[66:69], v[184:187], v[222:225], 0
	v_mfma_f32_16x16x32_bf16 v[66:69], v[188:191], v[226:229], v[66:69]
	v_mfma_f32_16x16x32_bf16 v[82:85], v[188:191], v[218:221], 0
	v_mfma_f32_16x16x32_bf16 v[82:85], v[184:187], v[214:217], v[82:85]
	v_mfma_f32_16x16x32_bf16 v[98:101], v[184:187], v[206:209], 0
	v_mfma_f32_16x16x32_bf16 v[98:101], v[188:191], v[210:213], v[98:101]
	v_mfma_f32_16x16x32_bf16 v[114:117], v[188:191], v[202:205], 0
	v_mfma_f32_16x16x32_bf16 v[114:117], v[184:187], v[198:201], v[114:117]
	s_barrier
	s_add_i32 s59, s81, s3
	s_mov_b32 m0, s59
	ds_read_b128 v[198:201], v164 offset:16384
	ds_read_b128 v[202:205], v164 offset:17408
	ds_read_b128 v[206:209], v164 offset:18432
	ds_read_b128 v[210:213], v164 offset:19456
	ds_read_b128 v[214:217], v164 offset:20480
	ds_read_b128 v[218:221], v164 offset:21504
	ds_read_b128 v[222:225], v164 offset:22528
	ds_read_b128 v[226:229], v164 offset:23552
	global_load_lds_dwordx4 v132, s[76:77]
	s_add_i32 m0, s59, 0x2000
	s_add_u32 s62, s76, 0x4000
	s_addc_u32 s63, s77, 0
	s_add_i32 s59, s82, s3
	global_load_lds_dwordx4 v136, s[76:77]
	s_mov_b32 m0, s59
	s_nop 0
	global_load_lds_dwordx4 v132, s[62:63]
	s_add_i32 m0, s59, 0x2000
	s_nop 0
	global_load_lds_dwordx4 v136, s[62:63]
	s_waitcnt vmcnt(6)
	s_waitcnt lgkmcnt(0)
	s_barrier
; #define PG8_STAGE(bufoff, gbase, voff) do { _Pragma("unroll") for (int _i = 0; _i < 2; ++_i) \
;         __builtin_amdgcn_global_load_lds((const unsigned*)((const char*)(gbase) + (voff)[_i]), (PG8_LAS unsigned*)(lds + (bufoff) + ldsw + _i * 8192), 16, 0, 0); } while (0)
; #define PG8_LDA(dst, b, h) do { _Pragma("unroll") for (int m = 0; m < 4; ++m) _Pragma("unroll") for (int k = 0; k < 2; ++k) dst[m][k] = *(const PG8_LAS bf16x8*)(lds + PG8_SA(b, h) + aoff + m * 2048 + k * 1024); } while (0)
; #define PG8_LDB(dst, b, h) do { _Pragma("unroll") for (int n = 0; n < 2; ++n) _Pragma("unroll") for (int k = 0; k < 2; ++k) dst[n][k] = *(const PG8_LAS bf16x8*)(lds + PG8_SB(b, h) + boff + n * 2048 + k * 1024); } while (0)
; #define PG8_MMA(ai, bj, At, Bt) do { __builtin_amdgcn_s_setprio(1); _Pragma("unroll") for (int m = 0; m < 4; ++m) _Pragma("unroll") for (int n = 0; n < 2; ++n) _Pragma("unroll") for (int k = 0; k < 2; ++k) \
;         acc[ai][bj][m][n] = __builtin_amdgcn_mfma_f32_16x16x32_bf16(Bt[n][k], At[m][k], acc[ai][bj][m][n], 0, 0, 0); __builtin_amdgcn_s_setprio(0); } while (0)
; #define PG8_WAIT_V(n) asm volatile("s_waitcnt vmcnt(" #n ")" ::: "memory")
; #define PG8_WAIT_L(n) asm volatile("s_waitcnt lgkmcnt(" #n ")" ::: "memory")
; #define PG8_BAR __builtin_amdgcn_s_barrier()
; #define PG8_SCHED __builtin_amdgcn_sched_barrier(0)
; template <class Epi, class Sched, bool ALIGN_EPI = false, bool SP2 = false>
; __device__ __forceinline__ void gemm_phase(PG8_LAS unsigned char* lds, const Gemm g, const Sched& S, const Epi& E) {
;     ...
;             PG8_WAIT_V(8); PG8_WAIT_L(0); PG8_BAR; PG8_MMA(1, 0, At, B0); PG8_MMA(1, 1, At, B1); PG8_BAR; PG8_SCHED;
;             PG8_LDB(B0, 1, 0); PG8_LDB(B1, 1, 1); PG8_SCHED; PG8_LDA(At, 1, 0); PG8_STAGE(PG8_SA(0, 1), a2 + hstep, voffA);
;             PG8_WAIT_V(8); PG8_WAIT_L(0); PG8_BAR; PG8_MMA(0, 0, At, B0); PG8_MMA(0, 1, At, B1); PG8_BAR; PG8_SCHED;
;             PG8_LDA(At, 1, 1); PG8_STAGE(PG8_SB(1, 0), b3, voffB); PG8_STAGE(PG8_SB(1, 1), b3 + hstep, voffB); PG8_STAGE(PG8_SA(1, 0), a3, voffA);
	s_waitcnt lgkmcnt(0)
	v_mfma_f32_16x16x32_bf16 v[62:65], v[146:149], v[198:201], 0
	v_mfma_f32_16x16x32_bf16 v[62:65], v[150:153], v[202:205], v[62:65]
	v_mfma_f32_16x16x32_bf16 v[46:49], v[150:153], v[210:213], 0
	v_mfma_f32_16x16x32_bf16 v[46:49], v[146:149], v[206:209], v[46:49]
	v_mfma_f32_16x16x32_bf16 v[30:33], v[146:149], v[214:217], 0
	v_mfma_f32_16x16x32_bf16 v[30:33], v[150:153], v[218:221], v[30:33]
	v_mfma_f32_16x16x32_bf16 v[14:17], v[150:153], v[226:229], 0
	v_mfma_f32_16x16x32_bf16 v[14:17], v[146:149], v[222:225], v[14:17]
	v_mfma_f32_16x16x32_bf16 v[10:13], v[154:157], v[222:225], 0
	v_mfma_f32_16x16x32_bf16 v[10:13], v[168:171], v[226:229], v[10:13]
	v_mfma_f32_16x16x32_bf16 v[26:29], v[168:171], v[218:221], 0
	v_mfma_f32_16x16x32_bf16 v[26:29], v[154:157], v[214:217], v[26:29]
	v_mfma_f32_16x16x32_bf16 v[42:45], v[154:157], v[206:209], 0
	v_mfma_f32_16x16x32_bf16 v[42:45], v[168:171], v[210:213], v[42:45]
	v_mfma_f32_16x16x32_bf16 v[58:61], v[168:171], v[202:205], 0
	v_mfma_f32_16x16x32_bf16 v[58:61], v[154:157], v[198:201], v[58:61]
	v_mfma_f32_16x16x32_bf16 v[54:57], v[172:175], v[198:201], 0
	v_mfma_f32_16x16x32_bf16 v[54:57], v[180:183], v[202:205], v[54:57]
	v_mfma_f32_16x16x32_bf16 v[38:41], v[180:183], v[210:213], 0
	v_mfma_f32_16x16x32_bf16 v[38:41], v[172:175], v[206:209], v[38:41]
	v_mfma_f32_16x16x32_bf16 v[22:25], v[172:175], v[214:217], 0
	v_mfma_f32_16x16x32_bf16 v[22:25], v[180:183], v[218:221], v[22:25]
	v_mfma_f32_16x16x32_bf16 v[6:9], v[180:183], v[226:229], 0
	v_mfma_f32_16x16x32_bf16 v[6:9], v[172:175], v[222:225], v[6:9]
	v_mfma_f32_16x16x32_bf16 v[2:5], v[184:187], v[222:225], 0
	v_mfma_f32_16x16x32_bf16 v[2:5], v[188:191], v[226:229], v[2:5]
	v_mfma_f32_16x16x32_bf16 v[18:21], v[188:191], v[218:221], 0
	v_mfma_f32_16x16x32_bf16 v[18:21], v[184:187], v[214:217], v[18:21]
	v_mfma_f32_16x16x32_bf16 v[34:37], v[184:187], v[206:209], 0
	v_mfma_f32_16x16x32_bf16 v[34:37], v[188:191], v[210:213], v[34:37]
	v_mfma_f32_16x16x32_bf16 v[50:53], v[188:191], v[202:205], 0
	v_mfma_f32_16x16x32_bf16 v[50:53], v[184:187], v[198:201], v[50:53]
	s_barrier
	s_add_i32 s59, 0, 0x18000
	v_add_u32_e32 v158, s59, v160
	s_add_i32 s64, 0, 0x1c000
	ds_read_b128 v[146:149], v158
	ds_read_b128 v[150:153], v158 offset:1024
	ds_read_b128 v[154:157], v158 offset:2048
	ds_read_b128 v[168:171], v158 offset:3072
	v_add_u32_e32 v158, s64, v160
	ds_read_b128 v[172:175], v158
	ds_read_b128 v[180:183], v158 offset:1024
	ds_read_b128 v[184:187], v158 offset:2048
	ds_read_b128 v[188:191], v158 offset:3072
	s_mov_b32 m0, s15
	s_nop 0
	global_load_lds_dwordx4 v130, s[78:79]
	s_mov_b32 m0, s27
	s_nop 0
	global_load_lds_dwordx4 v134, s[78:79]
	s_add_u32 s62, s78, 0x4000
	s_addc_u32 s63, s79, 0
	s_mov_b32 m0, s28
	ds_read_b128 v[198:201], v164 offset:32768
	ds_read_b128 v[202:205], v164 offset:33792
	ds_read_b128 v[206:209], v164 offset:34816
	ds_read_b128 v[210:213], v164 offset:35840
	ds_read_b128 v[214:217], v164 offset:36864
	ds_read_b128 v[218:221], v164 offset:37888
	ds_read_b128 v[222:225], v164 offset:38912
	ds_read_b128 v[226:229], v164 offset:39936
	global_load_lds_dwordx4 v130, s[62:63]
	s_mov_b32 m0, s29
	s_nop 0
	global_load_lds_dwordx4 v134, s[62:63]
	s_waitcnt vmcnt(8)
	s_waitcnt lgkmcnt(0)
	s_barrier
; #define PG8_STAGE(bufoff, gbase, voff) do { _Pragma("unroll") for (int _i = 0; _i < 2; ++_i) \
;         __builtin_amdgcn_global_load_lds((const unsigned*)((const char*)(gbase) + (voff)[_i]), (PG8_LAS unsigned*)(lds + (bufoff) + ldsw + _i * 8192), 16, 0, 0); } while (0)
; #define PG8_LDA(dst, b, h) do { _Pragma("unroll") for (int m = 0; m < 4; ++m) _Pragma("unroll") for (int k = 0; k < 2; ++k) dst[m][k] = *(const PG8_LAS bf16x8*)(lds + PG8_SA(b, h) + aoff + m * 2048 + k * 1024); } while (0)
; #define PG8_MMA(ai, bj, At, Bt) do { __builtin_amdgcn_s_setprio(1); _Pragma("unroll") for (int m = 0; m < 4; ++m) _Pragma("unroll") for (int n = 0; n < 2; ++n) _Pragma("unroll") for (int k = 0; k < 2; ++k) \
;         acc[ai][bj][m][n] = __builtin_amdgcn_mfma_f32_16x16x32_bf16(Bt[n][k], At[m][k], acc[ai][bj][m][n], 0, 0, 0); __builtin_amdgcn_s_setprio(0); } while (0)
; #define PG8_WAIT_V(n) asm volatile("s_waitcnt vmcnt(" #n ")" ::: "memory")
; #define PG8_WAIT_L(n) asm volatile("s_waitcnt lgkmcnt(" #n ")" ::: "memory")
; #define PG8_BAR __builtin_amdgcn_s_barrier()
; #define PG8_SCHED __builtin_amdgcn_sched_barrier(0)
; template <class Epi, class Sched, bool ALIGN_EPI = false, bool SP2 = false>
; __device__ __forceinline__ void gemm_phase(PG8_LAS unsigned char* lds, const Gemm g, const Sched& S, const Epi& E) {
;     ...
;             PG8_WAIT_V(8); PG8_WAIT_L(0); PG8_BAR; PG8_MMA(0, 0, At, B0); PG8_MMA(0, 1, At, B1); PG8_BAR; PG8_SCHED;
;             PG8_LDA(At, 1, 1); PG8_STAGE(PG8_SB(1, 0), b3, voffB); PG8_STAGE(PG8_SB(1, 1), b3 + hstep, voffB); PG8_STAGE(PG8_SA(1, 0), a3, voffA);
;             PG8_WAIT_V(8); PG8_WAIT_L(0); PG8_BAR; PG8_MMA(1, 0, At, B0); PG8_MMA(1, 1, At, B1); PG8_BAR; PG8_SCHED;
	s_waitcnt lgkmcnt(0)
	v_mfma_f32_16x16x32_bf16 v[126:129], v[146:149], v[198:201], v[126:129]
	v_mfma_f32_16x16x32_bf16 v[126:129], v[150:153], v[202:205], v[126:129]
	v_mfma_f32_16x16x32_bf16 v[110:113], v[150:153], v[210:213], v[110:113]
	v_mfma_f32_16x16x32_bf16 v[110:113], v[146:149], v[206:209], v[110:113]
	v_mfma_f32_16x16x32_bf16 v[94:97], v[146:149], v[214:217], v[94:97]
	v_mfma_f32_16x16x32_bf16 v[94:97], v[150:153], v[218:221], v[94:97]
	v_mfma_f32_16x16x32_bf16 v[78:81], v[150:153], v[226:229], v[78:81]
	v_mfma_f32_16x16x32_bf16 v[78:81], v[146:149], v[222:225], v[78:81]
	v_mfma_f32_16x16x32_bf16 v[74:77], v[154:157], v[222:225], v[74:77]
	v_mfma_f32_16x16x32_bf16 v[74:77], v[168:171], v[226:229], v[74:77]
	v_mfma_f32_16x16x32_bf16 v[90:93], v[168:171], v[218:221], v[90:93]
	v_mfma_f32_16x16x32_bf16 v[90:93], v[154:157], v[214:217], v[90:93]
	v_mfma_f32_16x16x32_bf16 v[106:109], v[154:157], v[206:209], v[106:109]
	v_mfma_f32_16x16x32_bf16 v[106:109], v[168:171], v[210:213], v[106:109]
	v_mfma_f32_16x16x32_bf16 v[122:125], v[168:171], v[202:205], v[122:125]
	v_mfma_f32_16x16x32_bf16 v[122:125], v[154:157], v[198:201], v[122:125]
	v_mfma_f32_16x16x32_bf16 v[118:121], v[172:175], v[198:201], v[118:121]
	v_mfma_f32_16x16x32_bf16 v[118:121], v[180:183], v[202:205], v[118:121]
	v_mfma_f32_16x16x32_bf16 v[102:105], v[180:183], v[210:213], v[102:105]
	v_mfma_f32_16x16x32_bf16 v[102:105], v[172:175], v[206:209], v[102:105]
	v_mfma_f32_16x16x32_bf16 v[86:89], v[172:175], v[214:217], v[86:89]
	v_mfma_f32_16x16x32_bf16 v[86:89], v[180:183], v[218:221], v[86:89]
	v_mfma_f32_16x16x32_bf16 v[70:73], v[180:183], v[226:229], v[70:73]
	v_mfma_f32_16x16x32_bf16 v[70:73], v[172:175], v[222:225], v[70:73]
	v_mfma_f32_16x16x32_bf16 v[66:69], v[184:187], v[222:225], v[66:69]
	v_mfma_f32_16x16x32_bf16 v[66:69], v[188:191], v[226:229], v[66:69]
	v_mfma_f32_16x16x32_bf16 v[82:85], v[188:191], v[218:221], v[82:85]
	v_mfma_f32_16x16x32_bf16 v[82:85], v[184:187], v[214:217], v[82:85]
	v_mfma_f32_16x16x32_bf16 v[98:101], v[184:187], v[206:209], v[98:101]
	v_mfma_f32_16x16x32_bf16 v[98:101], v[188:191], v[210:213], v[98:101]
	v_mfma_f32_16x16x32_bf16 v[114:117], v[188:191], v[202:205], v[114:117]
	v_mfma_f32_16x16x32_bf16 v[114:117], v[184:187], v[198:201], v[114:117]
	s_barrier
	s_add_u32 s62, s76, 0x8000
	s_addc_u32 s63, s77, 0
	s_add_i32 s59, s59, s3
	s_mov_b32 m0, s59
	ds_read_b128 v[198:201], v164 offset:49152
	ds_read_b128 v[202:205], v164 offset:50176
	ds_read_b128 v[206:209], v164 offset:51200
	ds_read_b128 v[210:213], v164 offset:52224
	ds_read_b128 v[214:217], v164 offset:53248
	ds_read_b128 v[218:221], v164 offset:54272
	ds_read_b128 v[222:225], v164 offset:55296
	ds_read_b128 v[226:229], v164 offset:56320
	global_load_lds_dwordx4 v132, s[62:63]
	s_add_i32 m0, s59, 0x2000
	v_lshl_add_u64 v[158:159], s[62:63], 0, v[136:137]
	s_add_u32 s62, s76, 0xc000
	s_addc_u32 s63, s77, 0
	s_add_i32 s59, s64, s3
	global_load_lds_dwordx4 v[158:159], off
	s_mov_b32 m0, s59
	s_nop 0
	global_load_lds_dwordx4 v132, s[62:63]
	s_add_i32 m0, s59, 0x2000
	s_nop 0
	global_load_lds_dwordx4 v136, s[62:63]
	s_waitcnt vmcnt(6)
	s_waitcnt lgkmcnt(0)
	s_barrier
	s_waitcnt lgkmcnt(0)
	v_mfma_f32_16x16x32_bf16 v[62:65], v[146:149], v[198:201], v[62:65]
	v_mfma_f32_16x16x32_bf16 v[62:65], v[150:153], v[202:205], v[62:65]
	v_mfma_f32_16x16x32_bf16 v[46:49], v[150:153], v[210:213], v[46:49]
	v_mfma_f32_16x16x32_bf16 v[46:49], v[146:149], v[206:209], v[46:49]
	v_mfma_f32_16x16x32_bf16 v[30:33], v[146:149], v[214:217], v[30:33]
	v_mfma_f32_16x16x32_bf16 v[30:33], v[150:153], v[218:221], v[30:33]
	v_mfma_f32_16x16x32_bf16 v[14:17], v[150:153], v[226:229], v[14:17]
	v_mfma_f32_16x16x32_bf16 v[14:17], v[146:149], v[222:225], v[14:17]
	v_mfma_f32_16x16x32_bf16 v[10:13], v[154:157], v[222:225], v[10:13]
	v_mfma_f32_16x16x32_bf16 v[10:13], v[168:171], v[226:229], v[10:13]
	v_mfma_f32_16x16x32_bf16 v[26:29], v[168:171], v[218:221], v[26:29]
	v_mfma_f32_16x16x32_bf16 v[26:29], v[154:157], v[214:217], v[26:29]
	v_mfma_f32_16x16x32_bf16 v[42:45], v[154:157], v[206:209], v[42:45]
	v_mfma_f32_16x16x32_bf16 v[42:45], v[168:171], v[210:213], v[42:45]
	v_mfma_f32_16x16x32_bf16 v[58:61], v[168:171], v[202:205], v[58:61]
	v_mfma_f32_16x16x32_bf16 v[58:61], v[154:157], v[198:201], v[58:61]
	v_mfma_f32_16x16x32_bf16 v[54:57], v[172:175], v[198:201], v[54:57]
	v_mfma_f32_16x16x32_bf16 v[54:57], v[180:183], v[202:205], v[54:57]
	v_mfma_f32_16x16x32_bf16 v[38:41], v[180:183], v[210:213], v[38:41]
	v_mfma_f32_16x16x32_bf16 v[38:41], v[172:175], v[206:209], v[38:41]
	v_mfma_f32_16x16x32_bf16 v[22:25], v[172:175], v[214:217], v[22:25]
	v_mfma_f32_16x16x32_bf16 v[22:25], v[180:183], v[218:221], v[22:25]
	v_mfma_f32_16x16x32_bf16 v[6:9], v[180:183], v[226:229], v[6:9]
	v_mfma_f32_16x16x32_bf16 v[6:9], v[172:175], v[222:225], v[6:9]
	v_mfma_f32_16x16x32_bf16 v[2:5], v[184:187], v[222:225], v[2:5]
	v_mfma_f32_16x16x32_bf16 v[2:5], v[188:191], v[226:229], v[2:5]
	v_mfma_f32_16x16x32_bf16 v[18:21], v[188:191], v[218:221], v[18:21]
	v_mfma_f32_16x16x32_bf16 v[18:21], v[184:187], v[214:217], v[18:21]
	v_mfma_f32_16x16x32_bf16 v[34:37], v[184:187], v[206:209], v[34:37]
	v_mfma_f32_16x16x32_bf16 v[34:37], v[188:191], v[210:213], v[34:37]
	v_mfma_f32_16x16x32_bf16 v[50:53], v[188:191], v[202:205], v[50:53]
	v_mfma_f32_16x16x32_bf16 v[50:53], v[184:187], v[198:201], v[50:53]
	s_barrier
	s_add_i32 s58, s58, 2
	s_add_u32 s72, s72, 0x10000
	s_addc_u32 s73, s73, 0
	s_add_u32 s33, s33, 0x10000
	s_addc_u32 s56, s56, 0
	s_cmp_gt_u32 s58, 61

; #define PG8_STAGE(bufoff, gbase, voff) do { _Pragma("unroll") for (int _i = 0; _i < 2; ++_i) \
;         __builtin_amdgcn_global_load_lds((const unsigned*)((const char*)(gbase) + (voff)[_i]), (PG8_LAS unsigned*)(lds + (bufoff) + ldsw + _i * 8192), 16, 0, 0); } while (0)
; #define PG8_LDA(dst, b, h) do { _Pragma("unroll") for (int m = 0; m < 4; ++m) _Pragma("unroll") for (int k = 0; k < 2; ++k) dst[m][k] = *(const PG8_LAS bf16x8*)(lds + PG8_SA(b, h) + aoff + m * 2048 + k * 1024); } while (0)
; #define PG8_LDB(dst, b, h) do { _Pragma("unroll") for (int n = 0; n < 2; ++n) _Pragma("unroll") for (int k = 0; k < 2; ++k) dst[n][k] = *(const PG8_LAS bf16x8*)(lds + PG8_SB(b, h) + boff + n * 2048 + k * 1024); } while (0)
; #define PG8_MMA(ai, bj, At, Bt) do { __builtin_amdgcn_s_setprio(1); _Pragma("unroll") for (int m = 0; m < 4; ++m) _Pragma("unroll") for (int n = 0; n < 2; ++n) _Pragma("unroll") for (int k = 0; k < 2; ++k) \
;         acc[ai][bj][m][n] = __builtin_amdgcn_mfma_f32_16x16x32_bf16(Bt[n][k], At[m][k], acc[ai][bj][m][n], 0, 0, 0); __builtin_amdgcn_s_setprio(0); } while (0)
; #define PG8_WAIT_V(n) asm volatile("s_waitcnt vmcnt(" #n ")" ::: "memory")
; #define PG8_WAIT_L(n) asm volatile("s_waitcnt lgkmcnt(" #n ")" ::: "memory")
; template <class Epi, class Sched, bool ALIGN_EPI = false, bool SP2 = false>
; __device__ __forceinline__ void gemm_phase(PG8_LAS unsigned char* lds, const Gemm g, const Sched& S, const Epi& E) {
;     ...
;         for (; t < tend; t += 2) {
;             const bool last = (t == nt - 2);
;             const char* a1 = cA + (size_t)(t + 1) * kstep;
;             const char* a2 = last ? nA : cA + (size_t)(t + 2) * kstep; const char* b2 = last ? nB : cB + (size_t)(t + 2) * kstep;
;             const char* a3 = a2 + kstep; const char* b3 = b2 + kstep;
;             if (last && has_next) S.a_ready(nxt);
;             if constexpr (SP2) {
;             PG8_LDB(B0, 0, 0); PG8_LDB(B1, 0, 1); PG8_SCHED; PG8_LDA(At, 0, 0); PG8_STAGE(PG8_SA(1, 1), a1 + hstep, voffA);
;             PG8_WAIT_V(8); PG8_WAIT_L(0); PG8_BAR; PG8_MMA(0, 0, At, B0); PG8_MMA(0, 1, At, B1); PG8_BAR; PG8_SCHED;
;             PG8_LDA(At, 0, 1); PG8_STAGE(PG8_SB(0, 0), b2, voffB); PG8_STAGE(PG8_SB(0, 1), b2 + hstep, voffB); PG8_STAGE(PG8_SA(0, 0), a2, voffA);
;             PG8_WAIT_V(8); PG8_WAIT_L(0); PG8_BAR; PG8_MMA(1, 0, At, B0); PG8_MMA(1, 1, At, B1); PG8_BAR; PG8_SCHED;
.LBB0_681:
	v_lshl_add_u64 v[130:131], s[50:51], 0, v[144:145]
	v_lshl_add_u64 v[132:133], s[50:51], 0, v[146:147]
	v_lshl_add_u64 v[156:157], s[48:49], 0, v[148:149]
	v_lshl_add_u64 v[158:159], s[48:49], 0, v[150:151]
	s_mov_b32 s27, -2
	s_mov_b64 s[44:45], 0
	s_nop 3
	ds_read_b128 v[166:169], v163
	ds_read_b128 v[170:173], v163 offset:1024
	ds_read_b128 v[174:177], v163 offset:2048
	ds_read_b128 v[180:183], v163 offset:3072
	ds_read_b128 v[184:187], v164
	ds_read_b128 v[188:191], v164 offset:1024
	ds_read_b128 v[198:201], v164 offset:2048
	ds_read_b128 v[202:205], v164 offset:3072
	v_lshl_add_u64 v[242:243], v[130:131], 0, s[44:45]
	s_add_i32 s83, s29, 0xc000
	v_lshl_add_u64 v[238:239], v[242:243], 0, s[10:11]
	s_mov_b32 m0, s83
	v_lshl_add_u64 v[244:245], v[132:133], 0, s[44:45]
	s_add_i32 s84, s29, 0xe000
	ds_read_b128 v[206:209], v165
	ds_read_b128 v[210:213], v165 offset:1024
	ds_read_b128 v[214:217], v165 offset:2048
	ds_read_b128 v[218:221], v165 offset:3072
	ds_read_b128 v[222:225], v165 offset:4096
	ds_read_b128 v[226:229], v165 offset:5120
	ds_read_b128 v[230:233], v165 offset:6144
	ds_read_b128 v[234:237], v165 offset:7168
	global_load_lds_dwordx4 v[238:239], off
	v_lshl_add_u64 v[238:239], v[244:245], 0, s[10:11]
	s_mov_b32 m0, s84
	s_nop 0
	global_load_lds_dwordx4 v[238:239], off
	s_waitcnt vmcnt(8)
	s_waitcnt lgkmcnt(0)
	s_barrier
	s_waitcnt lgkmcnt(0)
	v_mfma_f32_16x16x32_bf16 v[14:17], v[166:169], v[206:209], 0
	v_mfma_f32_16x16x32_bf16 v[14:17], v[170:173], v[210:213], v[14:17]
	v_mfma_f32_16x16x32_bf16 v[38:41], v[170:173], v[218:221], 0
	v_mfma_f32_16x16x32_bf16 v[38:41], v[166:169], v[214:217], v[38:41]
	v_mfma_f32_16x16x32_bf16 v[70:73], v[166:169], v[222:225], 0
	v_mfma_f32_16x16x32_bf16 v[70:73], v[170:173], v[226:229], v[70:73]
	v_mfma_f32_16x16x32_bf16 v[94:97], v[170:173], v[234:237], 0
	v_mfma_f32_16x16x32_bf16 v[94:97], v[166:169], v[230:233], v[94:97]
	v_mfma_f32_16x16x32_bf16 v[90:93], v[174:177], v[230:233], 0
	v_mfma_f32_16x16x32_bf16 v[90:93], v[180:183], v[234:237], v[90:93]
	v_mfma_f32_16x16x32_bf16 v[66:69], v[180:183], v[226:229], 0
	v_mfma_f32_16x16x32_bf16 v[66:69], v[174:177], v[222:225], v[66:69]
	v_mfma_f32_16x16x32_bf16 v[34:37], v[174:177], v[214:217], 0
	v_mfma_f32_16x16x32_bf16 v[34:37], v[180:183], v[218:221], v[34:37]
	v_mfma_f32_16x16x32_bf16 v[10:13], v[180:183], v[210:213], 0
	v_mfma_f32_16x16x32_bf16 v[10:13], v[174:177], v[206:209], v[10:13]
	v_mfma_f32_16x16x32_bf16 v[30:33], v[184:187], v[206:209], 0
	v_mfma_f32_16x16x32_bf16 v[30:33], v[188:191], v[210:213], v[30:33]
	v_mfma_f32_16x16x32_bf16 v[54:57], v[188:191], v[218:221], 0
	v_mfma_f32_16x16x32_bf16 v[54:57], v[184:187], v[214:217], v[54:57]
	v_mfma_f32_16x16x32_bf16 v[86:89], v[184:187], v[222:225], 0
	v_mfma_f32_16x16x32_bf16 v[86:89], v[188:191], v[226:229], v[86:89]
	v_mfma_f32_16x16x32_bf16 v[110:113], v[188:191], v[234:237], 0
	v_mfma_f32_16x16x32_bf16 v[110:113], v[184:187], v[230:233], v[110:113]
	v_mfma_f32_16x16x32_bf16 v[106:109], v[198:201], v[230:233], 0
	v_mfma_f32_16x16x32_bf16 v[106:109], v[202:205], v[234:237], v[106:109]
	v_mfma_f32_16x16x32_bf16 v[82:85], v[202:205], v[226:229], 0
	v_mfma_f32_16x16x32_bf16 v[82:85], v[198:201], v[222:225], v[82:85]
	v_mfma_f32_16x16x32_bf16 v[50:53], v[198:201], v[214:217], 0
	v_mfma_f32_16x16x32_bf16 v[50:53], v[202:205], v[218:221], v[50:53]
	v_mfma_f32_16x16x32_bf16 v[26:29], v[202:205], v[210:213], 0
	v_mfma_f32_16x16x32_bf16 v[26:29], v[198:201], v[206:209], v[26:29]
	s_barrier
	v_lshl_add_u64 v[246:247], v[156:157], 0, s[44:45]
	s_add_i32 s85, s80, s28
	v_lshl_add_u64 v[238:239], v[246:247], 0, s[14:15]
	s_mov_b32 m0, s85
	v_lshl_add_u64 v[248:249], v[158:159], 0, s[44:45]
	s_add_i32 s86, s85, 0x2000
	ds_read_b128 v[206:209], v165 offset:16384
	ds_read_b128 v[210:213], v165 offset:17408
	ds_read_b128 v[214:217], v165 offset:18432
	ds_read_b128 v[218:221], v165 offset:19456
	ds_read_b128 v[222:225], v165 offset:20480
	ds_read_b128 v[226:229], v165 offset:21504
	ds_read_b128 v[230:233], v165 offset:22528
	ds_read_b128 v[234:237], v165 offset:23552
	global_load_lds_dwordx4 v[238:239], off
	v_lshl_add_u64 v[238:239], v[248:249], 0, s[14:15]
	s_mov_b32 m0, s86
	s_add_i32 s87, s81, s28
	global_load_lds_dwordx4 v[238:239], off
	v_lshl_add_u64 v[238:239], v[246:247], 0, s[16:17]
	s_mov_b32 m0, s87
	s_add_i32 s88, s87, 0x2000
	global_load_lds_dwordx4 v[238:239], off
	v_lshl_add_u64 v[238:239], v[248:249], 0, s[16:17]
	s_mov_b32 m0, s88
	s_nop 0
	global_load_lds_dwordx4 v[238:239], off
	v_lshl_add_u64 v[238:239], v[242:243], 0, s[14:15]
	s_mov_b32 m0, s29
	s_nop 0
	global_load_lds_dwordx4 v[238:239], off
	v_lshl_add_u64 v[238:239], v[244:245], 0, s[14:15]
	s_mov_b32 m0, s30
	s_nop 0
	global_load_lds_dwordx4 v[238:239], off
	s_waitcnt vmcnt(8)
	s_waitcnt lgkmcnt(0)
	s_barrier
; #define PG8_STAGE(bufoff, gbase, voff) do { _Pragma("unroll") for (int _i = 0; _i < 2; ++_i) \
;         __builtin_amdgcn_global_load_lds((const unsigned*)((const char*)(gbase) + (voff)[_i]), (PG8_LAS unsigned*)(lds + (bufoff) + ldsw + _i * 8192), 16, 0, 0); } while (0)
; #define PG8_LDA(dst, b, h) do { _Pragma("unroll") for (int m = 0; m < 4; ++m) _Pragma("unroll") for (int k = 0; k < 2; ++k) dst[m][k] = *(const PG8_LAS bf16x8*)(lds + PG8_SA(b, h) + aoff + m * 2048 + k * 1024); } while (0)
; #define PG8_LDB(dst, b, h) do { _Pragma("unroll") for (int n = 0; n < 2; ++n) _Pragma("unroll") for (int k = 0; k < 2; ++k) dst[n][k] = *(const PG8_LAS bf16x8*)(lds + PG8_SB(b, h) + boff + n * 2048 + k * 1024); } while (0)
; #define PG8_MMA(ai, bj, At, Bt) do { __builtin_amdgcn_s_setprio(1); _Pragma("unroll") for (int m = 0; m < 4; ++m) _Pragma("unroll") for (int n = 0; n < 2; ++n) _Pragma("unroll") for (int k = 0; k < 2; ++k) \
;         acc[ai][bj][m][n] = __builtin_amdgcn_mfma_f32_16x16x32_bf16(Bt[n][k], At[m][k], acc[ai][bj][m][n], 0, 0, 0); __builtin_amdgcn_s_setprio(0); } while (0)
; #define PG8_WAIT_V(n) asm volatile("s_waitcnt vmcnt(" #n ")" ::: "memory")
; #define PG8_WAIT_L(n) asm volatile("s_waitcnt lgkmcnt(" #n ")" ::: "memory")
; #define PG8_BAR __builtin_amdgcn_s_barrier()
; #define PG8_SCHED __builtin_amdgcn_sched_barrier(0)
; template <class Epi, class Sched, bool ALIGN_EPI = false, bool SP2 = false>
; __device__ __forceinline__ void gemm_phase(PG8_LAS unsigned char* lds, const Gemm g, const Sched& S, const Epi& E) {
;     ...
;             PG8_WAIT_V(8); PG8_WAIT_L(0); PG8_BAR; PG8_MMA(1, 0, At, B0); PG8_MMA(1, 1, At, B1); PG8_BAR; PG8_SCHED;
;             PG8_LDB(B0, 1, 0); PG8_LDB(B1, 1, 1); PG8_SCHED; PG8_LDA(At, 1, 0); PG8_STAGE(PG8_SA(0, 1), a2 + hstep, voffA);
;             PG8_WAIT_V(8); PG8_WAIT_L(0); PG8_BAR; PG8_MMA(0, 0, At, B0); PG8_MMA(0, 1, At, B1); PG8_BAR; PG8_SCHED;
;             PG8_LDA(At, 1, 1); PG8_STAGE(PG8_SB(1, 0), b3, voffB); PG8_STAGE(PG8_SB(1, 1), b3 + hstep, voffB); PG8_STAGE(PG8_SA(1, 0), a3, voffA);
	s_waitcnt lgkmcnt(0)
	v_mfma_f32_16x16x32_bf16 v[126:129], v[166:169], v[206:209], 0
	v_mfma_f32_16x16x32_bf16 v[126:129], v[170:173], v[210:213], v[126:129]
	v_mfma_f32_16x16x32_bf16 v[102:105], v[170:173], v[218:221], 0
	v_mfma_f32_16x16x32_bf16 v[102:105], v[166:169], v[214:217], v[102:105]
	v_mfma_f32_16x16x32_bf16 v[62:65], v[166:169], v[222:225], 0
	v_mfma_f32_16x16x32_bf16 v[62:65], v[170:173], v[226:229], v[62:65]
	v_mfma_f32_16x16x32_bf16 v[22:25], v[170:173], v[234:237], 0
	v_mfma_f32_16x16x32_bf16 v[22:25], v[166:169], v[230:233], v[22:25]
	v_mfma_f32_16x16x32_bf16 v[18:21], v[174:177], v[230:233], 0
	v_mfma_f32_16x16x32_bf16 v[18:21], v[180:183], v[234:237], v[18:21]
	v_mfma_f32_16x16x32_bf16 v[58:61], v[180:183], v[226:229], 0
	v_mfma_f32_16x16x32_bf16 v[58:61], v[174:177], v[222:225], v[58:61]
	v_mfma_f32_16x16x32_bf16 v[98:101], v[174:177], v[214:217], 0
	v_mfma_f32_16x16x32_bf16 v[98:101], v[180:183], v[218:221], v[98:101]
	v_mfma_f32_16x16x32_bf16 v[122:125], v[180:183], v[210:213], 0
	v_mfma_f32_16x16x32_bf16 v[122:125], v[174:177], v[206:209], v[122:125]
	v_mfma_f32_16x16x32_bf16 v[118:121], v[184:187], v[206:209], 0
	v_mfma_f32_16x16x32_bf16 v[118:121], v[188:191], v[210:213], v[118:121]
	v_mfma_f32_16x16x32_bf16 v[78:81], v[188:191], v[218:221], 0
	v_mfma_f32_16x16x32_bf16 v[78:81], v[184:187], v[214:217], v[78:81]
	v_mfma_f32_16x16x32_bf16 v[46:49], v[184:187], v[222:225], 0
	v_mfma_f32_16x16x32_bf16 v[46:49], v[188:191], v[226:229], v[46:49]
	v_mfma_f32_16x16x32_bf16 v[6:9], v[188:191], v[234:237], 0
	v_mfma_f32_16x16x32_bf16 v[6:9], v[184:187], v[230:233], v[6:9]
	v_mfma_f32_16x16x32_bf16 v[2:5], v[198:201], v[230:233], 0
	v_mfma_f32_16x16x32_bf16 v[2:5], v[202:205], v[234:237], v[2:5]
	v_mfma_f32_16x16x32_bf16 v[42:45], v[202:205], v[226:229], 0
	v_mfma_f32_16x16x32_bf16 v[42:45], v[198:201], v[222:225], v[42:45]
	v_mfma_f32_16x16x32_bf16 v[74:77], v[198:201], v[214:217], 0
	v_mfma_f32_16x16x32_bf16 v[74:77], v[202:205], v[218:221], v[74:77]
	v_mfma_f32_16x16x32_bf16 v[114:117], v[202:205], v[210:213], 0
	v_mfma_f32_16x16x32_bf16 v[114:117], v[198:201], v[206:209], v[114:117]
	s_barrier
	s_add_i32 s89, 0, 0x18000
	s_add_i32 s91, 0, 0x1c000
	v_add_u32_e32 v142, s89, v161
	v_add_u32_e32 v167, s91, v161
	ds_read_b128 v[168:171], v142
	ds_read_b128 v[172:175], v142 offset:1024
	ds_read_b128 v[180:183], v142 offset:2048
	ds_read_b128 v[184:187], v142 offset:3072
	ds_read_b128 v[188:191], v167
	ds_read_b128 v[198:201], v167 offset:1024
	ds_read_b128 v[202:205], v167 offset:2048
	ds_read_b128 v[206:209], v167 offset:3072
	s_mov_b32 m0, s31
	v_lshl_add_u64 v[176:177], v[242:243], 0, s[16:17]
	ds_read_b128 v[210:213], v165 offset:32768
	ds_read_b128 v[214:217], v165 offset:33792
	ds_read_b128 v[218:221], v165 offset:34816
	ds_read_b128 v[222:225], v165 offset:35840
	ds_read_b128 v[226:229], v165 offset:36864
	ds_read_b128 v[230:233], v165 offset:37888
	ds_read_b128 v[234:237], v165 offset:38912
	ds_read_b128 v[238:241], v165 offset:39936
	global_load_lds_dwordx4 v[176:177], off
	v_lshl_add_u64 v[176:177], v[244:245], 0, s[16:17]
	s_mov_b32 m0, s35
	s_nop 0
	global_load_lds_dwordx4 v[176:177], off
	s_waitcnt vmcnt(8)
	s_waitcnt lgkmcnt(0)
	s_barrier
	s_waitcnt lgkmcnt(0)
	v_mfma_f32_16x16x32_bf16 v[14:17], v[168:171], v[210:213], v[14:17]
	v_mfma_f32_16x16x32_bf16 v[14:17], v[172:175], v[214:217], v[14:17]
	v_mfma_f32_16x16x32_bf16 v[38:41], v[172:175], v[222:225], v[38:41]
	v_mfma_f32_16x16x32_bf16 v[38:41], v[168:171], v[218:221], v[38:41]
	v_mfma_f32_16x16x32_bf16 v[70:73], v[168:171], v[226:229], v[70:73]
	v_mfma_f32_16x16x32_bf16 v[70:73], v[172:175], v[230:233], v[70:73]
	v_mfma_f32_16x16x32_bf16 v[94:97], v[172:175], v[238:241], v[94:97]
	v_mfma_f32_16x16x32_bf16 v[94:97], v[168:171], v[234:237], v[94:97]
	v_mfma_f32_16x16x32_bf16 v[90:93], v[180:183], v[234:237], v[90:93]
	v_mfma_f32_16x16x32_bf16 v[90:93], v[184:187], v[238:241], v[90:93]
	v_mfma_f32_16x16x32_bf16 v[66:69], v[184:187], v[230:233], v[66:69]
	v_mfma_f32_16x16x32_bf16 v[66:69], v[180:183], v[226:229], v[66:69]
	v_mfma_f32_16x16x32_bf16 v[34:37], v[180:183], v[218:221], v[34:37]
	v_mfma_f32_16x16x32_bf16 v[34:37], v[184:187], v[222:225], v[34:37]
	v_mfma_f32_16x16x32_bf16 v[10:13], v[184:187], v[214:217], v[10:13]
	v_mfma_f32_16x16x32_bf16 v[10:13], v[180:183], v[210:213], v[10:13]
	v_mfma_f32_16x16x32_bf16 v[30:33], v[188:191], v[210:213], v[30:33]
	v_mfma_f32_16x16x32_bf16 v[30:33], v[198:201], v[214:217], v[30:33]
	v_mfma_f32_16x16x32_bf16 v[54:57], v[198:201], v[222:225], v[54:57]
	v_mfma_f32_16x16x32_bf16 v[54:57], v[188:191], v[218:221], v[54:57]
	v_mfma_f32_16x16x32_bf16 v[86:89], v[188:191], v[226:229], v[86:89]
	v_mfma_f32_16x16x32_bf16 v[86:89], v[198:201], v[230:233], v[86:89]
	v_mfma_f32_16x16x32_bf16 v[110:113], v[198:201], v[238:241], v[110:113]
	v_mfma_f32_16x16x32_bf16 v[110:113], v[188:191], v[234:237], v[110:113]
	v_mfma_f32_16x16x32_bf16 v[106:109], v[202:205], v[234:237], v[106:109]
	v_mfma_f32_16x16x32_bf16 v[106:109], v[206:209], v[238:241], v[106:109]
	v_mfma_f32_16x16x32_bf16 v[82:85], v[206:209], v[230:233], v[82:85]
	v_mfma_f32_16x16x32_bf16 v[82:85], v[202:205], v[226:229], v[82:85]
	v_mfma_f32_16x16x32_bf16 v[50:53], v[202:205], v[218:221], v[50:53]
	v_mfma_f32_16x16x32_bf16 v[50:53], v[206:209], v[222:225], v[50:53]
	v_mfma_f32_16x16x32_bf16 v[26:29], v[206:209], v[214:217], v[26:29]
	v_mfma_f32_16x16x32_bf16 v[26:29], v[202:205], v[210:213], v[26:29]
	s_barrier
; #define PG8_STAGE(bufoff, gbase, voff) do { _Pragma("unroll") for (int _i = 0; _i < 2; ++_i) \
;         __builtin_amdgcn_global_load_lds((const unsigned*)((const char*)(gbase) + (voff)[_i]), (PG8_LAS unsigned*)(lds + (bufoff) + ldsw + _i * 8192), 16, 0, 0); } while (0)
; #define PG8_LDA(dst, b, h) do { _Pragma("unroll") for (int m = 0; m < 4; ++m) _Pragma("unroll") for (int k = 0; k < 2; ++k) dst[m][k] = *(const PG8_LAS bf16x8*)(lds + PG8_SA(b, h) + aoff + m * 2048 + k * 1024); } while (0)
; #define PG8_MMA(ai, bj, At, Bt) do { __builtin_amdgcn_s_setprio(1); _Pragma("unroll") for (int m = 0; m < 4; ++m) _Pragma("unroll") for (int n = 0; n < 2; ++n) _Pragma("unroll") for (int k = 0; k < 2; ++k) \
;         acc[ai][bj][m][n] = __builtin_amdgcn_mfma_f32_16x16x32_bf16(Bt[n][k], At[m][k], acc[ai][bj][m][n], 0, 0, 0); __builtin_amdgcn_s_setprio(0); } while (0)
; #define PG8_WAIT_V(n) asm volatile("s_waitcnt vmcnt(" #n ")" ::: "memory")
; #define PG8_WAIT_L(n) asm volatile("s_waitcnt lgkmcnt(" #n ")" ::: "memory")
; #define PG8_BAR __builtin_amdgcn_s_barrier()
; #define PG8_SCHED __builtin_amdgcn_sched_barrier(0)
; template <class Epi, class Sched, bool ALIGN_EPI = false, bool SP2 = false>
; __device__ __forceinline__ void gemm_phase(PG8_LAS unsigned char* lds, const Gemm g, const Sched& S, const Epi& E) {
;     ...
;             PG8_LDA(At, 1, 1); PG8_STAGE(PG8_SB(1, 0), b3, voffB); PG8_STAGE(PG8_SB(1, 1), b3 + hstep, voffB); PG8_STAGE(PG8_SA(1, 0), a3, voffA);
;             PG8_WAIT_V(8); PG8_WAIT_L(0); PG8_BAR; PG8_MMA(1, 0, At, B0); PG8_MMA(1, 1, At, B1); PG8_BAR; PG8_SCHED;
	s_add_i32 s89, s89, s28
	v_lshl_add_u64 v[176:177], v[246:247], 0, s[22:23]
	s_mov_b32 m0, s89
	s_add_i32 s90, s89, 0x2000
	ds_read_b128 v[210:213], v165 offset:49152
	ds_read_b128 v[214:217], v165 offset:50176
	ds_read_b128 v[218:221], v165 offset:51200
	ds_read_b128 v[222:225], v165 offset:52224
	ds_read_b128 v[226:229], v165 offset:53248
	ds_read_b128 v[230:233], v165 offset:54272
	ds_read_b128 v[234:237], v165 offset:55296
	ds_read_b128 v[238:241], v165 offset:56320
	global_load_lds_dwordx4 v[176:177], off
	v_lshl_add_u64 v[176:177], v[248:249], 0, s[22:23]
	s_mov_b32 m0, s90
	s_add_i32 s91, s91, s28
	global_load_lds_dwordx4 v[176:177], off
	v_lshl_add_u64 v[176:177], v[246:247], 0, s[36:37]
	s_mov_b32 m0, s91
	s_add_i32 s92, s91, 0x2000
	global_load_lds_dwordx4 v[176:177], off
	v_lshl_add_u64 v[176:177], v[248:249], 0, s[36:37]
	s_mov_b32 m0, s92
	s_nop 0
	global_load_lds_dwordx4 v[176:177], off
	v_lshl_add_u64 v[176:177], v[242:243], 0, s[22:23]
	s_mov_b32 m0, s75
	s_nop 0
	global_load_lds_dwordx4 v[176:177], off
	v_lshl_add_u64 v[176:177], v[244:245], 0, s[22:23]
	s_mov_b32 m0, s76
	s_nop 0
	global_load_lds_dwordx4 v[176:177], off
	s_waitcnt vmcnt(8)
	s_waitcnt lgkmcnt(0)
	s_barrier
	s_waitcnt lgkmcnt(0)
	v_mfma_f32_16x16x32_bf16 v[126:129], v[168:171], v[210:213], v[126:129]
	v_mfma_f32_16x16x32_bf16 v[126:129], v[172:175], v[214:217], v[126:129]
	v_mfma_f32_16x16x32_bf16 v[102:105], v[172:175], v[222:225], v[102:105]
	v_mfma_f32_16x16x32_bf16 v[102:105], v[168:171], v[218:221], v[102:105]
	v_mfma_f32_16x16x32_bf16 v[62:65], v[168:171], v[226:229], v[62:65]
	v_mfma_f32_16x16x32_bf16 v[62:65], v[172:175], v[230:233], v[62:65]
	v_mfma_f32_16x16x32_bf16 v[22:25], v[172:175], v[238:241], v[22:25]
	v_mfma_f32_16x16x32_bf16 v[22:25], v[168:171], v[234:237], v[22:25]
	v_mfma_f32_16x16x32_bf16 v[18:21], v[180:183], v[234:237], v[18:21]
	v_mfma_f32_16x16x32_bf16 v[18:21], v[184:187], v[238:241], v[18:21]
	v_mfma_f32_16x16x32_bf16 v[58:61], v[184:187], v[230:233], v[58:61]
	v_mfma_f32_16x16x32_bf16 v[58:61], v[180:183], v[226:229], v[58:61]
	v_mfma_f32_16x16x32_bf16 v[98:101], v[180:183], v[218:221], v[98:101]
	v_mfma_f32_16x16x32_bf16 v[98:101], v[184:187], v[222:225], v[98:101]
	v_mfma_f32_16x16x32_bf16 v[122:125], v[184:187], v[214:217], v[122:125]
	v_mfma_f32_16x16x32_bf16 v[122:125], v[180:183], v[210:213], v[122:125]
	v_mfma_f32_16x16x32_bf16 v[118:121], v[188:191], v[210:213], v[118:121]
	v_mfma_f32_16x16x32_bf16 v[118:121], v[198:201], v[214:217], v[118:121]
	v_mfma_f32_16x16x32_bf16 v[78:81], v[198:201], v[222:225], v[78:81]
	v_mfma_f32_16x16x32_bf16 v[78:81], v[188:191], v[218:221], v[78:81]
	v_mfma_f32_16x16x32_bf16 v[46:49], v[188:191], v[226:229], v[46:49]
	v_mfma_f32_16x16x32_bf16 v[46:49], v[198:201], v[230:233], v[46:49]
	v_mfma_f32_16x16x32_bf16 v[6:9], v[198:201], v[238:241], v[6:9]
	v_mfma_f32_16x16x32_bf16 v[6:9], v[188:191], v[234:237], v[6:9]
	v_mfma_f32_16x16x32_bf16 v[2:5], v[202:205], v[234:237], v[2:5]
	v_mfma_f32_16x16x32_bf16 v[2:5], v[206:209], v[238:241], v[2:5]
	v_mfma_f32_16x16x32_bf16 v[42:45], v[206:209], v[230:233], v[42:45]
	v_mfma_f32_16x16x32_bf16 v[42:45], v[202:205], v[226:229], v[42:45]
	v_mfma_f32_16x16x32_bf16 v[74:77], v[202:205], v[218:221], v[74:77]
	v_mfma_f32_16x16x32_bf16 v[74:77], v[206:209], v[222:225], v[74:77]
	v_mfma_f32_16x16x32_bf16 v[114:117], v[206:209], v[214:217], v[114:117]
	v_mfma_f32_16x16x32_bf16 v[114:117], v[202:205], v[210:213], v[114:117]
	s_barrier
	s_add_i32 s27, s27, 2
	s_add_u32 s44, s44, 0x10000
	s_addc_u32 s45, s45, 0
	s_cmp_lt_u32 s27, 30

;     __device__ __forceinline__ bool next(int i, Unit& u) const { if (i >= 2) return false; const int xcd = c & 7, off = c >> 3; u.pm = 16 * i + 4 * (xcd >> 1) + (off & 3); u.pn = 8 * (xcd & 1) + (off >> 2); return true; }
; #define PG8_STAGE(bufoff, gbase, voff) do { _Pragma("unroll") for (int _i = 0; _i < 2; ++_i) \
;         __builtin_amdgcn_global_load_lds((const unsigned*)((const char*)(gbase) + (voff)[_i]), (PG8_LAS unsigned*)(lds + (bufoff) + ldsw + _i * 8192), 16, 0, 0); } while (0)
; #define PG8_LDA(dst, b, h) do { _Pragma("unroll") for (int m = 0; m < 4; ++m) _Pragma("unroll") for (int k = 0; k < 2; ++k) dst[m][k] = *(const PG8_LAS bf16x8*)(lds + PG8_SA(b, h) + aoff + m * 2048 + k * 1024); } while (0)
; #define PG8_WAIT_V(n) asm volatile("s_waitcnt vmcnt(" #n ")" ::: "memory")
; #define PG8_BAR __builtin_amdgcn_s_barrier()
; template <class Epi, class Sched, bool ALIGN_EPI = false, bool SP2 = false>
; __device__ __forceinline__ void gemm_phase(PG8_LAS unsigned char* lds, const Gemm g, const Sched& S, const Epi& E) {
;     ...
;         const bool has_next = S.next(ui + 1, nxt);
;         const char* nA = has_next ? (const char*)g.A + (size_t)nxt.pm * tstep : cA; const char* nB = has_next ? (const char*)g.Bt + (size_t)nxt.pn * tstep : cB;
;         constexpr int NSEG = Epi::HAS_MID ? 2 : 1; int t = 0;
; #pragma unroll
;         for (int seg = 0; seg < NSEG; ++seg) { const int tend = (seg + 1 < NSEG) ? (nt >> 1) : nt;
;         for (; t < tend; t += 2) {
;             const bool last = (t == nt - 2);
;             const char* a1 = cA + (size_t)(t + 1) * kstep;
;             const char* a2 = last ? nA : cA + (size_t)(t + 2) * kstep; const char* b2 = last ? nB : cB + (size_t)(t + 2) * kstep;
;             const char* a3 = a2 + kstep; const char* b3 = b2 + kstep;
;             if (last && has_next) S.a_ready(nxt);
;             if constexpr (SP2) {
;             PG8_LDB(B0, 0, 0); PG8_LDB(B1, 0, 1); PG8_SCHED; PG8_LDA(At, 0, 0); PG8_STAGE(PG8_SA(1, 1), a1 + hstep, voffA);
;             PG8_WAIT_V(8); PG8_WAIT_L(0); PG8_BAR; PG8_MMA(0, 0, At, B0); PG8_MMA(0, 1, At, B1); PG8_BAR; PG8_SCHED;
;             PG8_LDA(At, 0, 1); PG8_STAGE(PG8_SB(0, 0), b2, voffB); PG8_STAGE(PG8_SB(0, 1), b2 + hstep, voffB); PG8_STAGE(PG8_SA(0, 0), a2, voffA);
;             PG8_WAIT_V(8); PG8_WAIT_L(0); PG8_BAR; PG8_MMA(1, 0, At, B0); PG8_MMA(1, 1, At, B1); PG8_BAR; PG8_SCHED;
.LBB0_756:
	s_ashr_i32 s17, s16, 31
	s_lshl_b64 s[22:23], s[16:17], 21
	s_add_u32 s22, s66, s22
	s_addc_u32 s23, s67, s23
	s_and_b64 s[36:37], s[4:5], exec
	s_cselect_b32 s17, s23, s45
	s_cselect_b32 s39, s22, s44
	s_ashr_i32 s15, s14, 31
	s_lshl_b64 s[36:37], s[14:15], 21
	v_readlane_b32 s48, v255, 17
	v_readlane_b32 s49, v255, 18
	s_add_u32 s36, s48, s36
	s_addc_u32 s37, s49, s37
	s_and_b64 s[48:49], s[4:5], exec
	s_cselect_b32 s15, s37, s47
	s_cselect_b32 s41, s36, s46
	s_add_u32 s44, s44, 0xc000
	s_addc_u32 s45, s45, 0
	s_add_u32 s68, s46, 0x10000
	s_addc_u32 s69, s47, 0
	s_mov_b32 s70, -2
	s_waitcnt lgkmcnt(0)
	s_nop 3
	ds_read_b128 v[154:157], v149
	ds_read_b128 v[158:161], v149 offset:1024
	ds_read_b128 v[162:165], v149 offset:2048
	ds_read_b128 v[166:169], v149 offset:3072
	ds_read_b128 v[170:173], v150
	ds_read_b128 v[174:177], v150 offset:1024
	ds_read_b128 v[180:183], v150 offset:2048
	ds_read_b128 v[184:187], v150 offset:3072
	s_add_u32 s46, s44, 0x4000
	s_addc_u32 s47, s45, 0
	s_cmp_eq_u32 s70, 60
	s_cselect_b32 s50, s39, s46
	s_cselect_b32 s51, s17, s47
	s_cselect_b32 s48, s41, s68
	s_cselect_b32 s49, s15, s69
	s_add_u32 s46, s50, 0x8000
	s_addc_u32 s47, s51, 0
	s_sub_u32 s46, s44, 0x4000
	s_subb_u32 s47, s45, 0
	s_mov_b32 m0, s57
	s_nop 0
	global_load_lds_dwordx4 v130, s[46:47]
	s_mov_b32 m0, s58
	s_nop 0
	global_load_lds_dwordx4 v134, s[46:47]
	s_add_i32 m0, s26, 0xc000
	ds_read_b128 v[188:191], v151
	ds_read_b128 v[198:201], v151 offset:1024
	ds_read_b128 v[202:205], v151 offset:2048
	ds_read_b128 v[206:209], v151 offset:3072
	ds_read_b128 v[210:213], v151 offset:4096
	ds_read_b128 v[214:217], v151 offset:5120
	ds_read_b128 v[218:221], v151 offset:6144
	ds_read_b128 v[222:225], v151 offset:7168
	global_load_lds_dwordx4 v138, s[44:45]
	s_add_i32 m0, s26, 0xe000
	s_nop 0
	global_load_lds_dwordx4 v140, s[44:45]
	s_waitcnt vmcnt(8)
	s_waitcnt lgkmcnt(0)
	s_barrier
	s_waitcnt lgkmcnt(0)
	v_mfma_f32_16x16x32_bf16 v[126:129], v[154:157], v[188:191], 0
	v_mfma_f32_16x16x32_bf16 v[126:129], v[158:161], v[198:201], v[126:129]
	v_mfma_f32_16x16x32_bf16 v[110:113], v[158:161], v[206:209], 0
	v_mfma_f32_16x16x32_bf16 v[110:113], v[154:157], v[202:205], v[110:113]
	v_mfma_f32_16x16x32_bf16 v[94:97], v[154:157], v[210:213], 0
	v_mfma_f32_16x16x32_bf16 v[94:97], v[158:161], v[214:217], v[94:97]
	v_mfma_f32_16x16x32_bf16 v[78:81], v[158:161], v[222:225], 0
	v_mfma_f32_16x16x32_bf16 v[78:81], v[154:157], v[218:221], v[78:81]
	v_mfma_f32_16x16x32_bf16 v[74:77], v[162:165], v[218:221], 0
	v_mfma_f32_16x16x32_bf16 v[74:77], v[166:169], v[222:225], v[74:77]
	v_mfma_f32_16x16x32_bf16 v[90:93], v[166:169], v[214:217], 0
	v_mfma_f32_16x16x32_bf16 v[90:93], v[162:165], v[210:213], v[90:93]
	v_mfma_f32_16x16x32_bf16 v[106:109], v[162:165], v[202:205], 0
	v_mfma_f32_16x16x32_bf16 v[106:109], v[166:169], v[206:209], v[106:109]
	v_mfma_f32_16x16x32_bf16 v[122:125], v[166:169], v[198:201], 0
	v_mfma_f32_16x16x32_bf16 v[122:125], v[162:165], v[188:191], v[122:125]
	v_mfma_f32_16x16x32_bf16 v[118:121], v[170:173], v[188:191], 0
	v_mfma_f32_16x16x32_bf16 v[118:121], v[174:177], v[198:201], v[118:121]
	v_mfma_f32_16x16x32_bf16 v[102:105], v[174:177], v[206:209], 0
	v_mfma_f32_16x16x32_bf16 v[102:105], v[170:173], v[202:205], v[102:105]
	v_mfma_f32_16x16x32_bf16 v[86:89], v[170:173], v[210:213], 0
	v_mfma_f32_16x16x32_bf16 v[86:89], v[174:177], v[214:217], v[86:89]
	v_mfma_f32_16x16x32_bf16 v[70:73], v[174:177], v[222:225], 0
	v_mfma_f32_16x16x32_bf16 v[70:73], v[170:173], v[218:221], v[70:73]
	v_mfma_f32_16x16x32_bf16 v[66:69], v[180:183], v[218:221], 0
	v_mfma_f32_16x16x32_bf16 v[66:69], v[184:187], v[222:225], v[66:69]
	v_mfma_f32_16x16x32_bf16 v[82:85], v[184:187], v[214:217], 0
	v_mfma_f32_16x16x32_bf16 v[82:85], v[180:183], v[210:213], v[82:85]
	v_mfma_f32_16x16x32_bf16 v[98:101], v[180:183], v[202:205], 0
	v_mfma_f32_16x16x32_bf16 v[98:101], v[184:187], v[206:209], v[98:101]
	v_mfma_f32_16x16x32_bf16 v[114:117], v[184:187], v[198:201], 0
	v_mfma_f32_16x16x32_bf16 v[114:117], v[180:183], v[188:191], v[114:117]
	s_barrier
	s_add_i32 s71, s59, s3
	s_mov_b32 m0, s71
	ds_read_b128 v[188:191], v151 offset:16384
	ds_read_b128 v[198:201], v151 offset:17408
	ds_read_b128 v[202:205], v151 offset:18432
	ds_read_b128 v[206:209], v151 offset:19456
	ds_read_b128 v[210:213], v151 offset:20480
	ds_read_b128 v[214:217], v151 offset:21504
	ds_read_b128 v[218:221], v151 offset:22528
	ds_read_b128 v[222:225], v151 offset:23552
	global_load_lds_dwordx4 v132, s[48:49]
	s_add_i32 m0, s71, 0x2000
	s_add_u32 s72, s48, 0x4000
	s_addc_u32 s73, s49, 0
	s_add_i32 s71, s61, s3
	global_load_lds_dwordx4 v136, s[48:49]
	s_mov_b32 m0, s71
	s_nop 0
	global_load_lds_dwordx4 v132, s[72:73]
	s_add_i32 m0, s71, 0x2000
	s_nop 0
	global_load_lds_dwordx4 v136, s[72:73]
	s_waitcnt vmcnt(6)
	s_waitcnt lgkmcnt(0)
	s_barrier
; #define PG8_STAGE(bufoff, gbase, voff) do { _Pragma("unroll") for (int _i = 0; _i < 2; ++_i) \
;         __builtin_amdgcn_global_load_lds((const unsigned*)((const char*)(gbase) + (voff)[_i]), (PG8_LAS unsigned*)(lds + (bufoff) + ldsw + _i * 8192), 16, 0, 0); } while (0)
; #define PG8_LDA(dst, b, h) do { _Pragma("unroll") for (int m = 0; m < 4; ++m) _Pragma("unroll") for (int k = 0; k < 2; ++k) dst[m][k] = *(const PG8_LAS bf16x8*)(lds + PG8_SA(b, h) + aoff + m * 2048 + k * 1024); } while (0)
; #define PG8_LDB(dst, b, h) do { _Pragma("unroll") for (int n = 0; n < 2; ++n) _Pragma("unroll") for (int k = 0; k < 2; ++k) dst[n][k] = *(const PG8_LAS bf16x8*)(lds + PG8_SB(b, h) + boff + n * 2048 + k * 1024); } while (0)
; #define PG8_MMA(ai, bj, At, Bt) do { __builtin_amdgcn_s_setprio(1); _Pragma("unroll") for (int m = 0; m < 4; ++m) _Pragma("unroll") for (int n = 0; n < 2; ++n) _Pragma("unroll") for (int k = 0; k < 2; ++k) \
;         acc[ai][bj][m][n] = __builtin_amdgcn_mfma_f32_16x16x32_bf16(Bt[n][k], At[m][k], acc[ai][bj][m][n], 0, 0, 0); __builtin_amdgcn_s_setprio(0); } while (0)
; #define PG8_WAIT_V(n) asm volatile("s_waitcnt vmcnt(" #n ")" ::: "memory")
; #define PG8_WAIT_L(n) asm volatile("s_waitcnt lgkmcnt(" #n ")" ::: "memory")
; #define PG8_BAR __builtin_amdgcn_s_barrier()
; #define PG8_SCHED __builtin_amdgcn_sched_barrier(0)
; template <class Epi, class Sched, bool ALIGN_EPI = false, bool SP2 = false>
; __device__ __forceinline__ void gemm_phase(PG8_LAS unsigned char* lds, const Gemm g, const Sched& S, const Epi& E) {
;     ...
;             PG8_WAIT_V(8); PG8_WAIT_L(0); PG8_BAR; PG8_MMA(1, 0, At, B0); PG8_MMA(1, 1, At, B1); PG8_BAR; PG8_SCHED;
;             PG8_LDB(B0, 1, 0); PG8_LDB(B1, 1, 1); PG8_SCHED; PG8_LDA(At, 1, 0); PG8_STAGE(PG8_SA(0, 1), a2 + hstep, voffA);
;             PG8_WAIT_V(8); PG8_WAIT_L(0); PG8_BAR; PG8_MMA(0, 0, At, B0); PG8_MMA(0, 1, At, B1); PG8_BAR; PG8_SCHED;
;             PG8_LDA(At, 1, 1); PG8_STAGE(PG8_SB(1, 0), b3, voffB); PG8_STAGE(PG8_SB(1, 1), b3 + hstep, voffB); PG8_STAGE(PG8_SA(1, 0), a3, voffA);
	s_waitcnt lgkmcnt(0)
	v_mfma_f32_16x16x32_bf16 v[62:65], v[154:157], v[188:191], 0
	v_mfma_f32_16x16x32_bf16 v[62:65], v[158:161], v[198:201], v[62:65]
	v_mfma_f32_16x16x32_bf16 v[46:49], v[158:161], v[206:209], 0
	v_mfma_f32_16x16x32_bf16 v[46:49], v[154:157], v[202:205], v[46:49]
	v_mfma_f32_16x16x32_bf16 v[30:33], v[154:157], v[210:213], 0
	v_mfma_f32_16x16x32_bf16 v[30:33], v[158:161], v[214:217], v[30:33]
	v_mfma_f32_16x16x32_bf16 v[14:17], v[158:161], v[222:225], 0
	v_mfma_f32_16x16x32_bf16 v[14:17], v[154:157], v[218:221], v[14:17]
	v_mfma_f32_16x16x32_bf16 v[10:13], v[162:165], v[218:221], 0
	v_mfma_f32_16x16x32_bf16 v[10:13], v[166:169], v[222:225], v[10:13]
	v_mfma_f32_16x16x32_bf16 v[26:29], v[166:169], v[214:217], 0
	v_mfma_f32_16x16x32_bf16 v[26:29], v[162:165], v[210:213], v[26:29]
	v_mfma_f32_16x16x32_bf16 v[42:45], v[162:165], v[202:205], 0
	v_mfma_f32_16x16x32_bf16 v[42:45], v[166:169], v[206:209], v[42:45]
	v_mfma_f32_16x16x32_bf16 v[58:61], v[166:169], v[198:201], 0
	v_mfma_f32_16x16x32_bf16 v[58:61], v[162:165], v[188:191], v[58:61]
	v_mfma_f32_16x16x32_bf16 v[54:57], v[170:173], v[188:191], 0
	v_mfma_f32_16x16x32_bf16 v[54:57], v[174:177], v[198:201], v[54:57]
	v_mfma_f32_16x16x32_bf16 v[38:41], v[174:177], v[206:209], 0
	v_mfma_f32_16x16x32_bf16 v[38:41], v[170:173], v[202:205], v[38:41]
	v_mfma_f32_16x16x32_bf16 v[22:25], v[170:173], v[210:213], 0
	v_mfma_f32_16x16x32_bf16 v[22:25], v[174:177], v[214:217], v[22:25]
	v_mfma_f32_16x16x32_bf16 v[6:9], v[174:177], v[222:225], 0
	v_mfma_f32_16x16x32_bf16 v[6:9], v[170:173], v[218:221], v[6:9]
	v_mfma_f32_16x16x32_bf16 v[2:5], v[180:183], v[218:221], 0
	v_mfma_f32_16x16x32_bf16 v[2:5], v[184:187], v[222:225], v[2:5]
	v_mfma_f32_16x16x32_bf16 v[18:21], v[184:187], v[214:217], 0
	v_mfma_f32_16x16x32_bf16 v[18:21], v[180:183], v[210:213], v[18:21]
	v_mfma_f32_16x16x32_bf16 v[34:37], v[180:183], v[202:205], 0
	v_mfma_f32_16x16x32_bf16 v[34:37], v[184:187], v[206:209], v[34:37]
	v_mfma_f32_16x16x32_bf16 v[50:53], v[184:187], v[198:201], 0
	v_mfma_f32_16x16x32_bf16 v[50:53], v[180:183], v[188:191], v[50:53]
	s_barrier
	s_add_i32 s71, 0, 0x18000
	v_add_u32_e32 v146, s71, v1
	s_add_i32 s72, 0, 0x1c000
	ds_read_b128 v[154:157], v146
	ds_read_b128 v[158:161], v146 offset:1024
	ds_read_b128 v[162:165], v146 offset:2048
	ds_read_b128 v[166:169], v146 offset:3072
	v_add_u32_e32 v146, s72, v1
	ds_read_b128 v[170:173], v146
	ds_read_b128 v[174:177], v146 offset:1024
	ds_read_b128 v[180:183], v146 offset:2048
	ds_read_b128 v[184:187], v146 offset:3072
	s_mov_b32 m0, s26
	s_nop 0
	global_load_lds_dwordx4 v130, s[50:51]
	s_mov_b32 m0, s27
	s_nop 0
	global_load_lds_dwordx4 v134, s[50:51]
	s_add_u32 s50, s50, 0x4000
	s_addc_u32 s51, s51, 0
	s_mov_b32 m0, s28
	ds_read_b128 v[188:191], v151 offset:32768
	ds_read_b128 v[198:201], v151 offset:33792
	ds_read_b128 v[202:205], v151 offset:34816
	ds_read_b128 v[206:209], v151 offset:35840
	ds_read_b128 v[210:213], v151 offset:36864
	ds_read_b128 v[214:217], v151 offset:37888
	ds_read_b128 v[218:221], v151 offset:38912
	ds_read_b128 v[222:225], v151 offset:39936
	global_load_lds_dwordx4 v130, s[50:51]
	s_mov_b32 m0, s29
	s_nop 0
	global_load_lds_dwordx4 v134, s[50:51]
	s_waitcnt vmcnt(8)
	s_waitcnt lgkmcnt(0)
	s_barrier
; #define PG8_STAGE(bufoff, gbase, voff) do { _Pragma("unroll") for (int _i = 0; _i < 2; ++_i) \
;         __builtin_amdgcn_global_load_lds((const unsigned*)((const char*)(gbase) + (voff)[_i]), (PG8_LAS unsigned*)(lds + (bufoff) + ldsw + _i * 8192), 16, 0, 0); } while (0)
; #define PG8_LDA(dst, b, h) do { _Pragma("unroll") for (int m = 0; m < 4; ++m) _Pragma("unroll") for (int k = 0; k < 2; ++k) dst[m][k] = *(const PG8_LAS bf16x8*)(lds + PG8_SA(b, h) + aoff + m * 2048 + k * 1024); } while (0)
; #define PG8_MMA(ai, bj, At, Bt) do { __builtin_amdgcn_s_setprio(1); _Pragma("unroll") for (int m = 0; m < 4; ++m) _Pragma("unroll") for (int n = 0; n < 2; ++n) _Pragma("unroll") for (int k = 0; k < 2; ++k) \
;         acc[ai][bj][m][n] = __builtin_amdgcn_mfma_f32_16x16x32_bf16(Bt[n][k], At[m][k], acc[ai][bj][m][n], 0, 0, 0); __builtin_amdgcn_s_setprio(0); } while (0)
; #define PG8_WAIT_V(n) asm volatile("s_waitcnt vmcnt(" #n ")" ::: "memory")
; #define PG8_WAIT_L(n) asm volatile("s_waitcnt lgkmcnt(" #n ")" ::: "memory")
; #define PG8_BAR __builtin_amdgcn_s_barrier()
; #define PG8_SCHED __builtin_amdgcn_sched_barrier(0)
; template <class Epi, class Sched, bool ALIGN_EPI = false, bool SP2 = false>
; __device__ __forceinline__ void gemm_phase(PG8_LAS unsigned char* lds, const Gemm g, const Sched& S, const Epi& E) {
;     ...
;             PG8_WAIT_V(8); PG8_WAIT_L(0); PG8_BAR; PG8_MMA(0, 0, At, B0); PG8_MMA(0, 1, At, B1); PG8_BAR; PG8_SCHED;
;             PG8_LDA(At, 1, 1); PG8_STAGE(PG8_SB(1, 0), b3, voffB); PG8_STAGE(PG8_SB(1, 1), b3 + hstep, voffB); PG8_STAGE(PG8_SA(1, 0), a3, voffA);
;             PG8_WAIT_V(8); PG8_WAIT_L(0); PG8_BAR; PG8_MMA(1, 0, At, B0); PG8_MMA(1, 1, At, B1); PG8_BAR; PG8_SCHED;
	s_waitcnt lgkmcnt(0)
	v_mfma_f32_16x16x32_bf16 v[126:129], v[154:157], v[188:191], v[126:129]
	v_mfma_f32_16x16x32_bf16 v[126:129], v[158:161], v[198:201], v[126:129]
	v_mfma_f32_16x16x32_bf16 v[110:113], v[158:161], v[206:209], v[110:113]
	v_mfma_f32_16x16x32_bf16 v[110:113], v[154:157], v[202:205], v[110:113]
	v_mfma_f32_16x16x32_bf16 v[94:97], v[154:157], v[210:213], v[94:97]
	v_mfma_f32_16x16x32_bf16 v[94:97], v[158:161], v[214:217], v[94:97]
	v_mfma_f32_16x16x32_bf16 v[78:81], v[158:161], v[222:225], v[78:81]
	v_mfma_f32_16x16x32_bf16 v[78:81], v[154:157], v[218:221], v[78:81]
	v_mfma_f32_16x16x32_bf16 v[74:77], v[162:165], v[218:221], v[74:77]
	v_mfma_f32_16x16x32_bf16 v[74:77], v[166:169], v[222:225], v[74:77]
	v_mfma_f32_16x16x32_bf16 v[90:93], v[166:169], v[214:217], v[90:93]
	v_mfma_f32_16x16x32_bf16 v[90:93], v[162:165], v[210:213], v[90:93]
	v_mfma_f32_16x16x32_bf16 v[106:109], v[162:165], v[202:205], v[106:109]
	v_mfma_f32_16x16x32_bf16 v[106:109], v[166:169], v[206:209], v[106:109]
	v_mfma_f32_16x16x32_bf16 v[122:125], v[166:169], v[198:201], v[122:125]
	v_mfma_f32_16x16x32_bf16 v[122:125], v[162:165], v[188:191], v[122:125]
	v_mfma_f32_16x16x32_bf16 v[118:121], v[170:173], v[188:191], v[118:121]
	v_mfma_f32_16x16x32_bf16 v[118:121], v[174:177], v[198:201], v[118:121]
	v_mfma_f32_16x16x32_bf16 v[102:105], v[174:177], v[206:209], v[102:105]
	v_mfma_f32_16x16x32_bf16 v[102:105], v[170:173], v[202:205], v[102:105]
	v_mfma_f32_16x16x32_bf16 v[86:89], v[170:173], v[210:213], v[86:89]
	v_mfma_f32_16x16x32_bf16 v[86:89], v[174:177], v[214:217], v[86:89]
	v_mfma_f32_16x16x32_bf16 v[70:73], v[174:177], v[222:225], v[70:73]
	v_mfma_f32_16x16x32_bf16 v[70:73], v[170:173], v[218:221], v[70:73]
	v_mfma_f32_16x16x32_bf16 v[66:69], v[180:183], v[218:221], v[66:69]
	v_mfma_f32_16x16x32_bf16 v[66:69], v[184:187], v[222:225], v[66:69]
	v_mfma_f32_16x16x32_bf16 v[82:85], v[184:187], v[214:217], v[82:85]
	v_mfma_f32_16x16x32_bf16 v[82:85], v[180:183], v[210:213], v[82:85]
	v_mfma_f32_16x16x32_bf16 v[98:101], v[180:183], v[202:205], v[98:101]
	v_mfma_f32_16x16x32_bf16 v[98:101], v[184:187], v[206:209], v[98:101]
	v_mfma_f32_16x16x32_bf16 v[114:117], v[184:187], v[198:201], v[114:117]
	v_mfma_f32_16x16x32_bf16 v[114:117], v[180:183], v[188:191], v[114:117]
	s_barrier
	s_add_u32 s50, s48, 0x8000
	s_addc_u32 s51, s49, 0
	s_add_i32 s71, s71, s3
	s_mov_b32 m0, s71
	ds_read_b128 v[188:191], v151 offset:49152
	ds_read_b128 v[198:201], v151 offset:50176
	ds_read_b128 v[202:205], v151 offset:51200
	ds_read_b128 v[206:209], v151 offset:52224
	ds_read_b128 v[210:213], v151 offset:53248
	ds_read_b128 v[214:217], v151 offset:54272
	ds_read_b128 v[218:221], v151 offset:55296
	ds_read_b128 v[222:225], v151 offset:56320
	global_load_lds_dwordx4 v132, s[50:51]
	s_add_i32 m0, s71, 0x2000
	s_add_u32 s48, s48, 0xc000
	v_lshl_add_u64 v[146:147], s[50:51], 0, v[136:137]
	s_addc_u32 s49, s49, 0
	s_add_i32 s50, s72, s3
	global_load_lds_dwordx4 v[146:147], off
	s_mov_b32 m0, s50
	s_nop 0
	global_load_lds_dwordx4 v132, s[48:49]
	s_add_i32 m0, s50, 0x2000
	s_nop 0
	global_load_lds_dwordx4 v136, s[48:49]
	s_waitcnt vmcnt(6)
	s_waitcnt lgkmcnt(0)
	s_barrier
	s_waitcnt lgkmcnt(0)
	v_mfma_f32_16x16x32_bf16 v[62:65], v[154:157], v[188:191], v[62:65]
	v_mfma_f32_16x16x32_bf16 v[62:65], v[158:161], v[198:201], v[62:65]
	v_mfma_f32_16x16x32_bf16 v[46:49], v[158:161], v[206:209], v[46:49]
	v_mfma_f32_16x16x32_bf16 v[46:49], v[154:157], v[202:205], v[46:49]
	v_mfma_f32_16x16x32_bf16 v[30:33], v[154:157], v[210:213], v[30:33]
	v_mfma_f32_16x16x32_bf16 v[30:33], v[158:161], v[214:217], v[30:33]
	v_mfma_f32_16x16x32_bf16 v[14:17], v[158:161], v[222:225], v[14:17]
	v_mfma_f32_16x16x32_bf16 v[14:17], v[154:157], v[218:221], v[14:17]
	v_mfma_f32_16x16x32_bf16 v[10:13], v[162:165], v[218:221], v[10:13]
	v_mfma_f32_16x16x32_bf16 v[10:13], v[166:169], v[222:225], v[10:13]
	v_mfma_f32_16x16x32_bf16 v[26:29], v[166:169], v[214:217], v[26:29]
	v_mfma_f32_16x16x32_bf16 v[26:29], v[162:165], v[210:213], v[26:29]
	v_mfma_f32_16x16x32_bf16 v[42:45], v[162:165], v[202:205], v[42:45]
	v_mfma_f32_16x16x32_bf16 v[42:45], v[166:169], v[206:209], v[42:45]
	v_mfma_f32_16x16x32_bf16 v[58:61], v[166:169], v[198:201], v[58:61]
	v_mfma_f32_16x16x32_bf16 v[58:61], v[162:165], v[188:191], v[58:61]
	v_mfma_f32_16x16x32_bf16 v[54:57], v[170:173], v[188:191], v[54:57]
	v_mfma_f32_16x16x32_bf16 v[54:57], v[174:177], v[198:201], v[54:57]
	v_mfma_f32_16x16x32_bf16 v[38:41], v[174:177], v[206:209], v[38:41]
	v_mfma_f32_16x16x32_bf16 v[38:41], v[170:173], v[202:205], v[38:41]
	v_mfma_f32_16x16x32_bf16 v[22:25], v[170:173], v[210:213], v[22:25]
	v_mfma_f32_16x16x32_bf16 v[22:25], v[174:177], v[214:217], v[22:25]
	v_mfma_f32_16x16x32_bf16 v[6:9], v[174:177], v[222:225], v[6:9]
	v_mfma_f32_16x16x32_bf16 v[6:9], v[170:173], v[218:221], v[6:9]
	v_mfma_f32_16x16x32_bf16 v[2:5], v[180:183], v[218:221], v[2:5]
	v_mfma_f32_16x16x32_bf16 v[2:5], v[184:187], v[222:225], v[2:5]
	v_mfma_f32_16x16x32_bf16 v[18:21], v[184:187], v[214:217], v[18:21]
	v_mfma_f32_16x16x32_bf16 v[18:21], v[180:183], v[210:213], v[18:21]
	v_mfma_f32_16x16x32_bf16 v[34:37], v[180:183], v[202:205], v[34:37]
	v_mfma_f32_16x16x32_bf16 v[34:37], v[184:187], v[206:209], v[34:37]
	v_mfma_f32_16x16x32_bf16 v[50:53], v[184:187], v[198:201], v[50:53]
	v_mfma_f32_16x16x32_bf16 v[50:53], v[180:183], v[188:191], v[50:53]
	s_barrier
	s_add_i32 s70, s70, 2
	s_add_u32 s44, s44, 0x10000
	s_addc_u32 s45, s45, 0
	s_add_u32 s68, s68, 0x10000
	s_addc_u32 s69, s69, 0
	s_cmp_gt_u32 s70, 61

;     __device__ __forceinline__ bool next(int i, Unit& u) const { if (i >= 2) return false; const int xcd = c & 7, off = c >> 3; u.pm = 16 * i + 4 * (xcd >> 1) + (off & 3); u.pn = 8 * (xcd & 1) + (off >> 2); return true; }
; #define PG8_STAGE(bufoff, gbase, voff) do { _Pragma("unroll") for (int _i = 0; _i < 2; ++_i) \
;         __builtin_amdgcn_global_load_lds((const unsigned*)((const char*)(gbase) + (voff)[_i]), (PG8_LAS unsigned*)(lds + (bufoff) + ldsw + _i * 8192), 16, 0, 0); } while (0)
; #define PG8_LDA(dst, b, h) do { _Pragma("unroll") for (int m = 0; m < 4; ++m) _Pragma("unroll") for (int k = 0; k < 2; ++k) dst[m][k] = *(const PG8_LAS bf16x8*)(lds + PG8_SA(b, h) + aoff + m * 2048 + k * 1024); } while (0)
; #define PG8_WAIT_V(n) asm volatile("s_waitcnt vmcnt(" #n ")" ::: "memory")
; #define PG8_BAR __builtin_amdgcn_s_barrier()
; template <class Epi, class Sched, bool ALIGN_EPI = false, bool SP2 = false>
; __device__ __forceinline__ void gemm_phase(PG8_LAS unsigned char* lds, const Gemm g, const Sched& S, const Epi& E) {
;     ...
;         const bool has_next = S.next(ui + 1, nxt);
;         const char* nA = has_next ? (const char*)g.A + (size_t)nxt.pm * tstep : cA; const char* nB = has_next ? (const char*)g.Bt + (size_t)nxt.pn * tstep : cB;
;         constexpr int NSEG = Epi::HAS_MID ? 2 : 1; int t = 0;
; #pragma unroll
;         for (int seg = 0; seg < NSEG; ++seg) { const int tend = (seg + 1 < NSEG) ? (nt >> 1) : nt;
;         for (; t < tend; t += 2) {
;             const bool last = (t == nt - 2);
;             const char* a1 = cA + (size_t)(t + 1) * kstep;
;             const char* a2 = last ? nA : cA + (size_t)(t + 2) * kstep; const char* b2 = last ? nB : cB + (size_t)(t + 2) * kstep;
;             const char* a3 = a2 + kstep; const char* b3 = b2 + kstep;
;             if (last && has_next) S.a_ready(nxt);
;             if constexpr (SP2) {
;             PG8_LDB(B0, 0, 0); PG8_LDB(B1, 0, 1); PG8_SCHED; PG8_LDA(At, 0, 0); PG8_STAGE(PG8_SA(1, 1), a1 + hstep, voffA);
;             PG8_WAIT_V(8); PG8_WAIT_L(0); PG8_BAR; PG8_MMA(0, 0, At, B0); PG8_MMA(0, 1, At, B1); PG8_BAR; PG8_SCHED;
;             PG8_LDA(At, 0, 1); PG8_STAGE(PG8_SB(0, 0), b2, voffB); PG8_STAGE(PG8_SB(0, 1), b2 + hstep, voffB); PG8_STAGE(PG8_SA(0, 0), a2, voffA);
;             PG8_WAIT_V(8); PG8_WAIT_L(0); PG8_BAR; PG8_MMA(1, 0, At, B0); PG8_MMA(1, 1, At, B1); PG8_BAR; PG8_SCHED;
.LBB0_839:
	s_ashr_i32 s23, s22, 31
	s_lshl_b64 s[36:37], s[22:23], 21
	s_add_u32 s36, s18, s36
	s_addc_u32 s37, s19, s37
	s_and_b64 s[38:39], s[0:1], exec
	s_cselect_b32 s23, s37, s41
	s_cselect_b32 s65, s36, s40
	s_ashr_i32 s17, s16, 31
	s_lshl_b64 s[38:39], s[16:17], 21
	v_readlane_b32 s17, v255, 13
	s_add_u32 s38, s17, s38
	v_readlane_b32 s17, v255, 14
	s_addc_u32 s39, s17, s39
	s_and_b64 s[44:45], s[0:1], exec
	s_cselect_b32 s17, s39, s43
	s_cselect_b32 s66, s38, s42
	s_add_u32 s40, s40, 0xc000
	s_addc_u32 s41, s41, 0
	s_add_u32 s67, s42, 0x10000
	s_addc_u32 s68, s43, 0
	s_mov_b32 s69, -2
	s_nop 3
	ds_read_b128 v[148:151], v153
	ds_read_b128 v[158:161], v153 offset:1024
	ds_read_b128 v[162:165], v153 offset:2048
	ds_read_b128 v[166:169], v153 offset:3072
	ds_read_b128 v[170:173], v154
	ds_read_b128 v[174:177], v154 offset:1024
	ds_read_b128 v[180:183], v154 offset:2048
	ds_read_b128 v[184:187], v154 offset:3072
	s_add_u32 s42, s40, 0x4000
	s_addc_u32 s43, s41, 0
	s_cmp_eq_u32 s69, 60
	s_cselect_b32 s46, s65, s42
	s_cselect_b32 s47, s23, s43
	s_cselect_b32 s44, s66, s67
	s_cselect_b32 s45, s17, s68
	s_add_u32 s42, s46, 0x8000
	s_addc_u32 s43, s47, 0
	s_sub_u32 s42, s40, 0x4000
	s_subb_u32 s43, s41, 0
	s_mov_b32 m0, s50
	s_nop 0
	global_load_lds_dwordx4 v130, s[42:43]
	s_mov_b32 m0, s51
	s_nop 0
	global_load_lds_dwordx4 v134, s[42:43]
	s_add_i32 m0, s28, 0xc000
	ds_read_b128 v[188:191], v155
	ds_read_b128 v[198:201], v155 offset:1024
	ds_read_b128 v[202:205], v155 offset:2048
	ds_read_b128 v[206:209], v155 offset:3072
	ds_read_b128 v[210:213], v155 offset:4096
	ds_read_b128 v[214:217], v155 offset:5120
	ds_read_b128 v[218:221], v155 offset:6144
	ds_read_b128 v[222:225], v155 offset:7168
	global_load_lds_dwordx4 v140, s[40:41]
	s_add_i32 m0, s28, 0xe000
	s_nop 0
	global_load_lds_dwordx4 v142, s[40:41]
	s_waitcnt vmcnt(8)
	s_waitcnt lgkmcnt(0)
	s_barrier
	s_waitcnt lgkmcnt(0)
	v_mfma_f32_16x16x32_bf16 v[126:129], v[148:151], v[188:191], 0
	v_mfma_f32_16x16x32_bf16 v[126:129], v[158:161], v[198:201], v[126:129]
	v_mfma_f32_16x16x32_bf16 v[110:113], v[158:161], v[206:209], 0
	v_mfma_f32_16x16x32_bf16 v[110:113], v[148:151], v[202:205], v[110:113]
	v_mfma_f32_16x16x32_bf16 v[94:97], v[148:151], v[210:213], 0
	v_mfma_f32_16x16x32_bf16 v[94:97], v[158:161], v[214:217], v[94:97]
	v_mfma_f32_16x16x32_bf16 v[78:81], v[158:161], v[222:225], 0
	v_mfma_f32_16x16x32_bf16 v[78:81], v[148:151], v[218:221], v[78:81]
	v_mfma_f32_16x16x32_bf16 v[74:77], v[162:165], v[218:221], 0
	v_mfma_f32_16x16x32_bf16 v[74:77], v[166:169], v[222:225], v[74:77]
	v_mfma_f32_16x16x32_bf16 v[90:93], v[166:169], v[214:217], 0
	v_mfma_f32_16x16x32_bf16 v[90:93], v[162:165], v[210:213], v[90:93]
	v_mfma_f32_16x16x32_bf16 v[106:109], v[162:165], v[202:205], 0
	v_mfma_f32_16x16x32_bf16 v[106:109], v[166:169], v[206:209], v[106:109]
	v_mfma_f32_16x16x32_bf16 v[122:125], v[166:169], v[198:201], 0
	v_mfma_f32_16x16x32_bf16 v[122:125], v[162:165], v[188:191], v[122:125]
	v_mfma_f32_16x16x32_bf16 v[118:121], v[170:173], v[188:191], 0
	v_mfma_f32_16x16x32_bf16 v[118:121], v[174:177], v[198:201], v[118:121]
	v_mfma_f32_16x16x32_bf16 v[102:105], v[174:177], v[206:209], 0
	v_mfma_f32_16x16x32_bf16 v[102:105], v[170:173], v[202:205], v[102:105]
	v_mfma_f32_16x16x32_bf16 v[86:89], v[170:173], v[210:213], 0
	v_mfma_f32_16x16x32_bf16 v[86:89], v[174:177], v[214:217], v[86:89]
	v_mfma_f32_16x16x32_bf16 v[70:73], v[174:177], v[222:225], 0
	v_mfma_f32_16x16x32_bf16 v[70:73], v[170:173], v[218:221], v[70:73]
	v_mfma_f32_16x16x32_bf16 v[66:69], v[180:183], v[218:221], 0
	v_mfma_f32_16x16x32_bf16 v[66:69], v[184:187], v[222:225], v[66:69]
	v_mfma_f32_16x16x32_bf16 v[82:85], v[184:187], v[214:217], 0
	v_mfma_f32_16x16x32_bf16 v[82:85], v[180:183], v[210:213], v[82:85]
	v_mfma_f32_16x16x32_bf16 v[98:101], v[180:183], v[202:205], 0
	v_mfma_f32_16x16x32_bf16 v[98:101], v[184:187], v[206:209], v[98:101]
	v_mfma_f32_16x16x32_bf16 v[114:117], v[184:187], v[198:201], 0
	v_mfma_f32_16x16x32_bf16 v[114:117], v[180:183], v[188:191], v[114:117]
	s_barrier
	s_add_i32 s70, s56, s3
	s_mov_b32 m0, s70
	ds_read_b128 v[188:191], v155 offset:16384
	ds_read_b128 v[198:201], v155 offset:17408
	ds_read_b128 v[202:205], v155 offset:18432
	ds_read_b128 v[206:209], v155 offset:19456
	ds_read_b128 v[210:213], v155 offset:20480
	ds_read_b128 v[214:217], v155 offset:21504
	ds_read_b128 v[218:221], v155 offset:22528
	ds_read_b128 v[222:225], v155 offset:23552
	global_load_lds_dwordx4 v132, s[44:45]
	s_add_i32 m0, s70, 0x2000
	s_add_u32 s70, s44, 0x4000
	s_addc_u32 s71, s45, 0
	s_add_i32 s72, s57, s3
	global_load_lds_dwordx4 v136, s[44:45]
	s_mov_b32 m0, s72
	s_nop 0
	global_load_lds_dwordx4 v132, s[70:71]
	s_add_i32 m0, s72, 0x2000
	s_nop 0
	global_load_lds_dwordx4 v136, s[70:71]
	s_waitcnt vmcnt(6)
	s_waitcnt lgkmcnt(0)
	s_barrier
; #define PG8_STAGE(bufoff, gbase, voff) do { _Pragma("unroll") for (int _i = 0; _i < 2; ++_i) \
;         __builtin_amdgcn_global_load_lds((const unsigned*)((const char*)(gbase) + (voff)[_i]), (PG8_LAS unsigned*)(lds + (bufoff) + ldsw + _i * 8192), 16, 0, 0); } while (0)
; #define PG8_LDA(dst, b, h) do { _Pragma("unroll") for (int m = 0; m < 4; ++m) _Pragma("unroll") for (int k = 0; k < 2; ++k) dst[m][k] = *(const PG8_LAS bf16x8*)(lds + PG8_SA(b, h) + aoff + m * 2048 + k * 1024); } while (0)
; #define PG8_LDB(dst, b, h) do { _Pragma("unroll") for (int n = 0; n < 2; ++n) _Pragma("unroll") for (int k = 0; k < 2; ++k) dst[n][k] = *(const PG8_LAS bf16x8*)(lds + PG8_SB(b, h) + boff + n * 2048 + k * 1024); } while (0)
; #define PG8_MMA(ai, bj, At, Bt) do { __builtin_amdgcn_s_setprio(1); _Pragma("unroll") for (int m = 0; m < 4; ++m) _Pragma("unroll") for (int n = 0; n < 2; ++n) _Pragma("unroll") for (int k = 0; k < 2; ++k) \
;         acc[ai][bj][m][n] = __builtin_amdgcn_mfma_f32_16x16x32_bf16(Bt[n][k], At[m][k], acc[ai][bj][m][n], 0, 0, 0); __builtin_amdgcn_s_setprio(0); } while (0)
; #define PG8_WAIT_V(n) asm volatile("s_waitcnt vmcnt(" #n ")" ::: "memory")
; #define PG8_WAIT_L(n) asm volatile("s_waitcnt lgkmcnt(" #n ")" ::: "memory")
; #define PG8_BAR __builtin_amdgcn_s_barrier()
; #define PG8_SCHED __builtin_amdgcn_sched_barrier(0)
; template <class Epi, class Sched, bool ALIGN_EPI = false, bool SP2 = false>
; __device__ __forceinline__ void gemm_phase(PG8_LAS unsigned char* lds, const Gemm g, const Sched& S, const Epi& E) {
;     ...
;             PG8_WAIT_V(8); PG8_WAIT_L(0); PG8_BAR; PG8_MMA(1, 0, At, B0); PG8_MMA(1, 1, At, B1); PG8_BAR; PG8_SCHED;
;             PG8_LDB(B0, 1, 0); PG8_LDB(B1, 1, 1); PG8_SCHED; PG8_LDA(At, 1, 0); PG8_STAGE(PG8_SA(0, 1), a2 + hstep, voffA);
;             PG8_WAIT_V(8); PG8_WAIT_L(0); PG8_BAR; PG8_MMA(0, 0, At, B0); PG8_MMA(0, 1, At, B1); PG8_BAR; PG8_SCHED;
;             PG8_LDA(At, 1, 1); PG8_STAGE(PG8_SB(1, 0), b3, voffB); PG8_STAGE(PG8_SB(1, 1), b3 + hstep, voffB); PG8_STAGE(PG8_SA(1, 0), a3, voffA);
	s_waitcnt lgkmcnt(0)
	v_mfma_f32_16x16x32_bf16 v[62:65], v[148:151], v[188:191], 0
	v_mfma_f32_16x16x32_bf16 v[62:65], v[158:161], v[198:201], v[62:65]
	v_mfma_f32_16x16x32_bf16 v[46:49], v[158:161], v[206:209], 0
	v_mfma_f32_16x16x32_bf16 v[46:49], v[148:151], v[202:205], v[46:49]
	v_mfma_f32_16x16x32_bf16 v[30:33], v[148:151], v[210:213], 0
	v_mfma_f32_16x16x32_bf16 v[30:33], v[158:161], v[214:217], v[30:33]
	v_mfma_f32_16x16x32_bf16 v[14:17], v[158:161], v[222:225], 0
	v_mfma_f32_16x16x32_bf16 v[14:17], v[148:151], v[218:221], v[14:17]
	v_mfma_f32_16x16x32_bf16 v[10:13], v[162:165], v[218:221], 0
	v_mfma_f32_16x16x32_bf16 v[10:13], v[166:169], v[222:225], v[10:13]
	v_mfma_f32_16x16x32_bf16 v[26:29], v[166:169], v[214:217], 0
	v_mfma_f32_16x16x32_bf16 v[26:29], v[162:165], v[210:213], v[26:29]
	v_mfma_f32_16x16x32_bf16 v[42:45], v[162:165], v[202:205], 0
	v_mfma_f32_16x16x32_bf16 v[42:45], v[166:169], v[206:209], v[42:45]
	v_mfma_f32_16x16x32_bf16 v[58:61], v[166:169], v[198:201], 0
	v_mfma_f32_16x16x32_bf16 v[58:61], v[162:165], v[188:191], v[58:61]
	v_mfma_f32_16x16x32_bf16 v[54:57], v[170:173], v[188:191], 0
	v_mfma_f32_16x16x32_bf16 v[54:57], v[174:177], v[198:201], v[54:57]
	v_mfma_f32_16x16x32_bf16 v[38:41], v[174:177], v[206:209], 0
	v_mfma_f32_16x16x32_bf16 v[38:41], v[170:173], v[202:205], v[38:41]
	v_mfma_f32_16x16x32_bf16 v[22:25], v[170:173], v[210:213], 0
	v_mfma_f32_16x16x32_bf16 v[22:25], v[174:177], v[214:217], v[22:25]
	v_mfma_f32_16x16x32_bf16 v[6:9], v[174:177], v[222:225], 0
	v_mfma_f32_16x16x32_bf16 v[6:9], v[170:173], v[218:221], v[6:9]
	v_mfma_f32_16x16x32_bf16 v[2:5], v[180:183], v[218:221], 0
	v_mfma_f32_16x16x32_bf16 v[2:5], v[184:187], v[222:225], v[2:5]
	v_mfma_f32_16x16x32_bf16 v[18:21], v[184:187], v[214:217], 0
	v_mfma_f32_16x16x32_bf16 v[18:21], v[180:183], v[210:213], v[18:21]
	v_mfma_f32_16x16x32_bf16 v[34:37], v[180:183], v[202:205], 0
	v_mfma_f32_16x16x32_bf16 v[34:37], v[184:187], v[206:209], v[34:37]
	v_mfma_f32_16x16x32_bf16 v[50:53], v[184:187], v[198:201], 0
	v_mfma_f32_16x16x32_bf16 v[50:53], v[180:183], v[188:191], v[50:53]
	s_barrier
	s_add_i32 s70, 0, 0x18000
	v_add_u32_e32 v138, s70, v1
	s_add_i32 s71, 0, 0x1c000
	ds_read_b128 v[148:151], v138
	ds_read_b128 v[158:161], v138 offset:1024
	ds_read_b128 v[162:165], v138 offset:2048
	ds_read_b128 v[166:169], v138 offset:3072
	v_add_u32_e32 v138, s71, v1
	ds_read_b128 v[170:173], v138
	ds_read_b128 v[174:177], v138 offset:1024
	ds_read_b128 v[180:183], v138 offset:2048
	ds_read_b128 v[184:187], v138 offset:3072
	s_mov_b32 m0, s28
	s_nop 0
	global_load_lds_dwordx4 v130, s[46:47]
	s_mov_b32 m0, s29
	s_nop 0
	global_load_lds_dwordx4 v134, s[46:47]
	s_add_u32 s46, s46, 0x4000
	s_addc_u32 s47, s47, 0
	s_mov_b32 m0, s30
	ds_read_b128 v[188:191], v155 offset:32768
	ds_read_b128 v[198:201], v155 offset:33792
	ds_read_b128 v[202:205], v155 offset:34816
	ds_read_b128 v[206:209], v155 offset:35840
	ds_read_b128 v[210:213], v155 offset:36864
	ds_read_b128 v[214:217], v155 offset:37888
	ds_read_b128 v[218:221], v155 offset:38912
	ds_read_b128 v[222:225], v155 offset:39936
	global_load_lds_dwordx4 v130, s[46:47]
	s_mov_b32 m0, s31
	s_nop 0
	global_load_lds_dwordx4 v134, s[46:47]
	s_waitcnt vmcnt(8)
	s_waitcnt lgkmcnt(0)
	s_barrier
; #define PG8_STAGE(bufoff, gbase, voff) do { _Pragma("unroll") for (int _i = 0; _i < 2; ++_i) \
;         __builtin_amdgcn_global_load_lds((const unsigned*)((const char*)(gbase) + (voff)[_i]), (PG8_LAS unsigned*)(lds + (bufoff) + ldsw + _i * 8192), 16, 0, 0); } while (0)
; #define PG8_LDA(dst, b, h) do { _Pragma("unroll") for (int m = 0; m < 4; ++m) _Pragma("unroll") for (int k = 0; k < 2; ++k) dst[m][k] = *(const PG8_LAS bf16x8*)(lds + PG8_SA(b, h) + aoff + m * 2048 + k * 1024); } while (0)
; #define PG8_LDB(dst, b, h) do { _Pragma("unroll") for (int n = 0; n < 2; ++n) _Pragma("unroll") for (int k = 0; k < 2; ++k) dst[n][k] = *(const PG8_LAS bf16x8*)(lds + PG8_SB(b, h) + boff + n * 2048 + k * 1024); } while (0)
; #define PG8_MMA(ai, bj, At, Bt) do { __builtin_amdgcn_s_setprio(1); _Pragma("unroll") for (int m = 0; m < 4; ++m) _Pragma("unroll") for (int n = 0; n < 2; ++n) _Pragma("unroll") for (int k = 0; k < 2; ++k) \
;         acc[ai][bj][m][n] = __builtin_amdgcn_mfma_f32_16x16x32_bf16(Bt[n][k], At[m][k], acc[ai][bj][m][n], 0, 0, 0); __builtin_amdgcn_s_setprio(0); } while (0)
; #define PG8_WAIT_V(n) asm volatile("s_waitcnt vmcnt(" #n ")" ::: "memory")
; #define PG8_WAIT_L(n) asm volatile("s_waitcnt lgkmcnt(" #n ")" ::: "memory")
; #define PG8_BAR __builtin_amdgcn_s_barrier()
; #define PG8_SCHED __builtin_amdgcn_sched_barrier(0)
; template <class Epi, class Sched, bool ALIGN_EPI = false, bool SP2 = false>
; __device__ __forceinline__ void gemm_phase(PG8_LAS unsigned char* lds, const Gemm g, const Sched& S, const Epi& E) {
;     ...
;         for (; t < tend; t += 2) {
;     ...
;             PG8_LDB(B0, 1, 0); PG8_LDB(B1, 1, 1); PG8_SCHED; PG8_LDA(At, 1, 0); PG8_STAGE(PG8_SA(0, 1), a2 + hstep, voffA);
;             PG8_WAIT_V(8); PG8_WAIT_L(0); PG8_BAR; PG8_MMA(0, 0, At, B0); PG8_MMA(0, 1, At, B1); PG8_BAR; PG8_SCHED;
;             PG8_LDA(At, 1, 1); PG8_STAGE(PG8_SB(1, 0), b3, voffB); PG8_STAGE(PG8_SB(1, 1), b3 + hstep, voffB); PG8_STAGE(PG8_SA(1, 0), a3, voffA);
;             PG8_WAIT_V(8); PG8_WAIT_L(0); PG8_BAR; PG8_MMA(1, 0, At, B0); PG8_MMA(1, 1, At, B1); PG8_BAR; PG8_SCHED;
	s_waitcnt lgkmcnt(0)
	v_mfma_f32_16x16x32_bf16 v[126:129], v[148:151], v[188:191], v[126:129]
	v_mfma_f32_16x16x32_bf16 v[126:129], v[158:161], v[198:201], v[126:129]
	v_mfma_f32_16x16x32_bf16 v[110:113], v[158:161], v[206:209], v[110:113]
	v_mfma_f32_16x16x32_bf16 v[110:113], v[148:151], v[202:205], v[110:113]
	v_mfma_f32_16x16x32_bf16 v[94:97], v[148:151], v[210:213], v[94:97]
	v_mfma_f32_16x16x32_bf16 v[94:97], v[158:161], v[214:217], v[94:97]
	v_mfma_f32_16x16x32_bf16 v[78:81], v[158:161], v[222:225], v[78:81]
	v_mfma_f32_16x16x32_bf16 v[78:81], v[148:151], v[218:221], v[78:81]
	v_mfma_f32_16x16x32_bf16 v[74:77], v[162:165], v[218:221], v[74:77]
	v_mfma_f32_16x16x32_bf16 v[74:77], v[166:169], v[222:225], v[74:77]
	v_mfma_f32_16x16x32_bf16 v[90:93], v[166:169], v[214:217], v[90:93]
	v_mfma_f32_16x16x32_bf16 v[90:93], v[162:165], v[210:213], v[90:93]
	v_mfma_f32_16x16x32_bf16 v[106:109], v[162:165], v[202:205], v[106:109]
	v_mfma_f32_16x16x32_bf16 v[106:109], v[166:169], v[206:209], v[106:109]
	v_mfma_f32_16x16x32_bf16 v[122:125], v[166:169], v[198:201], v[122:125]
	v_mfma_f32_16x16x32_bf16 v[122:125], v[162:165], v[188:191], v[122:125]
	v_mfma_f32_16x16x32_bf16 v[118:121], v[170:173], v[188:191], v[118:121]
	v_mfma_f32_16x16x32_bf16 v[118:121], v[174:177], v[198:201], v[118:121]
	v_mfma_f32_16x16x32_bf16 v[102:105], v[174:177], v[206:209], v[102:105]
	v_mfma_f32_16x16x32_bf16 v[102:105], v[170:173], v[202:205], v[102:105]
	v_mfma_f32_16x16x32_bf16 v[86:89], v[170:173], v[210:213], v[86:89]
	v_mfma_f32_16x16x32_bf16 v[86:89], v[174:177], v[214:217], v[86:89]
	v_mfma_f32_16x16x32_bf16 v[70:73], v[174:177], v[222:225], v[70:73]
	v_mfma_f32_16x16x32_bf16 v[70:73], v[170:173], v[218:221], v[70:73]
	v_mfma_f32_16x16x32_bf16 v[66:69], v[180:183], v[218:221], v[66:69]
	v_mfma_f32_16x16x32_bf16 v[66:69], v[184:187], v[222:225], v[66:69]
	v_mfma_f32_16x16x32_bf16 v[82:85], v[184:187], v[214:217], v[82:85]
	v_mfma_f32_16x16x32_bf16 v[82:85], v[180:183], v[210:213], v[82:85]
	v_mfma_f32_16x16x32_bf16 v[98:101], v[180:183], v[202:205], v[98:101]
	v_mfma_f32_16x16x32_bf16 v[98:101], v[184:187], v[206:209], v[98:101]
	v_mfma_f32_16x16x32_bf16 v[114:117], v[184:187], v[198:201], v[114:117]
	v_mfma_f32_16x16x32_bf16 v[114:117], v[180:183], v[188:191], v[114:117]
	s_barrier
	s_add_u32 s46, s44, 0x8000
	s_addc_u32 s47, s45, 0
	s_add_i32 s70, s70, s3
	s_mov_b32 m0, s70
	ds_read_b128 v[188:191], v155 offset:49152
	ds_read_b128 v[198:201], v155 offset:50176
	ds_read_b128 v[202:205], v155 offset:51200
	ds_read_b128 v[206:209], v155 offset:52224
	ds_read_b128 v[210:213], v155 offset:53248
	ds_read_b128 v[214:217], v155 offset:54272
	ds_read_b128 v[218:221], v155 offset:55296
	ds_read_b128 v[222:225], v155 offset:56320
	global_load_lds_dwordx4 v132, s[46:47]
	s_add_i32 m0, s70, 0x2000
	s_add_u32 s44, s44, 0xc000
	v_lshl_add_u64 v[226:227], s[46:47], 0, v[136:137]
	s_addc_u32 s45, s45, 0
	s_add_i32 s46, s71, s3
	global_load_lds_dwordx4 v[226:227], off
	s_mov_b32 m0, s46
	s_nop 0
	global_load_lds_dwordx4 v132, s[44:45]
	s_add_i32 m0, s46, 0x2000
	s_nop 0
	global_load_lds_dwordx4 v136, s[44:45]
	s_waitcnt vmcnt(6)
	s_waitcnt lgkmcnt(0)
	s_barrier
	s_waitcnt lgkmcnt(0)
	v_mfma_f32_16x16x32_bf16 v[62:65], v[148:151], v[188:191], v[62:65]
	v_mfma_f32_16x16x32_bf16 v[62:65], v[158:161], v[198:201], v[62:65]
	v_mfma_f32_16x16x32_bf16 v[46:49], v[158:161], v[206:209], v[46:49]
	v_mfma_f32_16x16x32_bf16 v[46:49], v[148:151], v[202:205], v[46:49]
	v_mfma_f32_16x16x32_bf16 v[30:33], v[148:151], v[210:213], v[30:33]
	v_mfma_f32_16x16x32_bf16 v[30:33], v[158:161], v[214:217], v[30:33]
	v_mfma_f32_16x16x32_bf16 v[14:17], v[158:161], v[222:225], v[14:17]
	v_mfma_f32_16x16x32_bf16 v[14:17], v[148:151], v[218:221], v[14:17]
	v_mfma_f32_16x16x32_bf16 v[10:13], v[162:165], v[218:221], v[10:13]
	v_mfma_f32_16x16x32_bf16 v[10:13], v[166:169], v[222:225], v[10:13]
	v_mfma_f32_16x16x32_bf16 v[26:29], v[166:169], v[214:217], v[26:29]
	v_mfma_f32_16x16x32_bf16 v[26:29], v[162:165], v[210:213], v[26:29]
	v_mfma_f32_16x16x32_bf16 v[42:45], v[162:165], v[202:205], v[42:45]
	v_mfma_f32_16x16x32_bf16 v[42:45], v[166:169], v[206:209], v[42:45]
	v_mfma_f32_16x16x32_bf16 v[58:61], v[166:169], v[198:201], v[58:61]
	v_mfma_f32_16x16x32_bf16 v[58:61], v[162:165], v[188:191], v[58:61]
	v_mfma_f32_16x16x32_bf16 v[54:57], v[170:173], v[188:191], v[54:57]
	v_mfma_f32_16x16x32_bf16 v[54:57], v[174:177], v[198:201], v[54:57]
	v_mfma_f32_16x16x32_bf16 v[38:41], v[174:177], v[206:209], v[38:41]
	v_mfma_f32_16x16x32_bf16 v[38:41], v[170:173], v[202:205], v[38:41]
	v_mfma_f32_16x16x32_bf16 v[22:25], v[170:173], v[210:213], v[22:25]
	v_mfma_f32_16x16x32_bf16 v[22:25], v[174:177], v[214:217], v[22:25]
	v_mfma_f32_16x16x32_bf16 v[6:9], v[174:177], v[222:225], v[6:9]
	v_mfma_f32_16x16x32_bf16 v[6:9], v[170:173], v[218:221], v[6:9]
	v_mfma_f32_16x16x32_bf16 v[2:5], v[180:183], v[218:221], v[2:5]
	v_mfma_f32_16x16x32_bf16 v[2:5], v[184:187], v[222:225], v[2:5]
	v_mfma_f32_16x16x32_bf16 v[18:21], v[184:187], v[214:217], v[18:21]
	v_mfma_f32_16x16x32_bf16 v[18:21], v[180:183], v[210:213], v[18:21]
	v_mfma_f32_16x16x32_bf16 v[34:37], v[180:183], v[202:205], v[34:37]
	v_mfma_f32_16x16x32_bf16 v[34:37], v[184:187], v[206:209], v[34:37]
	v_mfma_f32_16x16x32_bf16 v[50:53], v[184:187], v[198:201], v[50:53]
	v_mfma_f32_16x16x32_bf16 v[50:53], v[180:183], v[188:191], v[50:53]
	s_barrier
	s_add_i32 s69, s69, 2
	s_add_u32 s40, s40, 0x10000
	s_addc_u32 s41, s41, 0
	s_add_u32 s67, s67, 0x10000
	s_addc_u32 s68, s68, 0
	s_cmp_gt_u32 s69, 61

;     __device__ __forceinline__ bool next(int i, Unit& u) const { if (i >= 2) return false; const int xcd = c & 7, off = c >> 3; u.pm = 16 * i + 4 * (xcd >> 1) + (off & 3); u.pn = 8 * (xcd & 1) + (off >> 2); return true; }
; #define PG8_STAGE(bufoff, gbase, voff) do { _Pragma("unroll") for (int _i = 0; _i < 2; ++_i) \
;         __builtin_amdgcn_global_load_lds((const unsigned*)((const char*)(gbase) + (voff)[_i]), (PG8_LAS unsigned*)(lds + (bufoff) + ldsw + _i * 8192), 16, 0, 0); } while (0)
; #define PG8_LDA(dst, b, h) do { _Pragma("unroll") for (int m = 0; m < 4; ++m) _Pragma("unroll") for (int k = 0; k < 2; ++k) dst[m][k] = *(const PG8_LAS bf16x8*)(lds + PG8_SA(b, h) + aoff + m * 2048 + k * 1024); } while (0)
; #define PG8_WAIT_V(n) asm volatile("s_waitcnt vmcnt(" #n ")" ::: "memory")
; #define PG8_BAR __builtin_amdgcn_s_barrier()
; template <class Epi, class Sched, bool ALIGN_EPI = false, bool SP2 = false>
; __device__ __forceinline__ void gemm_phase(PG8_LAS unsigned char* lds, const Gemm g, const Sched& S, const Epi& E) {
;     ...
;         const bool has_next = S.next(ui + 1, nxt);
;         const char* nA = has_next ? (const char*)g.A + (size_t)nxt.pm * tstep : cA; const char* nB = has_next ? (const char*)g.Bt + (size_t)nxt.pn * tstep : cB;
;         constexpr int NSEG = Epi::HAS_MID ? 2 : 1; int t = 0;
; #pragma unroll
;         for (int seg = 0; seg < NSEG; ++seg) { const int tend = (seg + 1 < NSEG) ? (nt >> 1) : nt;
;         for (; t < tend; t += 2) {
;             const bool last = (t == nt - 2);
;             const char* a1 = cA + (size_t)(t + 1) * kstep;
;             const char* a2 = last ? nA : cA + (size_t)(t + 2) * kstep; const char* b2 = last ? nB : cB + (size_t)(t + 2) * kstep;
;             const char* a3 = a2 + kstep; const char* b3 = b2 + kstep;
;             if (last && has_next) S.a_ready(nxt);
;             if constexpr (SP2) {
;             PG8_LDB(B0, 0, 0); PG8_LDB(B1, 0, 1); PG8_SCHED; PG8_LDA(At, 0, 0); PG8_STAGE(PG8_SA(1, 1), a1 + hstep, voffA);
;             PG8_WAIT_V(8); PG8_WAIT_L(0); PG8_BAR; PG8_MMA(0, 0, At, B0); PG8_MMA(0, 1, At, B1); PG8_BAR; PG8_SCHED;
;             PG8_LDA(At, 0, 1); PG8_STAGE(PG8_SB(0, 0), b2, voffB); PG8_STAGE(PG8_SB(0, 1), b2 + hstep, voffB); PG8_STAGE(PG8_SA(0, 0), a2, voffA);
;             PG8_WAIT_V(8); PG8_WAIT_L(0); PG8_BAR; PG8_MMA(1, 0, At, B0); PG8_MMA(1, 1, At, B1); PG8_BAR; PG8_SCHED;
.LBB0_938:
	s_mov_b32 s33, s71
	s_or_b32 s71, s8, s28
	s_mul_i32 s8, s71, 0x560000
	s_mov_b64 s[6:7], s[16:17]
	s_add_u32 s16, s20, s8
	s_addc_u32 s17, s21, 0
	s_and_b64 s[8:9], s[42:43], exec
	s_cselect_b32 s56, s17, s7
	s_cselect_b32 s58, s16, s6
	s_mov_b32 s59, 0
	s_nop 3
	s_or_b32 s24, s59, 1
	s_lshl_b64 s[62:63], s[24:25], 15
	s_add_i32 s24, s59, 2
	ds_read_b128 v[156:159], v193
	ds_read_b128 v[160:163], v193 offset:1024
	ds_read_b128 v[196:199], v193 offset:2048
	ds_read_b128 v[200:203], v193 offset:3072
	ds_read_b128 v[204:207], v194
	ds_read_b128 v[208:211], v194 offset:1024
	ds_read_b128 v[212:215], v194 offset:2048
	ds_read_b128 v[216:219], v194 offset:3072
	s_lshl_b64 s[8:9], s[24:25], 15
	s_add_u32 s44, s6, s8
	s_addc_u32 s45, s7, s9
	s_cmpk_eq_i32 s59, 0xaa
	s_cselect_b32 s46, s58, s44
	s_cselect_b32 s47, s56, s45
	s_cselect_b32 s44, 0, s8
	s_cselect_b32 s45, 0, s9
	s_add_u32 s8, s46, 0x8000
	s_addc_u32 s9, s47, 0
	s_add_u32 s44, s14, s44
	s_addc_u32 s45, s15, s45
	s_add_u32 s62, s6, s62
	s_addc_u32 s63, s7, s63
	s_add_u32 s62, s62, 0x4000
	s_addc_u32 s63, s63, 0
	s_sub_u32 s8, s62, 0x4000
	s_subb_u32 s9, s63, 0
	s_mov_b32 m0, s51
	s_nop 0
	global_load_lds_dwordx4 v130, s[8:9]
	s_mov_b32 m0, s57
	s_nop 0
	global_load_lds_dwordx4 v134, s[8:9]
	s_add_i32 m0, s30, 0xc000
	ds_read_b128 v[220:223], v186
	ds_read_b128 v[224:227], v186 offset:1024
	ds_read_b128 v[228:231], v186 offset:2048
	ds_read_b128 v[232:235], v186 offset:3072
	ds_read_b128 v[236:239], v186 offset:4096
	ds_read_b128 v[240:243], v186 offset:5120
	ds_read_b128 v[244:247], v186 offset:6144
	ds_read_b128 v[248:251], v186 offset:7168
	global_load_lds_dwordx4 v130, s[62:63]
	s_add_i32 m0, s30, 0xe000
	s_nop 0
	global_load_lds_dwordx4 v134, s[62:63]
	s_waitcnt vmcnt(8)
	s_waitcnt lgkmcnt(0)
	s_barrier
	s_waitcnt lgkmcnt(0)
	v_mfma_f32_16x16x32_bf16 v[126:129], v[156:159], v[220:223], 0
	v_mfma_f32_16x16x32_bf16 v[126:129], v[160:163], v[224:227], v[126:129]
	v_mfma_f32_16x16x32_bf16 v[110:113], v[160:163], v[232:235], 0
	v_mfma_f32_16x16x32_bf16 v[110:113], v[156:159], v[228:231], v[110:113]
	v_mfma_f32_16x16x32_bf16 v[94:97], v[156:159], v[236:239], 0
	v_mfma_f32_16x16x32_bf16 v[94:97], v[160:163], v[240:243], v[94:97]
	v_mfma_f32_16x16x32_bf16 v[78:81], v[160:163], v[248:251], 0
	v_mfma_f32_16x16x32_bf16 v[78:81], v[156:159], v[244:247], v[78:81]
	v_mfma_f32_16x16x32_bf16 v[74:77], v[196:199], v[244:247], 0
	v_mfma_f32_16x16x32_bf16 v[74:77], v[200:203], v[248:251], v[74:77]
	v_mfma_f32_16x16x32_bf16 v[90:93], v[200:203], v[240:243], 0
	v_mfma_f32_16x16x32_bf16 v[90:93], v[196:199], v[236:239], v[90:93]
	v_mfma_f32_16x16x32_bf16 v[106:109], v[196:199], v[228:231], 0
	v_mfma_f32_16x16x32_bf16 v[106:109], v[200:203], v[232:235], v[106:109]
	v_mfma_f32_16x16x32_bf16 v[122:125], v[200:203], v[224:227], 0
	v_mfma_f32_16x16x32_bf16 v[122:125], v[196:199], v[220:223], v[122:125]
	v_mfma_f32_16x16x32_bf16 v[118:121], v[204:207], v[220:223], 0
	v_mfma_f32_16x16x32_bf16 v[118:121], v[208:211], v[224:227], v[118:121]
	v_mfma_f32_16x16x32_bf16 v[102:105], v[208:211], v[232:235], 0
	v_mfma_f32_16x16x32_bf16 v[102:105], v[204:207], v[228:231], v[102:105]
	v_mfma_f32_16x16x32_bf16 v[86:89], v[204:207], v[236:239], 0
	v_mfma_f32_16x16x32_bf16 v[86:89], v[208:211], v[240:243], v[86:89]
	v_mfma_f32_16x16x32_bf16 v[70:73], v[208:211], v[248:251], 0
	v_mfma_f32_16x16x32_bf16 v[70:73], v[204:207], v[244:247], v[70:73]
	v_mfma_f32_16x16x32_bf16 v[66:69], v[212:215], v[244:247], 0
	v_mfma_f32_16x16x32_bf16 v[66:69], v[216:219], v[248:251], v[66:69]
	v_mfma_f32_16x16x32_bf16 v[82:85], v[216:219], v[240:243], 0
	v_mfma_f32_16x16x32_bf16 v[82:85], v[212:215], v[236:239], v[82:85]
	v_mfma_f32_16x16x32_bf16 v[98:101], v[212:215], v[228:231], 0
	v_mfma_f32_16x16x32_bf16 v[98:101], v[216:219], v[232:235], v[98:101]
	v_mfma_f32_16x16x32_bf16 v[114:117], v[216:219], v[224:227], 0
	v_mfma_f32_16x16x32_bf16 v[114:117], v[212:215], v[220:223], v[114:117]
	s_barrier
	s_add_i32 s62, s67, s29
	s_mov_b32 m0, s62
	ds_read_b128 v[220:223], v186 offset:16384
	ds_read_b128 v[224:227], v186 offset:17408
	ds_read_b128 v[228:231], v186 offset:18432
	ds_read_b128 v[232:235], v186 offset:19456
	ds_read_b128 v[236:239], v186 offset:20480
	ds_read_b128 v[240:243], v186 offset:21504
	ds_read_b128 v[244:247], v186 offset:22528
	ds_read_b128 v[248:251], v186 offset:23552
	global_load_lds_dwordx4 v132, s[44:45]
	s_add_i32 m0, s62, 0x2000
	s_add_u32 s62, s44, 0x4000
	s_addc_u32 s63, s45, 0
	s_add_i32 s72, s68, s29
	global_load_lds_dwordx4 v136, s[44:45]
	s_mov_b32 m0, s72
	s_nop 0
	global_load_lds_dwordx4 v132, s[62:63]
	s_add_i32 m0, s72, 0x2000
	s_nop 0
	global_load_lds_dwordx4 v136, s[62:63]
	s_waitcnt vmcnt(6)
	s_waitcnt lgkmcnt(0)
	s_barrier
; #define PG8_STAGE(bufoff, gbase, voff) do { _Pragma("unroll") for (int _i = 0; _i < 2; ++_i) \
;         __builtin_amdgcn_global_load_lds((const unsigned*)((const char*)(gbase) + (voff)[_i]), (PG8_LAS unsigned*)(lds + (bufoff) + ldsw + _i * 8192), 16, 0, 0); } while (0)
; #define PG8_LDA(dst, b, h) do { _Pragma("unroll") for (int m = 0; m < 4; ++m) _Pragma("unroll") for (int k = 0; k < 2; ++k) dst[m][k] = *(const PG8_LAS bf16x8*)(lds + PG8_SA(b, h) + aoff + m * 2048 + k * 1024); } while (0)
; #define PG8_LDB(dst, b, h) do { _Pragma("unroll") for (int n = 0; n < 2; ++n) _Pragma("unroll") for (int k = 0; k < 2; ++k) dst[n][k] = *(const PG8_LAS bf16x8*)(lds + PG8_SB(b, h) + boff + n * 2048 + k * 1024); } while (0)
; #define PG8_MMA(ai, bj, At, Bt) do { __builtin_amdgcn_s_setprio(1); _Pragma("unroll") for (int m = 0; m < 4; ++m) _Pragma("unroll") for (int n = 0; n < 2; ++n) _Pragma("unroll") for (int k = 0; k < 2; ++k) \
;         acc[ai][bj][m][n] = __builtin_amdgcn_mfma_f32_16x16x32_bf16(Bt[n][k], At[m][k], acc[ai][bj][m][n], 0, 0, 0); __builtin_amdgcn_s_setprio(0); } while (0)
; #define PG8_WAIT_V(n) asm volatile("s_waitcnt vmcnt(" #n ")" ::: "memory")
; #define PG8_WAIT_L(n) asm volatile("s_waitcnt lgkmcnt(" #n ")" ::: "memory")
; #define PG8_BAR __builtin_amdgcn_s_barrier()
; #define PG8_SCHED __builtin_amdgcn_sched_barrier(0)
; template <class Epi, class Sched, bool ALIGN_EPI = false, bool SP2 = false>
; __device__ __forceinline__ void gemm_phase(PG8_LAS unsigned char* lds, const Gemm g, const Sched& S, const Epi& E) {
;     ...
;             PG8_WAIT_V(8); PG8_WAIT_L(0); PG8_BAR; PG8_MMA(1, 0, At, B0); PG8_MMA(1, 1, At, B1); PG8_BAR; PG8_SCHED;
;             PG8_LDB(B0, 1, 0); PG8_LDB(B1, 1, 1); PG8_SCHED; PG8_LDA(At, 1, 0); PG8_STAGE(PG8_SA(0, 1), a2 + hstep, voffA);
;             PG8_WAIT_V(8); PG8_WAIT_L(0); PG8_BAR; PG8_MMA(0, 0, At, B0); PG8_MMA(0, 1, At, B1); PG8_BAR; PG8_SCHED;
	s_waitcnt lgkmcnt(0)
	v_mfma_f32_16x16x32_bf16 v[62:65], v[156:159], v[220:223], 0
	v_mfma_f32_16x16x32_bf16 v[62:65], v[160:163], v[224:227], v[62:65]
	v_mfma_f32_16x16x32_bf16 v[46:49], v[160:163], v[232:235], 0
	v_mfma_f32_16x16x32_bf16 v[46:49], v[156:159], v[228:231], v[46:49]
	v_mfma_f32_16x16x32_bf16 v[30:33], v[156:159], v[236:239], 0
	v_mfma_f32_16x16x32_bf16 v[30:33], v[160:163], v[240:243], v[30:33]
	v_mfma_f32_16x16x32_bf16 v[14:17], v[160:163], v[248:251], 0
	v_mfma_f32_16x16x32_bf16 v[14:17], v[156:159], v[244:247], v[14:17]
	v_mfma_f32_16x16x32_bf16 v[10:13], v[196:199], v[244:247], 0
	v_mfma_f32_16x16x32_bf16 v[10:13], v[200:203], v[248:251], v[10:13]
	v_mfma_f32_16x16x32_bf16 v[26:29], v[200:203], v[240:243], 0
	v_mfma_f32_16x16x32_bf16 v[26:29], v[196:199], v[236:239], v[26:29]
	v_mfma_f32_16x16x32_bf16 v[42:45], v[196:199], v[228:231], 0
	v_mfma_f32_16x16x32_bf16 v[42:45], v[200:203], v[232:235], v[42:45]
	v_mfma_f32_16x16x32_bf16 v[58:61], v[200:203], v[224:227], 0
	v_mfma_f32_16x16x32_bf16 v[58:61], v[196:199], v[220:223], v[58:61]
	v_mfma_f32_16x16x32_bf16 v[54:57], v[204:207], v[220:223], 0
	v_mfma_f32_16x16x32_bf16 v[54:57], v[208:211], v[224:227], v[54:57]
	v_mfma_f32_16x16x32_bf16 v[38:41], v[208:211], v[232:235], 0
	v_mfma_f32_16x16x32_bf16 v[38:41], v[204:207], v[228:231], v[38:41]
	v_mfma_f32_16x16x32_bf16 v[22:25], v[204:207], v[236:239], 0
	v_mfma_f32_16x16x32_bf16 v[22:25], v[208:211], v[240:243], v[22:25]
	v_mfma_f32_16x16x32_bf16 v[6:9], v[208:211], v[248:251], 0
	v_mfma_f32_16x16x32_bf16 v[6:9], v[204:207], v[244:247], v[6:9]
	v_mfma_f32_16x16x32_bf16 v[2:5], v[212:215], v[244:247], 0
	v_mfma_f32_16x16x32_bf16 v[2:5], v[216:219], v[248:251], v[2:5]
	v_mfma_f32_16x16x32_bf16 v[18:21], v[216:219], v[240:243], 0
	v_mfma_f32_16x16x32_bf16 v[18:21], v[212:215], v[236:239], v[18:21]
	v_mfma_f32_16x16x32_bf16 v[34:37], v[212:215], v[228:231], 0
	v_mfma_f32_16x16x32_bf16 v[34:37], v[216:219], v[232:235], v[34:37]
	v_mfma_f32_16x16x32_bf16 v[50:53], v[216:219], v[224:227], 0
	v_mfma_f32_16x16x32_bf16 v[50:53], v[212:215], v[220:223], v[50:53]
	s_barrier
	s_add_i32 s62, 0, 0x18000
	v_add_u32_e32 v145, s62, v166
	s_add_i32 s63, 0, 0x1c000
	ds_read_b128 v[156:159], v145
	ds_read_b128 v[160:163], v145 offset:1024
	ds_read_b128 v[196:199], v145 offset:2048
	ds_read_b128 v[200:203], v145 offset:3072
	v_add_u32_e32 v145, s63, v166
	ds_read_b128 v[204:207], v145
	ds_read_b128 v[208:211], v145 offset:1024
	ds_read_b128 v[212:215], v145 offset:2048
	ds_read_b128 v[216:219], v145 offset:3072
	s_mov_b32 m0, s30
	s_nop 0
	global_load_lds_dwordx4 v130, s[46:47]
	s_mov_b32 m0, s31
	s_nop 0
	global_load_lds_dwordx4 v134, s[46:47]
	s_add_u32 s46, s46, 0x4000
	s_addc_u32 s47, s47, 0
	s_mov_b32 m0, s35
	ds_read_b128 v[220:223], v186 offset:32768
	ds_read_b128 v[224:227], v186 offset:33792
	ds_read_b128 v[228:231], v186 offset:34816
	ds_read_b128 v[232:235], v186 offset:35840
	ds_read_b128 v[236:239], v186 offset:36864
	ds_read_b128 v[240:243], v186 offset:37888
	ds_read_b128 v[244:247], v186 offset:38912
	ds_read_b128 v[248:251], v186 offset:39936
	global_load_lds_dwordx4 v130, s[46:47]
	s_mov_b32 m0, s48
	s_nop 0
	global_load_lds_dwordx4 v134, s[46:47]
	s_waitcnt vmcnt(8)
	s_waitcnt lgkmcnt(0)
	s_barrier
; #define PG8_STAGE(bufoff, gbase, voff) do { _Pragma("unroll") for (int _i = 0; _i < 2; ++_i) \
;         __builtin_amdgcn_global_load_lds((const unsigned*)((const char*)(gbase) + (voff)[_i]), (PG8_LAS unsigned*)(lds + (bufoff) + ldsw + _i * 8192), 16, 0, 0); } while (0)
; #define PG8_LDA(dst, b, h) do { _Pragma("unroll") for (int m = 0; m < 4; ++m) _Pragma("unroll") for (int k = 0; k < 2; ++k) dst[m][k] = *(const PG8_LAS bf16x8*)(lds + PG8_SA(b, h) + aoff + m * 2048 + k * 1024); } while (0)
; #define PG8_LDB(dst, b, h) do { _Pragma("unroll") for (int n = 0; n < 2; ++n) _Pragma("unroll") for (int k = 0; k < 2; ++k) dst[n][k] = *(const PG8_LAS bf16x8*)(lds + PG8_SB(b, h) + boff + n * 2048 + k * 1024); } while (0)
; #define PG8_MMA(ai, bj, At, Bt) do { __builtin_amdgcn_s_setprio(1); _Pragma("unroll") for (int m = 0; m < 4; ++m) _Pragma("unroll") for (int n = 0; n < 2; ++n) _Pragma("unroll") for (int k = 0; k < 2; ++k) \
;         acc[ai][bj][m][n] = __builtin_amdgcn_mfma_f32_16x16x32_bf16(Bt[n][k], At[m][k], acc[ai][bj][m][n], 0, 0, 0); __builtin_amdgcn_s_setprio(0); } while (0)
; #define PG8_WAIT_V(n) asm volatile("s_waitcnt vmcnt(" #n ")" ::: "memory")
; #define PG8_WAIT_L(n) asm volatile("s_waitcnt lgkmcnt(" #n ")" ::: "memory")
; #define PG8_BAR __builtin_amdgcn_s_barrier()
; #define PG8_SCHED __builtin_amdgcn_sched_barrier(0)
; template <class Epi, class Sched, bool ALIGN_EPI = false, bool SP2 = false>
; __device__ __forceinline__ void gemm_phase(PG8_LAS unsigned char* lds, const Gemm g, const Sched& S, const Epi& E) {
;     ...
;         for (; t < tend; t += 2) {
;     ...
;             PG8_LDB(B0, 1, 0); PG8_LDB(B1, 1, 1); PG8_SCHED; PG8_LDA(At, 1, 0); PG8_STAGE(PG8_SA(0, 1), a2 + hstep, voffA);
;             PG8_WAIT_V(8); PG8_WAIT_L(0); PG8_BAR; PG8_MMA(0, 0, At, B0); PG8_MMA(0, 1, At, B1); PG8_BAR; PG8_SCHED;
;             PG8_LDA(At, 1, 1); PG8_STAGE(PG8_SB(1, 0), b3, voffB); PG8_STAGE(PG8_SB(1, 1), b3 + hstep, voffB); PG8_STAGE(PG8_SA(1, 0), a3, voffA);
;             PG8_WAIT_V(8); PG8_WAIT_L(0); PG8_BAR; PG8_MMA(1, 0, At, B0); PG8_MMA(1, 1, At, B1); PG8_BAR; PG8_SCHED;
	s_waitcnt lgkmcnt(0)
	v_mfma_f32_16x16x32_bf16 v[126:129], v[156:159], v[220:223], v[126:129]
	v_mfma_f32_16x16x32_bf16 v[126:129], v[160:163], v[224:227], v[126:129]
	v_mfma_f32_16x16x32_bf16 v[110:113], v[160:163], v[232:235], v[110:113]
	v_mfma_f32_16x16x32_bf16 v[110:113], v[156:159], v[228:231], v[110:113]
	v_mfma_f32_16x16x32_bf16 v[94:97], v[156:159], v[236:239], v[94:97]
	v_mfma_f32_16x16x32_bf16 v[94:97], v[160:163], v[240:243], v[94:97]
	v_mfma_f32_16x16x32_bf16 v[78:81], v[160:163], v[248:251], v[78:81]
	v_mfma_f32_16x16x32_bf16 v[78:81], v[156:159], v[244:247], v[78:81]
	v_mfma_f32_16x16x32_bf16 v[74:77], v[196:199], v[244:247], v[74:77]
	v_mfma_f32_16x16x32_bf16 v[74:77], v[200:203], v[248:251], v[74:77]
	v_mfma_f32_16x16x32_bf16 v[90:93], v[200:203], v[240:243], v[90:93]
	v_mfma_f32_16x16x32_bf16 v[90:93], v[196:199], v[236:239], v[90:93]
	v_mfma_f32_16x16x32_bf16 v[106:109], v[196:199], v[228:231], v[106:109]
	v_mfma_f32_16x16x32_bf16 v[106:109], v[200:203], v[232:235], v[106:109]
	v_mfma_f32_16x16x32_bf16 v[122:125], v[200:203], v[224:227], v[122:125]
	v_mfma_f32_16x16x32_bf16 v[122:125], v[196:199], v[220:223], v[122:125]
	v_mfma_f32_16x16x32_bf16 v[118:121], v[204:207], v[220:223], v[118:121]
	v_mfma_f32_16x16x32_bf16 v[118:121], v[208:211], v[224:227], v[118:121]
	v_mfma_f32_16x16x32_bf16 v[102:105], v[208:211], v[232:235], v[102:105]
	v_mfma_f32_16x16x32_bf16 v[102:105], v[204:207], v[228:231], v[102:105]
	v_mfma_f32_16x16x32_bf16 v[86:89], v[204:207], v[236:239], v[86:89]
	v_mfma_f32_16x16x32_bf16 v[86:89], v[208:211], v[240:243], v[86:89]
	v_mfma_f32_16x16x32_bf16 v[70:73], v[208:211], v[248:251], v[70:73]
	v_mfma_f32_16x16x32_bf16 v[70:73], v[204:207], v[244:247], v[70:73]
	v_mfma_f32_16x16x32_bf16 v[66:69], v[212:215], v[244:247], v[66:69]
	v_mfma_f32_16x16x32_bf16 v[66:69], v[216:219], v[248:251], v[66:69]
	v_mfma_f32_16x16x32_bf16 v[82:85], v[216:219], v[240:243], v[82:85]
	v_mfma_f32_16x16x32_bf16 v[82:85], v[212:215], v[236:239], v[82:85]
	v_mfma_f32_16x16x32_bf16 v[98:101], v[212:215], v[228:231], v[98:101]
	v_mfma_f32_16x16x32_bf16 v[98:101], v[216:219], v[232:235], v[98:101]
	v_mfma_f32_16x16x32_bf16 v[114:117], v[216:219], v[224:227], v[114:117]
	v_mfma_f32_16x16x32_bf16 v[114:117], v[212:215], v[220:223], v[114:117]
	s_barrier
	s_add_u32 s46, s44, 0x8000
	s_addc_u32 s47, s45, 0
	s_add_i32 s62, s62, s29
	s_mov_b32 m0, s62
	ds_read_b128 v[220:223], v186 offset:49152
	ds_read_b128 v[224:227], v186 offset:50176
	ds_read_b128 v[228:231], v186 offset:51200
	ds_read_b128 v[232:235], v186 offset:52224
	ds_read_b128 v[236:239], v186 offset:53248
	ds_read_b128 v[240:243], v186 offset:54272
	ds_read_b128 v[244:247], v186 offset:55296
	ds_read_b128 v[248:251], v186 offset:56320
	global_load_lds_dwordx4 v132, s[46:47]
	s_add_i32 m0, s62, 0x2000
	s_add_u32 s44, s44, 0xc000
	v_lshl_add_u64 v[164:165], s[46:47], 0, v[136:137]
	s_addc_u32 s45, s45, 0
	s_add_i32 s46, s63, s29
	global_load_lds_dwordx4 v[164:165], off
	s_mov_b32 m0, s46
	s_nop 0
	global_load_lds_dwordx4 v132, s[44:45]
	s_add_i32 m0, s46, 0x2000
	s_nop 0
	global_load_lds_dwordx4 v136, s[44:45]
	s_waitcnt vmcnt(6)
	s_waitcnt lgkmcnt(0)
	s_barrier
	s_waitcnt lgkmcnt(0)
	v_mfma_f32_16x16x32_bf16 v[62:65], v[156:159], v[220:223], v[62:65]
	v_mfma_f32_16x16x32_bf16 v[62:65], v[160:163], v[224:227], v[62:65]
	v_mfma_f32_16x16x32_bf16 v[46:49], v[160:163], v[232:235], v[46:49]
	v_mfma_f32_16x16x32_bf16 v[46:49], v[156:159], v[228:231], v[46:49]
	v_mfma_f32_16x16x32_bf16 v[30:33], v[156:159], v[236:239], v[30:33]
	v_mfma_f32_16x16x32_bf16 v[30:33], v[160:163], v[240:243], v[30:33]
	v_mfma_f32_16x16x32_bf16 v[14:17], v[160:163], v[248:251], v[14:17]
	v_mfma_f32_16x16x32_bf16 v[14:17], v[156:159], v[244:247], v[14:17]
	v_mfma_f32_16x16x32_bf16 v[10:13], v[196:199], v[244:247], v[10:13]
	v_mfma_f32_16x16x32_bf16 v[10:13], v[200:203], v[248:251], v[10:13]
	v_mfma_f32_16x16x32_bf16 v[26:29], v[200:203], v[240:243], v[26:29]
	v_mfma_f32_16x16x32_bf16 v[26:29], v[196:199], v[236:239], v[26:29]
	v_mfma_f32_16x16x32_bf16 v[42:45], v[196:199], v[228:231], v[42:45]
	v_mfma_f32_16x16x32_bf16 v[42:45], v[200:203], v[232:235], v[42:45]
	v_mfma_f32_16x16x32_bf16 v[58:61], v[200:203], v[224:227], v[58:61]
	v_mfma_f32_16x16x32_bf16 v[58:61], v[196:199], v[220:223], v[58:61]
	v_mfma_f32_16x16x32_bf16 v[54:57], v[204:207], v[220:223], v[54:57]
	v_mfma_f32_16x16x32_bf16 v[54:57], v[208:211], v[224:227], v[54:57]
	v_mfma_f32_16x16x32_bf16 v[38:41], v[208:211], v[232:235], v[38:41]
	v_mfma_f32_16x16x32_bf16 v[38:41], v[204:207], v[228:231], v[38:41]
	v_mfma_f32_16x16x32_bf16 v[22:25], v[204:207], v[236:239], v[22:25]
	v_mfma_f32_16x16x32_bf16 v[22:25], v[208:211], v[240:243], v[22:25]
	v_mfma_f32_16x16x32_bf16 v[6:9], v[208:211], v[248:251], v[6:9]
	v_mfma_f32_16x16x32_bf16 v[6:9], v[204:207], v[244:247], v[6:9]
	v_mfma_f32_16x16x32_bf16 v[2:5], v[212:215], v[244:247], v[2:5]
	v_mfma_f32_16x16x32_bf16 v[2:5], v[216:219], v[248:251], v[2:5]
	v_mfma_f32_16x16x32_bf16 v[18:21], v[216:219], v[240:243], v[18:21]
	v_mfma_f32_16x16x32_bf16 v[18:21], v[212:215], v[236:239], v[18:21]
	v_mfma_f32_16x16x32_bf16 v[34:37], v[212:215], v[228:231], v[34:37]
	v_mfma_f32_16x16x32_bf16 v[34:37], v[216:219], v[232:235], v[34:37]
	v_mfma_f32_16x16x32_bf16 v[50:53], v[216:219], v[224:227], v[50:53]
	v_mfma_f32_16x16x32_bf16 v[50:53], v[212:215], v[220:223], v[50:53]
	s_barrier
	s_cmpk_gt_u32 s59, 0xa9
	s_mov_b32 s59, s24
